# the 13 k-loop heads aligned to 64-byte boundaries (s_nop fill on the fall-through path)
# baseline (speedup 1.0000x reference)
; #define PG8_STAGE(bufoff, gbase, voff) do { _Pragma("unroll") for (int _i = 0; _i < 2; ++_i) \
;         __builtin_amdgcn_global_load_lds((const unsigned*)((const char*)(gbase) + (voff)[_i]), (LAS unsigned*)(lds + (bufoff) + ldsw + _i * 8192), 16, 0, 0); } while (0)
; #define PG8_LDA(dst, b, h) do { _Pragma("unroll") for (int m = 0; m < 4; ++m) _Pragma("unroll") for (int k = 0; k < 2; ++k) dst[m][k] = *(const LAS bf16x8*)(lds + PG8_SA(b, h) + aoff + m * 2048 + k * 1024); } while (0)
; #define PG8_LDB(dst, b, h) do { _Pragma("unroll") for (int n = 0; n < 2; ++n) _Pragma("unroll") for (int k = 0; k < 2; ++k) dst[n][k] = *(const LAS bf16x8*)(lds + PG8_SB(b, h) + boff + n * 2048 + k * 1024); } while (0)
; #define PG8_MMA(ai, bj, At, Bt) do { __builtin_amdgcn_s_setprio(1); _Pragma("unroll") for (int m = 0; m < 4; ++m) _Pragma("unroll") for (int n = 0; n < 2; ++n) _Pragma("unroll") for (int k = 0; k < 2; ++k) \
;         acc[ai][bj][m][n] = __builtin_amdgcn_mfma_f32_16x16x32_bf16(Bt[n][k], At[m][k], acc[ai][bj][m][n], 0, 0, 0); __builtin_amdgcn_s_setprio(0); } while (0)
; #define PG8_BAR __builtin_amdgcn_s_barrier()
; template <class Epi>
; __device__ __forceinline__ void gemm_phase(LAS unsigned char* lds, const Gemm g, const StaticOrder& S, const Epi& E) {
;     ...
;         const bool has_next = S.next(ui + 1, nxt);
;         const char* nA = has_next ? (const char*)g.A + (size_t)nxt.pm * tstepA + (size_t)(nxt.pn >> g.a_shift) * g.a_step : cA; const char* nB = has_next ? (const char*)g.Bt + (size_t)nxt.pn * tstepB : cB;
;         for (int t = 0; t < nt; t += 2) {
;             const bool last = (t == nt - 2);
;             const char* a1 = cA + (size_t)(t + 1) * kstep;
;             const char* a2 = last ? nA : cA + (size_t)(t + 2) * kstep; const char* b2 = last ? nB : cB + (size_t)(t + 2) * kstep;
;             const char* a3 = a2 + kstep; const char* b3 = b2 + kstep;
;             PG8_LDB(B0, 0, 0); PG8_SCHED; PG8_LDA(At, 0, 0); PG8_STAGE(PG8_SA(1, 1), a1 + hstepA, voffA);
;             PG8_WAIT_L(8); PG8_BAR; PG8_WAIT_L(0); PG8_MMA(0, 0, At, B0); PG8_BAR; PG8_SCHED;
;             PG8_LDB(B1, 0, 1); PG8_STAGE(PG8_SB(0, 0), b2, voffB);
;             PG8_BAR; PG8_WAIT_L(0); PG8_MMA(0, 1, At, B1); PG8_BAR;
;             PG8_LDA(At, 0, 1); PG8_STAGE(PG8_SA(0, 0), a2, voffA);
;             PG8_BAR; PG8_WAIT_L(0); PG8_MMA(1, 0, At, B0); PG8_BAR; PG8_SCHED;
.LBB0_308:
	s_ashr_i32 s27, s26, 31
	v_cmp_lt_i64_e32 vcc, s[28:29], v[228:229]
	s_lshl_b64 s[28:29], s[26:27], 19
	s_add_u32 s28, s66, s28
	s_addc_u32 s29, s67, s29
	s_and_b64 s[30:31], vcc, exec
	s_cselect_b32 s27, s29, s37
	s_cselect_b32 s75, s28, s36
	s_ashr_i32 s25, s24, 31
	s_lshl_b64 s[30:31], s[24:25], 19
	s_add_u32 s30, s4, s30
	s_addc_u32 s31, s5, s31
	s_and_b64 s[40:41], vcc, exec
	s_cselect_b32 s25, s31, s39
	s_cselect_b32 s76, s30, s38
	s_add_u32 s77, s38, 0x100
	s_addc_u32 s78, s39, 0
	s_mov_b32 s79, -2
	ds_read_b128 v[96:99], v243
	ds_read_b128 v[100:103], v243 offset:1024
	ds_read_b128 v[104:107], v243 offset:2048
	ds_read_b128 v[108:111], v243 offset:3072
	s_add_u32 s38, s36, 0x100
	s_addc_u32 s39, s37, 0
	s_cmp_eq_u32 s79, 12
	s_cselect_b32 s43, s27, s39
	s_cselect_b32 s42, s75, s38
	s_cselect_b32 s41, s25, s78
	s_cselect_b32 s40, s76, s77
	v_lshl_add_u64 v[176:177], s[36:37], 0, v[224:225]
	s_add_i32 m0, s45, 0xc000
	ds_read_b128 v[112:115], v244
	ds_read_b128 v[116:119], v244 offset:1024
	ds_read_b128 v[120:123], v244 offset:2048
	ds_read_b128 v[124:127], v244 offset:3072
	ds_read_b128 v[160:163], v244 offset:4096
	ds_read_b128 v[164:167], v244 offset:5120
	ds_read_b128 v[168:171], v244 offset:6144
	ds_read_b128 v[172:175], v244 offset:7168
	global_load_lds_dwordx4 v[176:177], off
	v_lshl_add_u64 v[176:177], s[36:37], 0, v[226:227]
	s_add_i32 m0, s45, 0xe000
	s_nop 0
	global_load_lds_dwordx4 v[176:177], off
	ds_read_b128 v[176:179], v245
	ds_read_b128 v[180:183], v245 offset:1024
	ds_read_b128 v[184:187], v245 offset:2048
	ds_read_b128 v[188:191], v245 offset:3072
	s_waitcnt lgkmcnt(0)
	s_barrier
	s_setprio 1
	v_mfma_f32_16x16x32_bf16 v[156:159], v[96:99], v[112:115], 0
	v_mfma_f32_16x16x32_bf16 v[60:63], v[104:107], v[112:115], 0
	v_mfma_f32_16x16x32_bf16 v[144:147], v[96:99], v[120:123], 0
	v_mfma_f32_16x16x32_bf16 v[48:51], v[104:107], v[120:123], 0
	v_mfma_f32_16x16x32_bf16 v[136:139], v[96:99], v[160:163], 0
	v_mfma_f32_16x16x32_bf16 v[40:43], v[104:107], v[160:163], 0
	v_mfma_f32_16x16x32_bf16 v[148:151], v[96:99], v[168:171], 0
	v_mfma_f32_16x16x32_bf16 v[52:55], v[104:107], v[168:171], 0
	v_mfma_f32_16x16x32_bf16 v[156:159], v[100:103], v[116:119], v[156:159]
	v_mfma_f32_16x16x32_bf16 v[60:63], v[108:111], v[116:119], v[60:63]
	v_mfma_f32_16x16x32_bf16 v[144:147], v[100:103], v[124:127], v[144:147]
	v_mfma_f32_16x16x32_bf16 v[48:51], v[108:111], v[124:127], v[48:51]
	v_mfma_f32_16x16x32_bf16 v[136:139], v[100:103], v[164:167], v[136:139]
	v_mfma_f32_16x16x32_bf16 v[40:43], v[108:111], v[164:167], v[40:43]
	v_mfma_f32_16x16x32_bf16 v[148:151], v[100:103], v[172:175], v[148:151]
	v_mfma_f32_16x16x32_bf16 v[52:55], v[108:111], v[172:175], v[52:55]
	v_mfma_f32_16x16x32_bf16 v[152:155], v[176:179], v[112:115], 0
	v_mfma_f32_16x16x32_bf16 v[56:59], v[184:187], v[112:115], 0
	v_mfma_f32_16x16x32_bf16 v[36:39], v[184:187], v[120:123], 0
	v_mfma_f32_16x16x32_bf16 v[32:35], v[184:187], v[160:163], 0
	v_mfma_f32_16x16x32_bf16 v[44:47], v[184:187], v[168:171], 0
	v_mfma_f32_16x16x32_bf16 v[152:155], v[180:183], v[116:119], v[152:155]
	v_mfma_f32_16x16x32_bf16 v[56:59], v[188:191], v[116:119], v[56:59]
	v_mfma_f32_16x16x32_bf16 v[112:115], v[176:179], v[120:123], 0
	v_mfma_f32_16x16x32_bf16 v[36:39], v[188:191], v[124:127], v[36:39]
	v_mfma_f32_16x16x32_bf16 v[116:119], v[176:179], v[160:163], 0
	v_mfma_f32_16x16x32_bf16 v[32:35], v[188:191], v[164:167], v[32:35]
	v_mfma_f32_16x16x32_bf16 v[120:123], v[176:179], v[168:171], 0
	v_mfma_f32_16x16x32_bf16 v[44:47], v[188:191], v[172:175], v[44:47]
	v_mfma_f32_16x16x32_bf16 v[112:115], v[180:183], v[124:127], v[112:115]
	v_mfma_f32_16x16x32_bf16 v[116:119], v[180:183], v[164:167], v[116:119]
	v_mfma_f32_16x16x32_bf16 v[120:123], v[180:183], v[172:175], v[120:123]
	s_setprio 0
	s_barrier
	s_nop 1
	ds_read_b128 v[124:127], v244 offset:16384
	ds_read_b128 v[128:131], v244 offset:17408
	ds_read_b128 v[132:135], v244 offset:18432
	ds_read_b128 v[140:143], v244 offset:19456
	ds_read_b128 v[160:163], v244 offset:20480
	ds_read_b128 v[164:167], v244 offset:21504
	ds_read_b128 v[168:171], v244 offset:22528
	ds_read_b128 v[172:175], v244 offset:23552
	s_add_i32 s36, s72, s6
	v_lshl_add_u64 v[196:197], s[40:41], 0, v[214:215]
	s_mov_b32 m0, s36
	s_nop 0
	global_load_lds_dwordx4 v[196:197], off
	v_lshl_add_u64 v[198:199], s[40:41], 0, v[210:211]
	s_add_i32 m0, s36, 0x2000
	s_nop 0
	global_load_lds_dwordx4 v[198:199], off
	s_mov_b32 m0, s45
	v_lshl_add_u64 v[200:201], s[42:43], 0, v[216:217]
	global_load_lds_dwordx4 v[200:201], off
	v_lshl_add_u64 v[202:203], s[42:43], 0, v[212:213]
	s_mov_b32 m0, s46
	s_nop 0
	global_load_lds_dwordx4 v[202:203], off
	s_add_u32 s36, s40, 0x40000
	s_addc_u32 s37, s41, 0
	s_add_i32 s80, s73, s6
	v_lshl_add_u64 v[254:255], s[36:37], 0, v[214:215]
	s_mov_b32 m0, s80
	s_nop 0
	global_load_lds_dwordx4 v[254:255], off
	v_lshl_add_u64 v[254:255], s[36:37], 0, v[210:211]
	s_add_i32 m0, s80, 0x2000
	s_nop 0
	global_load_lds_dwordx4 v[254:255], off
	s_waitcnt vmcnt(6)
	s_waitcnt lgkmcnt(0)
	s_barrier
; #define PG8_STAGE(bufoff, gbase, voff) do { _Pragma("unroll") for (int _i = 0; _i < 2; ++_i) \
;         __builtin_amdgcn_global_load_lds((const unsigned*)((const char*)(gbase) + (voff)[_i]), (LAS unsigned*)(lds + (bufoff) + ldsw + _i * 8192), 16, 0, 0); } while (0)
; #define PG8_LDA(dst, b, h) do { _Pragma("unroll") for (int m = 0; m < 4; ++m) _Pragma("unroll") for (int k = 0; k < 2; ++k) dst[m][k] = *(const LAS bf16x8*)(lds + PG8_SA(b, h) + aoff + m * 2048 + k * 1024); } while (0)
; #define PG8_LDB(dst, b, h) do { _Pragma("unroll") for (int n = 0; n < 2; ++n) _Pragma("unroll") for (int k = 0; k < 2; ++k) dst[n][k] = *(const LAS bf16x8*)(lds + PG8_SB(b, h) + boff + n * 2048 + k * 1024); } while (0)
; #define PG8_MMA(ai, bj, At, Bt) do { __builtin_amdgcn_s_setprio(1); _Pragma("unroll") for (int m = 0; m < 4; ++m) _Pragma("unroll") for (int n = 0; n < 2; ++n) _Pragma("unroll") for (int k = 0; k < 2; ++k) \
;         acc[ai][bj][m][n] = __builtin_amdgcn_mfma_f32_16x16x32_bf16(Bt[n][k], At[m][k], acc[ai][bj][m][n], 0, 0, 0); __builtin_amdgcn_s_setprio(0); } while (0)
; #define PG8_WAIT_V(n) asm volatile("s_waitcnt vmcnt(" #n ")" ::: "memory")
; #define PG8_WAIT_L(n) asm volatile("s_waitcnt lgkmcnt(" #n ")" ::: "memory")
; #define PG8_BAR __builtin_amdgcn_s_barrier()
; #define PG8_SCHED __builtin_amdgcn_sched_barrier(0)
; template <class Epi>
; __device__ __forceinline__ void gemm_phase(LAS unsigned char* lds, const Gemm g, const StaticOrder& S, const Epi& E) {
;     ...
;             PG8_BAR; PG8_WAIT_L(0); PG8_MMA(1, 0, At, B0); PG8_BAR; PG8_SCHED;
;             PG8_STAGE(PG8_SB(0, 1), b2 + hstepB, voffB);
;             PG8_WAIT_V(6); PG8_BAR; PG8_MMA(1, 1, At, B1); PG8_BAR;
;             PG8_LDB(B0, 1, 0); PG8_SCHED; PG8_LDA(At, 1, 0); PG8_STAGE(PG8_SA(0, 1), a2 + hstepA, voffA);
;             PG8_WAIT_L(8); PG8_BAR; PG8_WAIT_L(0); PG8_MMA(0, 0, At, B0); PG8_BAR; PG8_SCHED;
;             PG8_LDB(B1, 1, 1); PG8_STAGE(PG8_SB(1, 0), b3, voffB);
;             PG8_BAR; PG8_WAIT_L(0); PG8_MMA(0, 1, At, B1); PG8_BAR;
	s_setprio 1
	v_mfma_f32_16x16x32_bf16 v[92:95], v[96:99], v[124:127], 0
	v_mfma_f32_16x16x32_bf16 v[28:31], v[104:107], v[124:127], 0
	v_mfma_f32_16x16x32_bf16 v[80:83], v[96:99], v[132:135], 0
	v_mfma_f32_16x16x32_bf16 v[16:19], v[104:107], v[132:135], 0
	v_mfma_f32_16x16x32_bf16 v[76:79], v[96:99], v[160:163], 0
	v_mfma_f32_16x16x32_bf16 v[12:15], v[104:107], v[160:163], 0
	v_mfma_f32_16x16x32_bf16 v[84:87], v[96:99], v[168:171], 0
	v_mfma_f32_16x16x32_bf16 v[20:23], v[104:107], v[168:171], 0
	v_mfma_f32_16x16x32_bf16 v[92:95], v[100:103], v[128:131], v[92:95]
	v_mfma_f32_16x16x32_bf16 v[28:31], v[108:111], v[128:131], v[28:31]
	v_mfma_f32_16x16x32_bf16 v[80:83], v[100:103], v[140:143], v[80:83]
	v_mfma_f32_16x16x32_bf16 v[16:19], v[108:111], v[140:143], v[16:19]
	v_mfma_f32_16x16x32_bf16 v[76:79], v[100:103], v[164:167], v[76:79]
	v_mfma_f32_16x16x32_bf16 v[12:15], v[108:111], v[164:167], v[12:15]
	v_mfma_f32_16x16x32_bf16 v[84:87], v[100:103], v[172:175], v[84:87]
	v_mfma_f32_16x16x32_bf16 v[20:23], v[108:111], v[172:175], v[20:23]
	v_mfma_f32_16x16x32_bf16 v[88:91], v[176:179], v[124:127], 0
	v_mfma_f32_16x16x32_bf16 v[24:27], v[184:187], v[124:127], 0
	v_mfma_f32_16x16x32_bf16 v[68:71], v[176:179], v[132:135], 0
	v_mfma_f32_16x16x32_bf16 v[4:7], v[184:187], v[132:135], 0
	v_mfma_f32_16x16x32_bf16 v[64:67], v[176:179], v[160:163], 0
	v_mfma_f32_16x16x32_bf16 v[0:3], v[184:187], v[160:163], 0
	v_mfma_f32_16x16x32_bf16 v[72:75], v[176:179], v[168:171], 0
	v_mfma_f32_16x16x32_bf16 v[8:11], v[184:187], v[168:171], 0
	v_mfma_f32_16x16x32_bf16 v[88:91], v[180:183], v[128:131], v[88:91]
	v_mfma_f32_16x16x32_bf16 v[24:27], v[188:191], v[128:131], v[24:27]
	v_mfma_f32_16x16x32_bf16 v[68:71], v[180:183], v[140:143], v[68:71]
	v_mfma_f32_16x16x32_bf16 v[4:7], v[188:191], v[140:143], v[4:7]
	v_mfma_f32_16x16x32_bf16 v[64:67], v[180:183], v[164:167], v[64:67]
	v_mfma_f32_16x16x32_bf16 v[0:3], v[188:191], v[164:167], v[0:3]
	v_mfma_f32_16x16x32_bf16 v[72:75], v[180:183], v[172:175], v[72:75]
	v_mfma_f32_16x16x32_bf16 v[8:11], v[188:191], v[172:175], v[8:11]
	s_setprio 0
	s_add_i32 s80, 0, 0x18000
	v_add_u32_e32 v108, s80, v235
	s_barrier
	ds_read_b128 v[96:99], v108
	ds_read_b128 v[100:103], v108 offset:1024
	ds_read_b128 v[104:107], v108 offset:2048
	ds_read_b128 v[108:111], v108 offset:3072
	s_add_u32 s36, s42, 0x40000
	s_addc_u32 s37, s43, 0
	s_mov_b32 m0, s47
	v_lshl_add_u64 v[132:133], s[36:37], 0, v[216:217]
	ds_read_b128 v[124:127], v244 offset:32768
	ds_read_b128 v[128:131], v244 offset:33792
	ds_read_b128 v[140:143], v244 offset:34816
	ds_read_b128 v[160:163], v244 offset:35840
	ds_read_b128 v[164:167], v244 offset:36864
	ds_read_b128 v[168:171], v244 offset:37888
	ds_read_b128 v[172:175], v244 offset:38912
	ds_read_b128 v[176:179], v244 offset:39936
	global_load_lds_dwordx4 v[132:133], off
	v_lshl_add_u64 v[132:133], s[36:37], 0, v[212:213]
	s_mov_b32 m0, s48
	s_nop 0
	global_load_lds_dwordx4 v[132:133], off
	s_add_i32 s42, 0, 0x1c000
	v_add_u32_e32 v132, s42, v235
	ds_read_b128 v[180:183], v132
	ds_read_b128 v[184:187], v132 offset:1024
	ds_read_b128 v[188:191], v132 offset:2048
	ds_read_b128 v[192:195], v132 offset:3072
	s_waitcnt lgkmcnt(0)
	s_barrier
	s_setprio 1
	v_mfma_f32_16x16x32_bf16 v[132:135], v[96:99], v[124:127], v[156:159]
	v_mfma_f32_16x16x32_bf16 v[156:159], v[100:103], v[128:131], v[132:135]
	v_mfma_f32_16x16x32_bf16 v[132:135], v[96:99], v[140:143], v[144:147]
	v_mfma_f32_16x16x32_bf16 v[144:147], v[100:103], v[160:163], v[132:135]
	v_mfma_f32_16x16x32_bf16 v[132:135], v[96:99], v[164:167], v[136:139]
	v_mfma_f32_16x16x32_bf16 v[60:63], v[104:107], v[124:127], v[60:63]
	v_mfma_f32_16x16x32_bf16 v[48:51], v[104:107], v[140:143], v[48:51]
	v_mfma_f32_16x16x32_bf16 v[136:139], v[100:103], v[168:171], v[132:135]
	v_mfma_f32_16x16x32_bf16 v[40:43], v[104:107], v[164:167], v[40:43]
	v_mfma_f32_16x16x32_bf16 v[132:135], v[96:99], v[172:175], v[148:151]
	v_mfma_f32_16x16x32_bf16 v[52:55], v[104:107], v[172:175], v[52:55]
	v_mfma_f32_16x16x32_bf16 v[60:63], v[108:111], v[128:131], v[60:63]
	v_mfma_f32_16x16x32_bf16 v[48:51], v[108:111], v[160:163], v[48:51]
	v_mfma_f32_16x16x32_bf16 v[40:43], v[108:111], v[168:171], v[40:43]
	v_mfma_f32_16x16x32_bf16 v[148:151], v[100:103], v[176:179], v[132:135]
	v_mfma_f32_16x16x32_bf16 v[52:55], v[108:111], v[176:179], v[52:55]
	v_mfma_f32_16x16x32_bf16 v[132:135], v[180:183], v[124:127], v[152:155]
	v_mfma_f32_16x16x32_bf16 v[112:115], v[180:183], v[140:143], v[112:115]
	v_mfma_f32_16x16x32_bf16 v[152:155], v[184:187], v[128:131], v[132:135]
	v_mfma_f32_16x16x32_bf16 v[56:59], v[188:191], v[124:127], v[56:59]
	v_mfma_f32_16x16x32_bf16 v[132:135], v[184:187], v[160:163], v[112:115]
	v_mfma_f32_16x16x32_bf16 v[112:115], v[180:183], v[164:167], v[116:119]
	v_mfma_f32_16x16x32_bf16 v[56:59], v[192:195], v[128:131], v[56:59]
	v_mfma_f32_16x16x32_bf16 v[36:39], v[188:191], v[140:143], v[36:39]
	v_mfma_f32_16x16x32_bf16 v[128:131], v[184:187], v[168:171], v[112:115]
	v_mfma_f32_16x16x32_bf16 v[32:35], v[188:191], v[164:167], v[32:35]
	v_mfma_f32_16x16x32_bf16 v[112:115], v[180:183], v[172:175], v[120:123]
	v_mfma_f32_16x16x32_bf16 v[44:47], v[188:191], v[172:175], v[44:47]
	v_mfma_f32_16x16x32_bf16 v[36:39], v[192:195], v[160:163], v[36:39]
	v_mfma_f32_16x16x32_bf16 v[32:35], v[192:195], v[168:171], v[32:35]
	v_mfma_f32_16x16x32_bf16 v[140:143], v[184:187], v[176:179], v[112:115]
	v_mfma_f32_16x16x32_bf16 v[44:47], v[192:195], v[176:179], v[44:47]
	s_setprio 0
	s_barrier
; #define PG8_STAGE(bufoff, gbase, voff) do { _Pragma("unroll") for (int _i = 0; _i < 2; ++_i) \
;         __builtin_amdgcn_global_load_lds((const unsigned*)((const char*)(gbase) + (voff)[_i]), (LAS unsigned*)(lds + (bufoff) + ldsw + _i * 8192), 16, 0, 0); } while (0)
; #define PG8_LDA(dst, b, h) do { _Pragma("unroll") for (int m = 0; m < 4; ++m) _Pragma("unroll") for (int k = 0; k < 2; ++k) dst[m][k] = *(const LAS bf16x8*)(lds + PG8_SA(b, h) + aoff + m * 2048 + k * 1024); } while (0)
; #define PG8_MMA(ai, bj, At, Bt) do { __builtin_amdgcn_s_setprio(1); _Pragma("unroll") for (int m = 0; m < 4; ++m) _Pragma("unroll") for (int n = 0; n < 2; ++n) _Pragma("unroll") for (int k = 0; k < 2; ++k) \
;         acc[ai][bj][m][n] = __builtin_amdgcn_mfma_f32_16x16x32_bf16(Bt[n][k], At[m][k], acc[ai][bj][m][n], 0, 0, 0); __builtin_amdgcn_s_setprio(0); } while (0)
; #define PG8_WAIT_V(n) asm volatile("s_waitcnt vmcnt(" #n ")" ::: "memory")
; #define PG8_WAIT_L(n) asm volatile("s_waitcnt lgkmcnt(" #n ")" ::: "memory")
; #define PG8_BAR __builtin_amdgcn_s_barrier()
; #define PG8_SCHED __builtin_amdgcn_sched_barrier(0)
; template <class Epi>
; __device__ __forceinline__ void gemm_phase(LAS unsigned char* lds, const Gemm g, const StaticOrder& S, const Epi& E) {
;     ...
;             PG8_LDA(At, 1, 1); PG8_STAGE(PG8_SA(1, 0), a3, voffA);
;             PG8_BAR; PG8_WAIT_L(0); PG8_MMA(1, 0, At, B0); PG8_BAR; PG8_SCHED;
;             PG8_STAGE(PG8_SB(1, 1), b3 + hstepB, voffB);
;             PG8_WAIT_V(6); PG8_BAR; PG8_MMA(1, 1, At, B1); PG8_BAR;
	s_nop 1
	ds_read_b128 v[112:115], v244 offset:49152
	ds_read_b128 v[116:119], v244 offset:50176
	ds_read_b128 v[120:123], v244 offset:51200
	ds_read_b128 v[124:127], v244 offset:52224
	ds_read_b128 v[160:163], v244 offset:53248
	ds_read_b128 v[164:167], v244 offset:54272
	ds_read_b128 v[168:171], v244 offset:55296
	ds_read_b128 v[172:175], v244 offset:56320
	s_add_i32 s36, s80, s6
	v_lshl_add_u64 v[254:255], v[196:197], 0, s[14:15]
	s_mov_b32 m0, s36
	s_nop 0
	global_load_lds_dwordx4 v[254:255], off
	v_lshl_add_u64 v[254:255], v[198:199], 0, s[14:15]
	s_add_i32 m0, s36, 0x2000
	s_nop 0
	global_load_lds_dwordx4 v[254:255], off
	s_mov_b32 m0, s68
	v_lshl_add_u64 v[254:255], v[200:201], 0, s[14:15]
	global_load_lds_dwordx4 v[254:255], off
	v_lshl_add_u64 v[254:255], v[202:203], 0, s[14:15]
	s_mov_b32 m0, s69
	s_nop 0
	global_load_lds_dwordx4 v[254:255], off
	s_add_u32 s36, s40, 0x40080
	s_addc_u32 s37, s41, 0
	s_add_i32 s40, s42, s6
	v_lshl_add_u64 v[254:255], s[36:37], 0, v[214:215]
	s_mov_b32 m0, s40
	s_nop 0
	global_load_lds_dwordx4 v[254:255], off
	v_lshl_add_u64 v[254:255], s[36:37], 0, v[210:211]
	s_add_i32 m0, s40, 0x2000
	s_nop 0
	global_load_lds_dwordx4 v[254:255], off
	s_waitcnt vmcnt(6)
	s_waitcnt lgkmcnt(0)
	s_barrier
	s_setprio 1
	v_mfma_f32_16x16x32_bf16 v[92:95], v[96:99], v[112:115], v[92:95]
	v_mfma_f32_16x16x32_bf16 v[28:31], v[104:107], v[112:115], v[28:31]
	v_mfma_f32_16x16x32_bf16 v[80:83], v[96:99], v[120:123], v[80:83]
	v_mfma_f32_16x16x32_bf16 v[16:19], v[104:107], v[120:123], v[16:19]
	v_mfma_f32_16x16x32_bf16 v[76:79], v[96:99], v[160:163], v[76:79]
	v_mfma_f32_16x16x32_bf16 v[12:15], v[104:107], v[160:163], v[12:15]
	v_mfma_f32_16x16x32_bf16 v[84:87], v[96:99], v[168:171], v[84:87]
	v_mfma_f32_16x16x32_bf16 v[20:23], v[104:107], v[168:171], v[20:23]
	v_mfma_f32_16x16x32_bf16 v[92:95], v[100:103], v[116:119], v[92:95]
	v_mfma_f32_16x16x32_bf16 v[28:31], v[108:111], v[116:119], v[28:31]
	v_mfma_f32_16x16x32_bf16 v[80:83], v[100:103], v[124:127], v[80:83]
	v_mfma_f32_16x16x32_bf16 v[16:19], v[108:111], v[124:127], v[16:19]
	v_mfma_f32_16x16x32_bf16 v[76:79], v[100:103], v[164:167], v[76:79]
	v_mfma_f32_16x16x32_bf16 v[12:15], v[108:111], v[164:167], v[12:15]
	v_mfma_f32_16x16x32_bf16 v[84:87], v[100:103], v[172:175], v[84:87]
	v_mfma_f32_16x16x32_bf16 v[20:23], v[108:111], v[172:175], v[20:23]
	v_mfma_f32_16x16x32_bf16 v[88:91], v[180:183], v[112:115], v[88:91]
	v_mfma_f32_16x16x32_bf16 v[24:27], v[188:191], v[112:115], v[24:27]
	v_mfma_f32_16x16x32_bf16 v[68:71], v[180:183], v[120:123], v[68:71]
	v_mfma_f32_16x16x32_bf16 v[4:7], v[188:191], v[120:123], v[4:7]
	v_mfma_f32_16x16x32_bf16 v[64:67], v[180:183], v[160:163], v[64:67]
	v_mfma_f32_16x16x32_bf16 v[0:3], v[188:191], v[160:163], v[0:3]
	v_mfma_f32_16x16x32_bf16 v[72:75], v[180:183], v[168:171], v[72:75]
	v_mfma_f32_16x16x32_bf16 v[8:11], v[188:191], v[168:171], v[8:11]
	v_mfma_f32_16x16x32_bf16 v[88:91], v[184:187], v[116:119], v[88:91]
	v_mfma_f32_16x16x32_bf16 v[24:27], v[192:195], v[116:119], v[24:27]
	v_mfma_f32_16x16x32_bf16 v[68:71], v[184:187], v[124:127], v[68:71]
	v_mfma_f32_16x16x32_bf16 v[4:7], v[192:195], v[124:127], v[4:7]
	v_mfma_f32_16x16x32_bf16 v[64:67], v[184:187], v[164:167], v[64:67]
	v_mfma_f32_16x16x32_bf16 v[0:3], v[192:195], v[164:167], v[0:3]
	v_mfma_f32_16x16x32_bf16 v[72:75], v[184:187], v[172:175], v[72:75]
	v_mfma_f32_16x16x32_bf16 v[8:11], v[192:195], v[172:175], v[8:11]
	s_setprio 0
	s_add_i32 s79, s79, 2
	s_add_u32 s77, s77, 0x100
	s_addc_u32 s78, s78, 0
	s_cmp_gt_u32 s79, 13
	s_mov_b64 s[36:37], s[38:39]
	s_barrier
	.p2alignl 6, 3212836864

; #define PG8_STAGE(bufoff, gbase, voff) do { _Pragma("unroll") for (int _i = 0; _i < 2; ++_i) \
;         __builtin_amdgcn_global_load_lds((const unsigned*)((const char*)(gbase) + (voff)[_i]), (LAS unsigned*)(lds + (bufoff) + ldsw + _i * 8192), 16, 0, 0); } while (0)
; #define PG8_LDA(dst, b, h) do { _Pragma("unroll") for (int m = 0; m < 4; ++m) _Pragma("unroll") for (int k = 0; k < 2; ++k) dst[m][k] = *(const LAS bf16x8*)(lds + PG8_SA(b, h) + aoff + m * 2048 + k * 1024); } while (0)
; #define PG8_LDB(dst, b, h) do { _Pragma("unroll") for (int n = 0; n < 2; ++n) _Pragma("unroll") for (int k = 0; k < 2; ++k) dst[n][k] = *(const LAS bf16x8*)(lds + PG8_SB(b, h) + boff + n * 2048 + k * 1024); } while (0)
; #define PG8_MMA(ai, bj, At, Bt) do { __builtin_amdgcn_s_setprio(1); _Pragma("unroll") for (int m = 0; m < 4; ++m) _Pragma("unroll") for (int n = 0; n < 2; ++n) _Pragma("unroll") for (int k = 0; k < 2; ++k) \
;         acc[ai][bj][m][n] = __builtin_amdgcn_mfma_f32_16x16x32_bf16(Bt[n][k], At[m][k], acc[ai][bj][m][n], 0, 0, 0); __builtin_amdgcn_s_setprio(0); } while (0)
; #define PG8_WAIT_L(n) asm volatile("s_waitcnt lgkmcnt(" #n ")" ::: "memory")
; #define PG8_BAR __builtin_amdgcn_s_barrier()
; #define PG8_SCHED __builtin_amdgcn_sched_barrier(0)
; template <class Epi>
; __device__ __forceinline__ void gemm_phase(LAS unsigned char* lds, const Gemm g, const StaticOrder& S, const Epi& E) {
;     ...
;         for (int t = 0; t < nt; t += 2) {
;             const bool last = (t == nt - 2);
;             const char* a1 = cA + (size_t)(t + 1) * kstep;
;             const char* a2 = last ? nA : cA + (size_t)(t + 2) * kstep; const char* b2 = last ? nB : cB + (size_t)(t + 2) * kstep;
;             const char* a3 = a2 + kstep; const char* b3 = b2 + kstep;
;             PG8_LDB(B0, 0, 0); PG8_SCHED; PG8_LDA(At, 0, 0); PG8_STAGE(PG8_SA(1, 1), a1 + hstepA, voffA);
;             PG8_WAIT_L(8); PG8_BAR; PG8_WAIT_L(0); PG8_MMA(0, 0, At, B0); PG8_BAR; PG8_SCHED;
;             PG8_LDB(B1, 0, 1); PG8_STAGE(PG8_SB(0, 0), b2, voffB);
;             PG8_BAR; PG8_WAIT_L(0); PG8_MMA(0, 1, At, B1); PG8_BAR;
;             PG8_LDA(At, 0, 1); PG8_STAGE(PG8_SA(0, 0), a2, voffA);
;             PG8_BAR; PG8_WAIT_L(0); PG8_MMA(1, 0, At, B0); PG8_BAR; PG8_SCHED;
.LBB0_410:
	s_add_u32 s49, s28, 0x100
	s_addc_u32 s63, s29, 0
	s_mov_b32 s68, -2
	ds_read_b128 v[140:143], v149
	ds_read_b128 v[152:155], v149 offset:1024
	ds_read_b128 v[156:159], v149 offset:2048
	ds_read_b128 v[160:163], v149 offset:3072
	s_add_u32 s28, s26, 0x100
	s_addc_u32 s29, s27, 0
	s_cmp_eq_u32 s68, 40
	s_cselect_b32 s35, s11, s29
	s_cselect_b32 s34, s10, s28
	s_cselect_b32 s31, s13, s63
	s_cselect_b32 s30, s12, s49
	v_lshl_add_u64 v[144:145], s[26:27], 0, v[132:133]
	s_add_i32 m0, s36, 0xc000
	ds_read_b128 v[164:167], v150
	ds_read_b128 v[168:171], v150 offset:1024
	ds_read_b128 v[172:175], v150 offset:2048
	ds_read_b128 v[176:179], v150 offset:3072
	ds_read_b128 v[180:183], v150 offset:4096
	ds_read_b128 v[184:187], v150 offset:5120
	ds_read_b128 v[188:191], v150 offset:6144
	ds_read_b128 v[192:195], v150 offset:7168
	global_load_lds_dwordx4 v[144:145], off
	v_lshl_add_u64 v[144:145], s[26:27], 0, v[134:135]
	s_add_i32 m0, s36, 0xe000
	s_nop 0
	global_load_lds_dwordx4 v[144:145], off
	ds_read_b128 v[196:199], v151
	ds_read_b128 v[200:203], v151 offset:1024
	ds_read_b128 v[204:207], v151 offset:2048
	ds_read_b128 v[208:211], v151 offset:3072
	s_waitcnt lgkmcnt(0)
	s_barrier
	s_setprio 1
	v_mfma_f32_16x16x32_bf16 v[124:127], v[140:143], v[164:167], 0
	v_mfma_f32_16x16x32_bf16 v[120:123], v[156:159], v[164:167], 0
	v_mfma_f32_16x16x32_bf16 v[112:115], v[140:143], v[172:175], 0
	v_mfma_f32_16x16x32_bf16 v[104:107], v[156:159], v[172:175], 0
	v_mfma_f32_16x16x32_bf16 v[92:95], v[140:143], v[180:183], 0
	v_mfma_f32_16x16x32_bf16 v[88:91], v[156:159], v[180:183], 0
	v_mfma_f32_16x16x32_bf16 v[80:83], v[140:143], v[188:191], 0
	v_mfma_f32_16x16x32_bf16 v[72:75], v[156:159], v[188:191], 0
	v_mfma_f32_16x16x32_bf16 v[124:127], v[152:155], v[168:171], v[124:127]
	v_mfma_f32_16x16x32_bf16 v[120:123], v[160:163], v[168:171], v[120:123]
	v_mfma_f32_16x16x32_bf16 v[112:115], v[152:155], v[176:179], v[112:115]
	v_mfma_f32_16x16x32_bf16 v[104:107], v[160:163], v[176:179], v[104:107]
	v_mfma_f32_16x16x32_bf16 v[92:95], v[152:155], v[184:187], v[92:95]
	v_mfma_f32_16x16x32_bf16 v[88:91], v[160:163], v[184:187], v[88:91]
	v_mfma_f32_16x16x32_bf16 v[80:83], v[152:155], v[192:195], v[80:83]
	v_mfma_f32_16x16x32_bf16 v[72:75], v[160:163], v[192:195], v[72:75]
	v_mfma_f32_16x16x32_bf16 v[116:119], v[196:199], v[164:167], 0
	v_mfma_f32_16x16x32_bf16 v[108:111], v[204:207], v[164:167], 0
	v_mfma_f32_16x16x32_bf16 v[100:103], v[196:199], v[172:175], 0
	v_mfma_f32_16x16x32_bf16 v[96:99], v[204:207], v[172:175], 0
	v_mfma_f32_16x16x32_bf16 v[84:87], v[196:199], v[180:183], 0
	v_mfma_f32_16x16x32_bf16 v[76:79], v[204:207], v[180:183], 0
	v_mfma_f32_16x16x32_bf16 v[68:71], v[196:199], v[188:191], 0
	v_mfma_f32_16x16x32_bf16 v[64:67], v[204:207], v[188:191], 0
	v_mfma_f32_16x16x32_bf16 v[116:119], v[200:203], v[168:171], v[116:119]
	v_mfma_f32_16x16x32_bf16 v[108:111], v[208:211], v[168:171], v[108:111]
	v_mfma_f32_16x16x32_bf16 v[100:103], v[200:203], v[176:179], v[100:103]
	v_mfma_f32_16x16x32_bf16 v[96:99], v[208:211], v[176:179], v[96:99]
	v_mfma_f32_16x16x32_bf16 v[84:87], v[200:203], v[184:187], v[84:87]
	v_mfma_f32_16x16x32_bf16 v[76:79], v[208:211], v[184:187], v[76:79]
	v_mfma_f32_16x16x32_bf16 v[68:71], v[200:203], v[192:195], v[68:71]
	v_mfma_f32_16x16x32_bf16 v[64:67], v[208:211], v[192:195], v[64:67]
	s_setprio 0
	s_barrier
	s_nop 1
	ds_read_b128 v[164:167], v150 offset:16384
	ds_read_b128 v[168:171], v150 offset:17408
	ds_read_b128 v[172:175], v150 offset:18432
	ds_read_b128 v[176:179], v150 offset:19456
	ds_read_b128 v[180:183], v150 offset:20480
	ds_read_b128 v[184:187], v150 offset:21504
	ds_read_b128 v[188:191], v150 offset:22528
	ds_read_b128 v[192:195], v150 offset:23552
	s_add_i32 s26, s43, s7
	v_lshl_add_u64 v[144:145], s[30:31], 0, v[128:129]
	s_mov_b32 m0, s26
	s_nop 0
	global_load_lds_dwordx4 v[144:145], off
	v_lshl_add_u64 v[212:213], s[30:31], 0, v[130:131]
	s_add_i32 m0, s26, 0x2000
	s_nop 0
	global_load_lds_dwordx4 v[212:213], off
	s_mov_b32 m0, s36
	v_lshl_add_u64 v[214:215], s[34:35], 0, v[128:129]
	global_load_lds_dwordx4 v[214:215], off
	v_lshl_add_u64 v[216:217], s[34:35], 0, v[130:131]
	s_mov_b32 m0, s37
	s_nop 0
	global_load_lds_dwordx4 v[216:217], off
	s_add_u32 s26, s30, 0xb0000
	s_addc_u32 s27, s31, 0
	s_add_i32 s69, s44, s7
	v_lshl_add_u64 v[254:255], s[26:27], 0, v[128:129]
	s_mov_b32 m0, s69
	s_nop 0
	global_load_lds_dwordx4 v[254:255], off
	v_lshl_add_u64 v[254:255], s[26:27], 0, v[130:131]
	s_add_i32 m0, s69, 0x2000
	s_nop 0
	global_load_lds_dwordx4 v[254:255], off
	s_waitcnt vmcnt(6)
	s_waitcnt lgkmcnt(0)
	s_barrier
; #define PG8_STAGE(bufoff, gbase, voff) do { _Pragma("unroll") for (int _i = 0; _i < 2; ++_i) \
;         __builtin_amdgcn_global_load_lds((const unsigned*)((const char*)(gbase) + (voff)[_i]), (LAS unsigned*)(lds + (bufoff) + ldsw + _i * 8192), 16, 0, 0); } while (0)
; #define PG8_LDA(dst, b, h) do { _Pragma("unroll") for (int m = 0; m < 4; ++m) _Pragma("unroll") for (int k = 0; k < 2; ++k) dst[m][k] = *(const LAS bf16x8*)(lds + PG8_SA(b, h) + aoff + m * 2048 + k * 1024); } while (0)
; #define PG8_LDB(dst, b, h) do { _Pragma("unroll") for (int n = 0; n < 2; ++n) _Pragma("unroll") for (int k = 0; k < 2; ++k) dst[n][k] = *(const LAS bf16x8*)(lds + PG8_SB(b, h) + boff + n * 2048 + k * 1024); } while (0)
; #define PG8_MMA(ai, bj, At, Bt) do { __builtin_amdgcn_s_setprio(1); _Pragma("unroll") for (int m = 0; m < 4; ++m) _Pragma("unroll") for (int n = 0; n < 2; ++n) _Pragma("unroll") for (int k = 0; k < 2; ++k) \
;         acc[ai][bj][m][n] = __builtin_amdgcn_mfma_f32_16x16x32_bf16(Bt[n][k], At[m][k], acc[ai][bj][m][n], 0, 0, 0); __builtin_amdgcn_s_setprio(0); } while (0)
; #define PG8_WAIT_V(n) asm volatile("s_waitcnt vmcnt(" #n ")" ::: "memory")
; #define PG8_WAIT_L(n) asm volatile("s_waitcnt lgkmcnt(" #n ")" ::: "memory")
; #define PG8_BAR __builtin_amdgcn_s_barrier()
; #define PG8_SCHED __builtin_amdgcn_sched_barrier(0)
; template <class Epi>
; __device__ __forceinline__ void gemm_phase(LAS unsigned char* lds, const Gemm g, const StaticOrder& S, const Epi& E) {
;     ...
;             PG8_BAR; PG8_WAIT_L(0); PG8_MMA(1, 0, At, B0); PG8_BAR; PG8_SCHED;
;             PG8_STAGE(PG8_SB(0, 1), b2 + hstepB, voffB);
;             PG8_WAIT_V(6); PG8_BAR; PG8_MMA(1, 1, At, B1); PG8_BAR;
;             PG8_LDB(B0, 1, 0); PG8_SCHED; PG8_LDA(At, 1, 0); PG8_STAGE(PG8_SA(0, 1), a2 + hstepA, voffA);
;             PG8_WAIT_L(8); PG8_BAR; PG8_WAIT_L(0); PG8_MMA(0, 0, At, B0); PG8_BAR; PG8_SCHED;
;             PG8_LDB(B1, 1, 1); PG8_STAGE(PG8_SB(1, 0), b3, voffB);
;             PG8_BAR; PG8_WAIT_L(0); PG8_MMA(0, 1, At, B1); PG8_BAR;
	s_setprio 1
	v_mfma_f32_16x16x32_bf16 v[60:63], v[140:143], v[164:167], 0
	v_mfma_f32_16x16x32_bf16 v[56:59], v[156:159], v[164:167], 0
	v_mfma_f32_16x16x32_bf16 v[48:51], v[140:143], v[172:175], 0
	v_mfma_f32_16x16x32_bf16 v[40:43], v[156:159], v[172:175], 0
	v_mfma_f32_16x16x32_bf16 v[28:31], v[140:143], v[180:183], 0
	v_mfma_f32_16x16x32_bf16 v[24:27], v[156:159], v[180:183], 0
	v_mfma_f32_16x16x32_bf16 v[16:19], v[140:143], v[188:191], 0
	v_mfma_f32_16x16x32_bf16 v[8:11], v[156:159], v[188:191], 0
	v_mfma_f32_16x16x32_bf16 v[60:63], v[152:155], v[168:171], v[60:63]
	v_mfma_f32_16x16x32_bf16 v[56:59], v[160:163], v[168:171], v[56:59]
	v_mfma_f32_16x16x32_bf16 v[48:51], v[152:155], v[176:179], v[48:51]
	v_mfma_f32_16x16x32_bf16 v[40:43], v[160:163], v[176:179], v[40:43]
	v_mfma_f32_16x16x32_bf16 v[28:31], v[152:155], v[184:187], v[28:31]
	v_mfma_f32_16x16x32_bf16 v[24:27], v[160:163], v[184:187], v[24:27]
	v_mfma_f32_16x16x32_bf16 v[16:19], v[152:155], v[192:195], v[16:19]
	v_mfma_f32_16x16x32_bf16 v[8:11], v[160:163], v[192:195], v[8:11]
	v_mfma_f32_16x16x32_bf16 v[52:55], v[196:199], v[164:167], 0
	v_mfma_f32_16x16x32_bf16 v[44:47], v[204:207], v[164:167], 0
	v_mfma_f32_16x16x32_bf16 v[36:39], v[196:199], v[172:175], 0
	v_mfma_f32_16x16x32_bf16 v[32:35], v[204:207], v[172:175], 0
	v_mfma_f32_16x16x32_bf16 v[20:23], v[196:199], v[180:183], 0
	v_mfma_f32_16x16x32_bf16 v[12:15], v[204:207], v[180:183], 0
	v_mfma_f32_16x16x32_bf16 v[4:7], v[196:199], v[188:191], 0
	v_mfma_f32_16x16x32_bf16 v[0:3], v[204:207], v[188:191], 0
	v_mfma_f32_16x16x32_bf16 v[52:55], v[200:203], v[168:171], v[52:55]
	v_mfma_f32_16x16x32_bf16 v[44:47], v[208:211], v[168:171], v[44:47]
	v_mfma_f32_16x16x32_bf16 v[36:39], v[200:203], v[176:179], v[36:39]
	v_mfma_f32_16x16x32_bf16 v[32:35], v[208:211], v[176:179], v[32:35]
	v_mfma_f32_16x16x32_bf16 v[20:23], v[200:203], v[184:187], v[20:23]
	v_mfma_f32_16x16x32_bf16 v[12:15], v[208:211], v[184:187], v[12:15]
	v_mfma_f32_16x16x32_bf16 v[4:7], v[200:203], v[192:195], v[4:7]
	v_mfma_f32_16x16x32_bf16 v[0:3], v[208:211], v[192:195], v[0:3]
	s_setprio 0
	s_add_i32 s69, 0, 0x18000
	v_add_u32_e32 v160, s69, v147
	s_barrier
	ds_read_b128 v[140:143], v160
	ds_read_b128 v[152:155], v160 offset:1024
	ds_read_b128 v[156:159], v160 offset:2048
	ds_read_b128 v[160:163], v160 offset:3072
	s_add_u32 s26, s34, 0xb0000
	s_addc_u32 s27, s35, 0
	s_mov_b32 m0, s38
	v_lshl_add_u64 v[196:197], s[26:27], 0, v[128:129]
	ds_read_b128 v[164:167], v150 offset:32768
	ds_read_b128 v[168:171], v150 offset:33792
	ds_read_b128 v[172:175], v150 offset:34816
	ds_read_b128 v[176:179], v150 offset:35840
	ds_read_b128 v[180:183], v150 offset:36864
	ds_read_b128 v[184:187], v150 offset:37888
	ds_read_b128 v[188:191], v150 offset:38912
	ds_read_b128 v[192:195], v150 offset:39936
	global_load_lds_dwordx4 v[196:197], off
	v_lshl_add_u64 v[196:197], s[26:27], 0, v[130:131]
	s_mov_b32 m0, s39
	s_nop 0
	global_load_lds_dwordx4 v[196:197], off
	s_add_i32 s34, 0, 0x1c000
	v_add_u32_e32 v208, s34, v147
	ds_read_b128 v[196:199], v208
	ds_read_b128 v[200:203], v208 offset:1024
	ds_read_b128 v[204:207], v208 offset:2048
	ds_read_b128 v[208:211], v208 offset:3072
	s_waitcnt lgkmcnt(0)
	s_barrier
	s_setprio 1
	v_mfma_f32_16x16x32_bf16 v[124:127], v[140:143], v[164:167], v[124:127]
	v_mfma_f32_16x16x32_bf16 v[120:123], v[156:159], v[164:167], v[120:123]
	v_mfma_f32_16x16x32_bf16 v[112:115], v[140:143], v[172:175], v[112:115]
	v_mfma_f32_16x16x32_bf16 v[104:107], v[156:159], v[172:175], v[104:107]
	v_mfma_f32_16x16x32_bf16 v[92:95], v[140:143], v[180:183], v[92:95]
	v_mfma_f32_16x16x32_bf16 v[88:91], v[156:159], v[180:183], v[88:91]
	v_mfma_f32_16x16x32_bf16 v[80:83], v[140:143], v[188:191], v[80:83]
	v_mfma_f32_16x16x32_bf16 v[72:75], v[156:159], v[188:191], v[72:75]
	v_mfma_f32_16x16x32_bf16 v[124:127], v[152:155], v[168:171], v[124:127]
	v_mfma_f32_16x16x32_bf16 v[120:123], v[160:163], v[168:171], v[120:123]
	v_mfma_f32_16x16x32_bf16 v[112:115], v[152:155], v[176:179], v[112:115]
	v_mfma_f32_16x16x32_bf16 v[104:107], v[160:163], v[176:179], v[104:107]
	v_mfma_f32_16x16x32_bf16 v[92:95], v[152:155], v[184:187], v[92:95]
	v_mfma_f32_16x16x32_bf16 v[88:91], v[160:163], v[184:187], v[88:91]
	v_mfma_f32_16x16x32_bf16 v[80:83], v[152:155], v[192:195], v[80:83]
	v_mfma_f32_16x16x32_bf16 v[72:75], v[160:163], v[192:195], v[72:75]
	v_mfma_f32_16x16x32_bf16 v[116:119], v[196:199], v[164:167], v[116:119]
	v_mfma_f32_16x16x32_bf16 v[108:111], v[204:207], v[164:167], v[108:111]
	v_mfma_f32_16x16x32_bf16 v[100:103], v[196:199], v[172:175], v[100:103]
	v_mfma_f32_16x16x32_bf16 v[96:99], v[204:207], v[172:175], v[96:99]
	v_mfma_f32_16x16x32_bf16 v[84:87], v[196:199], v[180:183], v[84:87]
	v_mfma_f32_16x16x32_bf16 v[76:79], v[204:207], v[180:183], v[76:79]
	v_mfma_f32_16x16x32_bf16 v[68:71], v[196:199], v[188:191], v[68:71]
	v_mfma_f32_16x16x32_bf16 v[64:67], v[204:207], v[188:191], v[64:67]
	v_mfma_f32_16x16x32_bf16 v[116:119], v[200:203], v[168:171], v[116:119]
	v_mfma_f32_16x16x32_bf16 v[108:111], v[208:211], v[168:171], v[108:111]
	v_mfma_f32_16x16x32_bf16 v[100:103], v[200:203], v[176:179], v[100:103]
	v_mfma_f32_16x16x32_bf16 v[96:99], v[208:211], v[176:179], v[96:99]
	v_mfma_f32_16x16x32_bf16 v[84:87], v[200:203], v[184:187], v[84:87]
	v_mfma_f32_16x16x32_bf16 v[76:79], v[208:211], v[184:187], v[76:79]
	v_mfma_f32_16x16x32_bf16 v[68:71], v[200:203], v[192:195], v[68:71]
	v_mfma_f32_16x16x32_bf16 v[64:67], v[208:211], v[192:195], v[64:67]
	s_setprio 0
	s_barrier
; #define PG8_STAGE(bufoff, gbase, voff) do { _Pragma("unroll") for (int _i = 0; _i < 2; ++_i) \
;         __builtin_amdgcn_global_load_lds((const unsigned*)((const char*)(gbase) + (voff)[_i]), (LAS unsigned*)(lds + (bufoff) + ldsw + _i * 8192), 16, 0, 0); } while (0)
; #define PG8_LDA(dst, b, h) do { _Pragma("unroll") for (int m = 0; m < 4; ++m) _Pragma("unroll") for (int k = 0; k < 2; ++k) dst[m][k] = *(const LAS bf16x8*)(lds + PG8_SA(b, h) + aoff + m * 2048 + k * 1024); } while (0)
; #define PG8_MMA(ai, bj, At, Bt) do { __builtin_amdgcn_s_setprio(1); _Pragma("unroll") for (int m = 0; m < 4; ++m) _Pragma("unroll") for (int n = 0; n < 2; ++n) _Pragma("unroll") for (int k = 0; k < 2; ++k) \
;         acc[ai][bj][m][n] = __builtin_amdgcn_mfma_f32_16x16x32_bf16(Bt[n][k], At[m][k], acc[ai][bj][m][n], 0, 0, 0); __builtin_amdgcn_s_setprio(0); } while (0)
; #define PG8_WAIT_V(n) asm volatile("s_waitcnt vmcnt(" #n ")" ::: "memory")
; #define PG8_WAIT_L(n) asm volatile("s_waitcnt lgkmcnt(" #n ")" ::: "memory")
; #define PG8_BAR __builtin_amdgcn_s_barrier()
; #define PG8_SCHED __builtin_amdgcn_sched_barrier(0)
; template <class Epi>
; __device__ __forceinline__ void gemm_phase(LAS unsigned char* lds, const Gemm g, const StaticOrder& S, const Epi& E) {
;     ...
;             PG8_LDA(At, 1, 1); PG8_STAGE(PG8_SA(1, 0), a3, voffA);
;             PG8_BAR; PG8_WAIT_L(0); PG8_MMA(1, 0, At, B0); PG8_BAR; PG8_SCHED;
;             PG8_STAGE(PG8_SB(1, 1), b3 + hstepB, voffB);
;             PG8_WAIT_V(6); PG8_BAR; PG8_MMA(1, 1, At, B1); PG8_BAR;
	s_nop 1
	ds_read_b128 v[164:167], v150 offset:49152
	ds_read_b128 v[168:171], v150 offset:50176
	ds_read_b128 v[172:175], v150 offset:51200
	ds_read_b128 v[176:179], v150 offset:52224
	ds_read_b128 v[180:183], v150 offset:53248
	ds_read_b128 v[184:187], v150 offset:54272
	ds_read_b128 v[188:191], v150 offset:55296
	ds_read_b128 v[192:195], v150 offset:56320
	s_add_i32 s26, s69, s7
	v_lshl_add_u64 v[254:255], v[144:145], 0, s[16:17]
	s_mov_b32 m0, s26
	s_nop 0
	global_load_lds_dwordx4 v[254:255], off
	v_lshl_add_u64 v[254:255], v[212:213], 0, s[16:17]
	s_add_i32 m0, s26, 0x2000
	s_nop 0
	global_load_lds_dwordx4 v[254:255], off
	s_mov_b32 m0, s41
	v_lshl_add_u64 v[254:255], v[214:215], 0, s[16:17]
	global_load_lds_dwordx4 v[254:255], off
	v_lshl_add_u64 v[144:145], v[216:217], 0, s[16:17]
	s_mov_b32 m0, s42
	s_nop 0
	global_load_lds_dwordx4 v[144:145], off
	s_add_u32 s26, s30, 0xb0080
	s_addc_u32 s27, s31, 0
	s_add_i32 s30, s34, s7
	v_lshl_add_u64 v[254:255], s[26:27], 0, v[128:129]
	s_mov_b32 m0, s30
	s_nop 0
	global_load_lds_dwordx4 v[254:255], off
	v_lshl_add_u64 v[254:255], s[26:27], 0, v[130:131]
	s_add_i32 m0, s30, 0x2000
	s_nop 0
	global_load_lds_dwordx4 v[254:255], off
	s_waitcnt vmcnt(6)
	s_waitcnt lgkmcnt(0)
	s_barrier
	s_setprio 1
	v_mfma_f32_16x16x32_bf16 v[60:63], v[140:143], v[164:167], v[60:63]
	v_mfma_f32_16x16x32_bf16 v[56:59], v[156:159], v[164:167], v[56:59]
	v_mfma_f32_16x16x32_bf16 v[48:51], v[140:143], v[172:175], v[48:51]
	v_mfma_f32_16x16x32_bf16 v[40:43], v[156:159], v[172:175], v[40:43]
	v_mfma_f32_16x16x32_bf16 v[28:31], v[140:143], v[180:183], v[28:31]
	v_mfma_f32_16x16x32_bf16 v[24:27], v[156:159], v[180:183], v[24:27]
	v_mfma_f32_16x16x32_bf16 v[16:19], v[140:143], v[188:191], v[16:19]
	v_mfma_f32_16x16x32_bf16 v[8:11], v[156:159], v[188:191], v[8:11]
	v_mfma_f32_16x16x32_bf16 v[60:63], v[152:155], v[168:171], v[60:63]
	v_mfma_f32_16x16x32_bf16 v[56:59], v[160:163], v[168:171], v[56:59]
	v_mfma_f32_16x16x32_bf16 v[48:51], v[152:155], v[176:179], v[48:51]
	v_mfma_f32_16x16x32_bf16 v[40:43], v[160:163], v[176:179], v[40:43]
	v_mfma_f32_16x16x32_bf16 v[28:31], v[152:155], v[184:187], v[28:31]
	v_mfma_f32_16x16x32_bf16 v[24:27], v[160:163], v[184:187], v[24:27]
	v_mfma_f32_16x16x32_bf16 v[16:19], v[152:155], v[192:195], v[16:19]
	v_mfma_f32_16x16x32_bf16 v[8:11], v[160:163], v[192:195], v[8:11]
	v_mfma_f32_16x16x32_bf16 v[52:55], v[196:199], v[164:167], v[52:55]
	v_mfma_f32_16x16x32_bf16 v[44:47], v[204:207], v[164:167], v[44:47]
	v_mfma_f32_16x16x32_bf16 v[36:39], v[196:199], v[172:175], v[36:39]
	v_mfma_f32_16x16x32_bf16 v[32:35], v[204:207], v[172:175], v[32:35]
	v_mfma_f32_16x16x32_bf16 v[20:23], v[196:199], v[180:183], v[20:23]
	v_mfma_f32_16x16x32_bf16 v[12:15], v[204:207], v[180:183], v[12:15]
	v_mfma_f32_16x16x32_bf16 v[4:7], v[196:199], v[188:191], v[4:7]
	v_mfma_f32_16x16x32_bf16 v[0:3], v[204:207], v[188:191], v[0:3]
	v_mfma_f32_16x16x32_bf16 v[52:55], v[200:203], v[168:171], v[52:55]
	v_mfma_f32_16x16x32_bf16 v[44:47], v[208:211], v[168:171], v[44:47]
	v_mfma_f32_16x16x32_bf16 v[36:39], v[200:203], v[176:179], v[36:39]
	v_mfma_f32_16x16x32_bf16 v[32:35], v[208:211], v[176:179], v[32:35]
	v_mfma_f32_16x16x32_bf16 v[20:23], v[200:203], v[184:187], v[20:23]
	v_mfma_f32_16x16x32_bf16 v[12:15], v[208:211], v[184:187], v[12:15]
	v_mfma_f32_16x16x32_bf16 v[4:7], v[200:203], v[192:195], v[4:7]
	v_mfma_f32_16x16x32_bf16 v[0:3], v[208:211], v[192:195], v[0:3]
	s_setprio 0
	s_add_i32 s68, s68, 2
	s_add_u32 s49, s49, 0x100
	s_addc_u32 s63, s63, 0
	s_cmp_gt_u32 s68, 41
	s_mov_b64 s[26:27], s[28:29]
	s_barrier
	.p2alignl 6, 3212836864

; #define PG8_STAGE(bufoff, gbase, voff) do { _Pragma("unroll") for (int _i = 0; _i < 2; ++_i) \
;         __builtin_amdgcn_global_load_lds((const unsigned*)((const char*)(gbase) + (voff)[_i]), (LAS unsigned*)(lds + (bufoff) + ldsw + _i * 8192), 16, 0, 0); } while (0)
; #define PG8_LDA(dst, b, h) do { _Pragma("unroll") for (int m = 0; m < 4; ++m) _Pragma("unroll") for (int k = 0; k < 2; ++k) dst[m][k] = *(const LAS bf16x8*)(lds + PG8_SA(b, h) + aoff + m * 2048 + k * 1024); } while (0)
; #define PG8_LDB(dst, b, h) do { _Pragma("unroll") for (int n = 0; n < 2; ++n) _Pragma("unroll") for (int k = 0; k < 2; ++k) dst[n][k] = *(const LAS bf16x8*)(lds + PG8_SB(b, h) + boff + n * 2048 + k * 1024); } while (0)
; #define PG8_MMA(ai, bj, At, Bt) do { __builtin_amdgcn_s_setprio(1); _Pragma("unroll") for (int m = 0; m < 4; ++m) _Pragma("unroll") for (int n = 0; n < 2; ++n) _Pragma("unroll") for (int k = 0; k < 2; ++k) \
;         acc[ai][bj][m][n] = __builtin_amdgcn_mfma_f32_16x16x32_bf16(Bt[n][k], At[m][k], acc[ai][bj][m][n], 0, 0, 0); __builtin_amdgcn_s_setprio(0); } while (0)
; #define PG8_BAR __builtin_amdgcn_s_barrier()
; template <class Epi>
; __device__ __forceinline__ void gemm_phase(LAS unsigned char* lds, const Gemm g, const StaticOrder& S, const Epi& E) {
;     ...
;         const bool has_next = S.next(ui + 1, nxt);
;         const char* nA = has_next ? (const char*)g.A + (size_t)nxt.pm * tstepA + (size_t)(nxt.pn >> g.a_shift) * g.a_step : cA; const char* nB = has_next ? (const char*)g.Bt + (size_t)nxt.pn * tstepB : cB;
;         for (int t = 0; t < nt; t += 2) {
;             const bool last = (t == nt - 2);
;             const char* a1 = cA + (size_t)(t + 1) * kstep;
;             const char* a2 = last ? nA : cA + (size_t)(t + 2) * kstep; const char* b2 = last ? nB : cB + (size_t)(t + 2) * kstep;
;             const char* a3 = a2 + kstep; const char* b3 = b2 + kstep;
;             PG8_LDB(B0, 0, 0); PG8_SCHED; PG8_LDA(At, 0, 0); PG8_STAGE(PG8_SA(1, 1), a1 + hstepA, voffA);
;             PG8_WAIT_L(8); PG8_BAR; PG8_WAIT_L(0); PG8_MMA(0, 0, At, B0); PG8_BAR; PG8_SCHED;
;             PG8_LDB(B1, 0, 1); PG8_STAGE(PG8_SB(0, 0), b2, voffB);
;             PG8_BAR; PG8_WAIT_L(0); PG8_MMA(0, 1, At, B1); PG8_BAR;
;             PG8_LDA(At, 0, 1); PG8_STAGE(PG8_SA(0, 0), a2, voffA);
;             PG8_BAR; PG8_WAIT_L(0); PG8_MMA(1, 0, At, B0); PG8_BAR; PG8_SCHED;
.LBB0_637:
	s_ashr_i32 s31, s30, 31
	v_cmp_lt_i64_e32 vcc, s[34:35], v[168:169]
	s_lshl_b64 s[34:35], s[30:31], 19
	s_add_u32 s34, s60, s34
	s_addc_u32 s35, s61, s35
	s_and_b64 s[36:37], vcc, exec
	s_cselect_b32 s31, s35, s41
	s_cselect_b32 s72, s34, s40
	s_ashr_i32 s29, s28, 31
	s_lshl_b64 s[36:37], s[28:29], 19
	s_add_u32 s36, s5, s36
	s_addc_u32 s37, s6, s37
	s_and_b64 s[44:45], vcc, exec
	s_cselect_b32 s29, s37, s43
	s_cselect_b32 s73, s36, s42
	s_add_u32 s40, s40, 0x40080
	s_addc_u32 s41, s41, 0
	s_add_u32 s74, s42, 0x100
	s_addc_u32 s75, s43, 0
	s_mov_b32 s76, -2
	ds_read_b128 v[128:131], v185
	ds_read_b128 v[132:135], v185 offset:1024
	ds_read_b128 v[136:139], v185 offset:2048
	ds_read_b128 v[140:143], v185 offset:3072
	s_add_u32 s42, s40, 0xfffc0080
	s_addc_u32 s43, s41, -1
	s_cmp_eq_u32 s76, 12
	s_cselect_b32 s45, s31, s43
	s_cselect_b32 s44, s72, s42
	s_cselect_b32 s43, s29, s75
	s_cselect_b32 s42, s73, s74
	v_lshl_add_u64 v[180:181], s[40:41], 0, v[164:165]
	s_add_i32 m0, s39, 0xc000
	ds_read_b128 v[144:147], v186
	ds_read_b128 v[148:151], v186 offset:1024
	ds_read_b128 v[152:155], v186 offset:2048
	ds_read_b128 v[172:175], v186 offset:3072
	ds_read_b128 v[176:179], v186 offset:4096
	ds_read_b128 v[188:191], v186 offset:5120
	ds_read_b128 v[192:195], v186 offset:6144
	ds_read_b128 v[196:199], v186 offset:7168
	global_load_lds_dwordx4 v[180:181], off
	v_lshl_add_u64 v[180:181], s[40:41], 0, v[166:167]
	s_add_i32 m0, s39, 0xe000
	s_nop 0
	global_load_lds_dwordx4 v[180:181], off
	ds_read_b128 v[200:203], v187
	ds_read_b128 v[204:207], v187 offset:1024
	ds_read_b128 v[208:211], v187 offset:2048
	ds_read_b128 v[212:215], v187 offset:3072
	s_waitcnt lgkmcnt(0)
	s_barrier
	s_setprio 1
	v_mfma_f32_16x16x32_bf16 v[124:127], v[128:131], v[144:147], 0
	v_mfma_f32_16x16x32_bf16 v[116:119], v[136:139], v[144:147], 0
	v_mfma_f32_16x16x32_bf16 v[108:111], v[128:131], v[152:155], 0
	v_mfma_f32_16x16x32_bf16 v[100:103], v[136:139], v[152:155], 0
	v_mfma_f32_16x16x32_bf16 v[92:95], v[128:131], v[176:179], 0
	v_mfma_f32_16x16x32_bf16 v[84:87], v[136:139], v[176:179], 0
	v_mfma_f32_16x16x32_bf16 v[76:79], v[128:131], v[192:195], 0
	v_mfma_f32_16x16x32_bf16 v[68:71], v[136:139], v[192:195], 0
	v_mfma_f32_16x16x32_bf16 v[124:127], v[132:135], v[148:151], v[124:127]
	v_mfma_f32_16x16x32_bf16 v[116:119], v[140:143], v[148:151], v[116:119]
	v_mfma_f32_16x16x32_bf16 v[108:111], v[132:135], v[172:175], v[108:111]
	v_mfma_f32_16x16x32_bf16 v[100:103], v[140:143], v[172:175], v[100:103]
	v_mfma_f32_16x16x32_bf16 v[92:95], v[132:135], v[188:191], v[92:95]
	v_mfma_f32_16x16x32_bf16 v[84:87], v[140:143], v[188:191], v[84:87]
	v_mfma_f32_16x16x32_bf16 v[76:79], v[132:135], v[196:199], v[76:79]
	v_mfma_f32_16x16x32_bf16 v[68:71], v[140:143], v[196:199], v[68:71]
	v_mfma_f32_16x16x32_bf16 v[120:123], v[200:203], v[144:147], 0
	v_mfma_f32_16x16x32_bf16 v[112:115], v[208:211], v[144:147], 0
	v_mfma_f32_16x16x32_bf16 v[104:107], v[200:203], v[152:155], 0
	v_mfma_f32_16x16x32_bf16 v[96:99], v[208:211], v[152:155], 0
	v_mfma_f32_16x16x32_bf16 v[88:91], v[200:203], v[176:179], 0
	v_mfma_f32_16x16x32_bf16 v[80:83], v[208:211], v[176:179], 0
	v_mfma_f32_16x16x32_bf16 v[72:75], v[200:203], v[192:195], 0
	v_mfma_f32_16x16x32_bf16 v[64:67], v[208:211], v[192:195], 0
	v_mfma_f32_16x16x32_bf16 v[120:123], v[204:207], v[148:151], v[120:123]
	v_mfma_f32_16x16x32_bf16 v[112:115], v[212:215], v[148:151], v[112:115]
	v_mfma_f32_16x16x32_bf16 v[104:107], v[204:207], v[172:175], v[104:107]
	v_mfma_f32_16x16x32_bf16 v[96:99], v[212:215], v[172:175], v[96:99]
	v_mfma_f32_16x16x32_bf16 v[88:91], v[204:207], v[188:191], v[88:91]
	v_mfma_f32_16x16x32_bf16 v[80:83], v[212:215], v[188:191], v[80:83]
	v_mfma_f32_16x16x32_bf16 v[72:75], v[204:207], v[196:199], v[72:75]
	v_mfma_f32_16x16x32_bf16 v[64:67], v[212:215], v[196:199], v[64:67]
	s_setprio 0
	s_barrier
	s_nop 1
	ds_read_b128 v[144:147], v186 offset:16384
	ds_read_b128 v[148:151], v186 offset:17408
	ds_read_b128 v[152:155], v186 offset:18432
	ds_read_b128 v[172:175], v186 offset:19456
	ds_read_b128 v[176:179], v186 offset:20480
	ds_read_b128 v[188:191], v186 offset:21504
	ds_read_b128 v[192:195], v186 offset:22528
	ds_read_b128 v[196:199], v186 offset:23552
	s_add_i32 s77, s69, s7
	v_lshl_add_u64 v[180:181], s[42:43], 0, v[158:159]
	s_mov_b32 m0, s77
	s_nop 0
	global_load_lds_dwordx4 v[180:181], off
	v_lshl_add_u64 v[216:217], s[42:43], 0, v[162:163]
	s_add_i32 m0, s77, 0x2000
	s_nop 0
	global_load_lds_dwordx4 v[216:217], off
	s_mov_b32 m0, s39
	v_lshl_add_u64 v[220:221], s[44:45], 0, v[156:157]
	global_load_lds_dwordx4 v[220:221], off
	v_lshl_add_u64 v[222:223], s[44:45], 0, v[160:161]
	s_mov_b32 m0, s46
	s_nop 0
	global_load_lds_dwordx4 v[222:223], off
	s_add_u32 s78, s42, 0x40000
	s_addc_u32 s79, s43, 0
	s_add_i32 s77, s70, s7
	v_lshl_add_u64 v[254:255], s[78:79], 0, v[158:159]
	s_mov_b32 m0, s77
	s_nop 0
	global_load_lds_dwordx4 v[254:255], off
	v_lshl_add_u64 v[254:255], s[78:79], 0, v[162:163]
	s_add_i32 m0, s77, 0x2000
	s_nop 0
	global_load_lds_dwordx4 v[254:255], off
	s_waitcnt vmcnt(6)
	s_waitcnt lgkmcnt(0)
	s_barrier
; #define PG8_STAGE(bufoff, gbase, voff) do { _Pragma("unroll") for (int _i = 0; _i < 2; ++_i) \
;         __builtin_amdgcn_global_load_lds((const unsigned*)((const char*)(gbase) + (voff)[_i]), (LAS unsigned*)(lds + (bufoff) + ldsw + _i * 8192), 16, 0, 0); } while (0)
; #define PG8_LDA(dst, b, h) do { _Pragma("unroll") for (int m = 0; m < 4; ++m) _Pragma("unroll") for (int k = 0; k < 2; ++k) dst[m][k] = *(const LAS bf16x8*)(lds + PG8_SA(b, h) + aoff + m * 2048 + k * 1024); } while (0)
; #define PG8_LDB(dst, b, h) do { _Pragma("unroll") for (int n = 0; n < 2; ++n) _Pragma("unroll") for (int k = 0; k < 2; ++k) dst[n][k] = *(const LAS bf16x8*)(lds + PG8_SB(b, h) + boff + n * 2048 + k * 1024); } while (0)
; #define PG8_MMA(ai, bj, At, Bt) do { __builtin_amdgcn_s_setprio(1); _Pragma("unroll") for (int m = 0; m < 4; ++m) _Pragma("unroll") for (int n = 0; n < 2; ++n) _Pragma("unroll") for (int k = 0; k < 2; ++k) \
;         acc[ai][bj][m][n] = __builtin_amdgcn_mfma_f32_16x16x32_bf16(Bt[n][k], At[m][k], acc[ai][bj][m][n], 0, 0, 0); __builtin_amdgcn_s_setprio(0); } while (0)
; #define PG8_WAIT_V(n) asm volatile("s_waitcnt vmcnt(" #n ")" ::: "memory")
; #define PG8_WAIT_L(n) asm volatile("s_waitcnt lgkmcnt(" #n ")" ::: "memory")
; #define PG8_BAR __builtin_amdgcn_s_barrier()
; #define PG8_SCHED __builtin_amdgcn_sched_barrier(0)
; template <class Epi>
; __device__ __forceinline__ void gemm_phase(LAS unsigned char* lds, const Gemm g, const StaticOrder& S, const Epi& E) {
;     ...
;             PG8_BAR; PG8_WAIT_L(0); PG8_MMA(1, 0, At, B0); PG8_BAR; PG8_SCHED;
;             PG8_STAGE(PG8_SB(0, 1), b2 + hstepB, voffB);
;             PG8_WAIT_V(6); PG8_BAR; PG8_MMA(1, 1, At, B1); PG8_BAR;
;             PG8_LDB(B0, 1, 0); PG8_SCHED; PG8_LDA(At, 1, 0); PG8_STAGE(PG8_SA(0, 1), a2 + hstepA, voffA);
;             PG8_WAIT_L(8); PG8_BAR; PG8_WAIT_L(0); PG8_MMA(0, 0, At, B0); PG8_BAR; PG8_SCHED;
;             PG8_LDB(B1, 1, 1); PG8_STAGE(PG8_SB(1, 0), b3, voffB);
;             PG8_BAR; PG8_WAIT_L(0); PG8_MMA(0, 1, At, B1); PG8_BAR;
	s_setprio 1
	v_mfma_f32_16x16x32_bf16 v[60:63], v[128:131], v[144:147], 0
	v_mfma_f32_16x16x32_bf16 v[52:55], v[136:139], v[144:147], 0
	v_mfma_f32_16x16x32_bf16 v[44:47], v[128:131], v[152:155], 0
	v_mfma_f32_16x16x32_bf16 v[36:39], v[136:139], v[152:155], 0
	v_mfma_f32_16x16x32_bf16 v[28:31], v[128:131], v[176:179], 0
	v_mfma_f32_16x16x32_bf16 v[20:23], v[136:139], v[176:179], 0
	v_mfma_f32_16x16x32_bf16 v[12:15], v[128:131], v[192:195], 0
	v_mfma_f32_16x16x32_bf16 v[4:7], v[136:139], v[192:195], 0
	v_mfma_f32_16x16x32_bf16 v[60:63], v[132:135], v[148:151], v[60:63]
	v_mfma_f32_16x16x32_bf16 v[52:55], v[140:143], v[148:151], v[52:55]
	v_mfma_f32_16x16x32_bf16 v[44:47], v[132:135], v[172:175], v[44:47]
	v_mfma_f32_16x16x32_bf16 v[36:39], v[140:143], v[172:175], v[36:39]
	v_mfma_f32_16x16x32_bf16 v[28:31], v[132:135], v[188:191], v[28:31]
	v_mfma_f32_16x16x32_bf16 v[20:23], v[140:143], v[188:191], v[20:23]
	v_mfma_f32_16x16x32_bf16 v[12:15], v[132:135], v[196:199], v[12:15]
	v_mfma_f32_16x16x32_bf16 v[4:7], v[140:143], v[196:199], v[4:7]
	v_mfma_f32_16x16x32_bf16 v[56:59], v[200:203], v[144:147], 0
	v_mfma_f32_16x16x32_bf16 v[48:51], v[208:211], v[144:147], 0
	v_mfma_f32_16x16x32_bf16 v[40:43], v[200:203], v[152:155], 0
	v_mfma_f32_16x16x32_bf16 v[32:35], v[208:211], v[152:155], 0
	v_mfma_f32_16x16x32_bf16 v[24:27], v[200:203], v[176:179], 0
	v_mfma_f32_16x16x32_bf16 v[16:19], v[208:211], v[176:179], 0
	v_mfma_f32_16x16x32_bf16 v[8:11], v[200:203], v[192:195], 0
	v_mfma_f32_16x16x32_bf16 v[0:3], v[208:211], v[192:195], 0
	v_mfma_f32_16x16x32_bf16 v[56:59], v[204:207], v[148:151], v[56:59]
	v_mfma_f32_16x16x32_bf16 v[48:51], v[212:215], v[148:151], v[48:51]
	v_mfma_f32_16x16x32_bf16 v[40:43], v[204:207], v[172:175], v[40:43]
	v_mfma_f32_16x16x32_bf16 v[32:35], v[212:215], v[172:175], v[32:35]
	v_mfma_f32_16x16x32_bf16 v[24:27], v[204:207], v[188:191], v[24:27]
	v_mfma_f32_16x16x32_bf16 v[16:19], v[212:215], v[188:191], v[16:19]
	v_mfma_f32_16x16x32_bf16 v[8:11], v[204:207], v[196:199], v[8:11]
	v_mfma_f32_16x16x32_bf16 v[0:3], v[212:215], v[196:199], v[0:3]
	s_setprio 0
	s_add_i32 s77, 0, 0x18000
	v_add_u32_e32 v140, s77, v183
	s_barrier
	ds_read_b128 v[128:131], v140
	ds_read_b128 v[132:135], v140 offset:1024
	ds_read_b128 v[136:139], v140 offset:2048
	ds_read_b128 v[140:143], v140 offset:3072
	s_add_u32 s44, s44, 0x40000
	s_addc_u32 s45, s45, 0
	s_mov_b32 m0, s47
	v_lshl_add_u64 v[200:201], s[44:45], 0, v[156:157]
	ds_read_b128 v[144:147], v186 offset:32768
	ds_read_b128 v[148:151], v186 offset:33792
	ds_read_b128 v[152:155], v186 offset:34816
	ds_read_b128 v[172:175], v186 offset:35840
	ds_read_b128 v[176:179], v186 offset:36864
	ds_read_b128 v[188:191], v186 offset:37888
	ds_read_b128 v[192:195], v186 offset:38912
	ds_read_b128 v[196:199], v186 offset:39936
	global_load_lds_dwordx4 v[200:201], off
	v_lshl_add_u64 v[200:201], s[44:45], 0, v[160:161]
	s_mov_b32 m0, s48
	s_nop 0
	global_load_lds_dwordx4 v[200:201], off
	s_add_i32 s44, 0, 0x1c000
	v_add_u32_e32 v212, s44, v183
	ds_read_b128 v[200:203], v212
	ds_read_b128 v[204:207], v212 offset:1024
	ds_read_b128 v[208:211], v212 offset:2048
	ds_read_b128 v[212:215], v212 offset:3072
	s_waitcnt lgkmcnt(0)
	s_barrier
	s_setprio 1
	v_mfma_f32_16x16x32_bf16 v[124:127], v[128:131], v[144:147], v[124:127]
	v_mfma_f32_16x16x32_bf16 v[116:119], v[136:139], v[144:147], v[116:119]
	v_mfma_f32_16x16x32_bf16 v[108:111], v[128:131], v[152:155], v[108:111]
	v_mfma_f32_16x16x32_bf16 v[100:103], v[136:139], v[152:155], v[100:103]
	v_mfma_f32_16x16x32_bf16 v[92:95], v[128:131], v[176:179], v[92:95]
	v_mfma_f32_16x16x32_bf16 v[84:87], v[136:139], v[176:179], v[84:87]
	v_mfma_f32_16x16x32_bf16 v[76:79], v[128:131], v[192:195], v[76:79]
	v_mfma_f32_16x16x32_bf16 v[68:71], v[136:139], v[192:195], v[68:71]
	v_mfma_f32_16x16x32_bf16 v[124:127], v[132:135], v[148:151], v[124:127]
	v_mfma_f32_16x16x32_bf16 v[116:119], v[140:143], v[148:151], v[116:119]
	v_mfma_f32_16x16x32_bf16 v[108:111], v[132:135], v[172:175], v[108:111]
	v_mfma_f32_16x16x32_bf16 v[100:103], v[140:143], v[172:175], v[100:103]
	v_mfma_f32_16x16x32_bf16 v[92:95], v[132:135], v[188:191], v[92:95]
	v_mfma_f32_16x16x32_bf16 v[84:87], v[140:143], v[188:191], v[84:87]
	v_mfma_f32_16x16x32_bf16 v[76:79], v[132:135], v[196:199], v[76:79]
	v_mfma_f32_16x16x32_bf16 v[68:71], v[140:143], v[196:199], v[68:71]
	v_mfma_f32_16x16x32_bf16 v[120:123], v[200:203], v[144:147], v[120:123]
	v_mfma_f32_16x16x32_bf16 v[112:115], v[208:211], v[144:147], v[112:115]
	v_mfma_f32_16x16x32_bf16 v[104:107], v[200:203], v[152:155], v[104:107]
	v_mfma_f32_16x16x32_bf16 v[96:99], v[208:211], v[152:155], v[96:99]
	v_mfma_f32_16x16x32_bf16 v[88:91], v[200:203], v[176:179], v[88:91]
	v_mfma_f32_16x16x32_bf16 v[80:83], v[208:211], v[176:179], v[80:83]
	v_mfma_f32_16x16x32_bf16 v[72:75], v[200:203], v[192:195], v[72:75]
	v_mfma_f32_16x16x32_bf16 v[64:67], v[208:211], v[192:195], v[64:67]
	v_mfma_f32_16x16x32_bf16 v[120:123], v[204:207], v[148:151], v[120:123]
	v_mfma_f32_16x16x32_bf16 v[112:115], v[212:215], v[148:151], v[112:115]
	v_mfma_f32_16x16x32_bf16 v[104:107], v[204:207], v[172:175], v[104:107]
	v_mfma_f32_16x16x32_bf16 v[96:99], v[212:215], v[172:175], v[96:99]
	v_mfma_f32_16x16x32_bf16 v[88:91], v[204:207], v[188:191], v[88:91]
	v_mfma_f32_16x16x32_bf16 v[80:83], v[212:215], v[188:191], v[80:83]
	v_mfma_f32_16x16x32_bf16 v[72:75], v[204:207], v[196:199], v[72:75]
	v_mfma_f32_16x16x32_bf16 v[64:67], v[212:215], v[196:199], v[64:67]
	s_setprio 0
	s_barrier
; #define PG8_STAGE(bufoff, gbase, voff) do { _Pragma("unroll") for (int _i = 0; _i < 2; ++_i) \
;         __builtin_amdgcn_global_load_lds((const unsigned*)((const char*)(gbase) + (voff)[_i]), (LAS unsigned*)(lds + (bufoff) + ldsw + _i * 8192), 16, 0, 0); } while (0)
; #define PG8_LDA(dst, b, h) do { _Pragma("unroll") for (int m = 0; m < 4; ++m) _Pragma("unroll") for (int k = 0; k < 2; ++k) dst[m][k] = *(const LAS bf16x8*)(lds + PG8_SA(b, h) + aoff + m * 2048 + k * 1024); } while (0)
; #define PG8_MMA(ai, bj, At, Bt) do { __builtin_amdgcn_s_setprio(1); _Pragma("unroll") for (int m = 0; m < 4; ++m) _Pragma("unroll") for (int n = 0; n < 2; ++n) _Pragma("unroll") for (int k = 0; k < 2; ++k) \
;         acc[ai][bj][m][n] = __builtin_amdgcn_mfma_f32_16x16x32_bf16(Bt[n][k], At[m][k], acc[ai][bj][m][n], 0, 0, 0); __builtin_amdgcn_s_setprio(0); } while (0)
; #define PG8_WAIT_V(n) asm volatile("s_waitcnt vmcnt(" #n ")" ::: "memory")
; #define PG8_WAIT_L(n) asm volatile("s_waitcnt lgkmcnt(" #n ")" ::: "memory")
; #define PG8_BAR __builtin_amdgcn_s_barrier()
; #define PG8_SCHED __builtin_amdgcn_sched_barrier(0)
; template <class Epi>
; __device__ __forceinline__ void gemm_phase(LAS unsigned char* lds, const Gemm g, const StaticOrder& S, const Epi& E) {
;     ...
;             PG8_LDA(At, 1, 1); PG8_STAGE(PG8_SA(1, 0), a3, voffA);
;             PG8_BAR; PG8_WAIT_L(0); PG8_MMA(1, 0, At, B0); PG8_BAR; PG8_SCHED;
;             PG8_STAGE(PG8_SB(1, 1), b3 + hstepB, voffB);
;             PG8_WAIT_V(6); PG8_BAR; PG8_MMA(1, 1, At, B1); PG8_BAR;
	s_nop 1
	ds_read_b128 v[144:147], v186 offset:49152
	ds_read_b128 v[148:151], v186 offset:50176
	ds_read_b128 v[152:155], v186 offset:51200
	ds_read_b128 v[172:175], v186 offset:52224
	ds_read_b128 v[176:179], v186 offset:53248
	ds_read_b128 v[188:191], v186 offset:54272
	ds_read_b128 v[192:195], v186 offset:55296
	ds_read_b128 v[196:199], v186 offset:56320
	s_add_i32 s45, s77, s7
	v_lshl_add_u64 v[254:255], v[180:181], 0, s[12:13]
	s_mov_b32 m0, s45
	s_nop 0
	global_load_lds_dwordx4 v[254:255], off
	v_lshl_add_u64 v[254:255], v[216:217], 0, s[12:13]
	s_add_i32 m0, s45, 0x2000
	s_nop 0
	global_load_lds_dwordx4 v[254:255], off
	s_mov_b32 m0, s63
	v_lshl_add_u64 v[254:255], v[220:221], 0, s[12:13]
	global_load_lds_dwordx4 v[254:255], off
	v_lshl_add_u64 v[180:181], v[222:223], 0, s[12:13]
	s_mov_b32 m0, s68
	s_nop 0
	global_load_lds_dwordx4 v[180:181], off
	s_add_u32 s42, s42, 0x40080
	s_addc_u32 s43, s43, 0
	s_add_i32 s44, s44, s7
	v_lshl_add_u64 v[254:255], s[42:43], 0, v[158:159]
	s_mov_b32 m0, s44
	s_nop 0
	global_load_lds_dwordx4 v[254:255], off
	v_lshl_add_u64 v[254:255], s[42:43], 0, v[162:163]
	s_add_i32 m0, s44, 0x2000
	s_nop 0
	global_load_lds_dwordx4 v[254:255], off
	s_waitcnt vmcnt(6)
	s_waitcnt lgkmcnt(0)
	s_barrier
	s_setprio 1
	v_mfma_f32_16x16x32_bf16 v[60:63], v[128:131], v[144:147], v[60:63]
	v_mfma_f32_16x16x32_bf16 v[52:55], v[136:139], v[144:147], v[52:55]
	v_mfma_f32_16x16x32_bf16 v[44:47], v[128:131], v[152:155], v[44:47]
	v_mfma_f32_16x16x32_bf16 v[36:39], v[136:139], v[152:155], v[36:39]
	v_mfma_f32_16x16x32_bf16 v[28:31], v[128:131], v[176:179], v[28:31]
	v_mfma_f32_16x16x32_bf16 v[20:23], v[136:139], v[176:179], v[20:23]
	v_mfma_f32_16x16x32_bf16 v[12:15], v[128:131], v[192:195], v[12:15]
	v_mfma_f32_16x16x32_bf16 v[4:7], v[136:139], v[192:195], v[4:7]
	v_mfma_f32_16x16x32_bf16 v[60:63], v[132:135], v[148:151], v[60:63]
	v_mfma_f32_16x16x32_bf16 v[52:55], v[140:143], v[148:151], v[52:55]
	v_mfma_f32_16x16x32_bf16 v[44:47], v[132:135], v[172:175], v[44:47]
	v_mfma_f32_16x16x32_bf16 v[36:39], v[140:143], v[172:175], v[36:39]
	v_mfma_f32_16x16x32_bf16 v[28:31], v[132:135], v[188:191], v[28:31]
	v_mfma_f32_16x16x32_bf16 v[20:23], v[140:143], v[188:191], v[20:23]
	v_mfma_f32_16x16x32_bf16 v[12:15], v[132:135], v[196:199], v[12:15]
	v_mfma_f32_16x16x32_bf16 v[4:7], v[140:143], v[196:199], v[4:7]
	v_mfma_f32_16x16x32_bf16 v[56:59], v[200:203], v[144:147], v[56:59]
	v_mfma_f32_16x16x32_bf16 v[48:51], v[208:211], v[144:147], v[48:51]
	v_mfma_f32_16x16x32_bf16 v[40:43], v[200:203], v[152:155], v[40:43]
	v_mfma_f32_16x16x32_bf16 v[32:35], v[208:211], v[152:155], v[32:35]
	v_mfma_f32_16x16x32_bf16 v[24:27], v[200:203], v[176:179], v[24:27]
	v_mfma_f32_16x16x32_bf16 v[16:19], v[208:211], v[176:179], v[16:19]
	v_mfma_f32_16x16x32_bf16 v[8:11], v[200:203], v[192:195], v[8:11]
	v_mfma_f32_16x16x32_bf16 v[0:3], v[208:211], v[192:195], v[0:3]
	v_mfma_f32_16x16x32_bf16 v[56:59], v[204:207], v[148:151], v[56:59]
	v_mfma_f32_16x16x32_bf16 v[48:51], v[212:215], v[148:151], v[48:51]
	v_mfma_f32_16x16x32_bf16 v[40:43], v[204:207], v[172:175], v[40:43]
	v_mfma_f32_16x16x32_bf16 v[32:35], v[212:215], v[172:175], v[32:35]
	v_mfma_f32_16x16x32_bf16 v[24:27], v[204:207], v[188:191], v[24:27]
	v_mfma_f32_16x16x32_bf16 v[16:19], v[212:215], v[188:191], v[16:19]
	v_mfma_f32_16x16x32_bf16 v[8:11], v[204:207], v[196:199], v[8:11]
	v_mfma_f32_16x16x32_bf16 v[0:3], v[212:215], v[196:199], v[0:3]
	s_setprio 0
	s_add_i32 s76, s76, 2
	s_add_u32 s40, s40, 0x100
	s_addc_u32 s41, s41, 0
	s_add_u32 s74, s74, 0x100
	s_addc_u32 s75, s75, 0
	s_cmp_gt_u32 s76, 13
	s_barrier
	.p2alignl 6, 3212836864

; #define PG8_STAGE(bufoff, gbase, voff) do { _Pragma("unroll") for (int _i = 0; _i < 2; ++_i) \
;         __builtin_amdgcn_global_load_lds((const unsigned*)((const char*)(gbase) + (voff)[_i]), (LAS unsigned*)(lds + (bufoff) + ldsw + _i * 8192), 16, 0, 0); } while (0)
; #define PG8_LDA(dst, b, h) do { _Pragma("unroll") for (int m = 0; m < 4; ++m) _Pragma("unroll") for (int k = 0; k < 2; ++k) dst[m][k] = *(const LAS bf16x8*)(lds + PG8_SA(b, h) + aoff + m * 2048 + k * 1024); } while (0)
; #define PG8_LDB(dst, b, h) do { _Pragma("unroll") for (int n = 0; n < 2; ++n) _Pragma("unroll") for (int k = 0; k < 2; ++k) dst[n][k] = *(const LAS bf16x8*)(lds + PG8_SB(b, h) + boff + n * 2048 + k * 1024); } while (0)
; #define PG8_MMA(ai, bj, At, Bt) do { __builtin_amdgcn_s_setprio(1); _Pragma("unroll") for (int m = 0; m < 4; ++m) _Pragma("unroll") for (int n = 0; n < 2; ++n) _Pragma("unroll") for (int k = 0; k < 2; ++k) \
;         acc[ai][bj][m][n] = __builtin_amdgcn_mfma_f32_16x16x32_bf16(Bt[n][k], At[m][k], acc[ai][bj][m][n], 0, 0, 0); __builtin_amdgcn_s_setprio(0); } while (0)
; #define PG8_BAR __builtin_amdgcn_s_barrier()
; template <class Epi>
; __device__ __forceinline__ void gemm_phase(LAS unsigned char* lds, const Gemm g, const StaticOrder& S, const Epi& E) {
;     ...
;         const bool has_next = S.next(ui + 1, nxt);
;         const char* nA = has_next ? (const char*)g.A + (size_t)nxt.pm * tstepA + (size_t)(nxt.pn >> g.a_shift) * g.a_step : cA; const char* nB = has_next ? (const char*)g.Bt + (size_t)nxt.pn * tstepB : cB;
;         for (int t = 0; t < nt; t += 2) {
;             const bool last = (t == nt - 2);
;             const char* a1 = cA + (size_t)(t + 1) * kstep;
;             const char* a2 = last ? nA : cA + (size_t)(t + 2) * kstep; const char* b2 = last ? nB : cB + (size_t)(t + 2) * kstep;
;             const char* a3 = a2 + kstep; const char* b3 = b2 + kstep;
;             PG8_LDB(B0, 0, 0); PG8_SCHED; PG8_LDA(At, 0, 0); PG8_STAGE(PG8_SA(1, 1), a1 + hstepA, voffA);
;             PG8_WAIT_L(8); PG8_BAR; PG8_WAIT_L(0); PG8_MMA(0, 0, At, B0); PG8_BAR; PG8_SCHED;
;             PG8_LDB(B1, 0, 1); PG8_STAGE(PG8_SB(0, 0), b2, voffB);
;             PG8_BAR; PG8_WAIT_L(0); PG8_MMA(0, 1, At, B1); PG8_BAR;
;             PG8_LDA(At, 0, 1); PG8_STAGE(PG8_SA(0, 0), a2, voffA);
;             PG8_BAR; PG8_WAIT_L(0); PG8_MMA(1, 0, At, B0); PG8_BAR; PG8_SCHED;
.LBB0_757:
	s_ashr_i32 s35, s34, 31
	v_cmp_lt_i64_e32 vcc, s[36:37], v[228:229]
	s_lshl_b64 s[36:37], s[34:35], 19
	s_add_u32 s36, s66, s36
	s_addc_u32 s37, s67, s37
	s_and_b64 s[38:39], vcc, exec
	s_cselect_b32 s35, s37, s43
	s_cselect_b32 s77, s36, s42
	s_ashr_i32 s31, s30, 31
	s_lshl_b64 s[38:39], s[30:31], 19
	s_add_u32 s38, s5, s38
	s_addc_u32 s39, s6, s39
	s_and_b64 s[46:47], vcc, exec
	s_cselect_b32 s31, s39, s45
	s_cselect_b32 s78, s38, s44
	s_add_u32 s79, s44, 0x100
	s_addc_u32 s80, s45, 0
	s_mov_b32 s81, -2
	ds_read_b128 v[96:99], v243
	ds_read_b128 v[100:103], v243 offset:1024
	ds_read_b128 v[104:107], v243 offset:2048
	ds_read_b128 v[108:111], v243 offset:3072
	s_add_u32 s44, s42, 0x100
	s_addc_u32 s45, s43, 0
	s_cmp_eq_u32 s81, 12
	s_cselect_b32 s49, s35, s45
	s_cselect_b32 s48, s77, s44
	s_cselect_b32 s47, s31, s80
	s_cselect_b32 s46, s78, s79
	v_lshl_add_u64 v[176:177], s[42:43], 0, v[224:225]
	s_add_i32 m0, s9, 0xc000
	ds_read_b128 v[112:115], v244
	ds_read_b128 v[116:119], v244 offset:1024
	ds_read_b128 v[120:123], v244 offset:2048
	ds_read_b128 v[124:127], v244 offset:3072
	ds_read_b128 v[160:163], v244 offset:4096
	ds_read_b128 v[164:167], v244 offset:5120
	ds_read_b128 v[168:171], v244 offset:6144
	ds_read_b128 v[172:175], v244 offset:7168
	global_load_lds_dwordx4 v[176:177], off
	v_lshl_add_u64 v[176:177], s[42:43], 0, v[226:227]
	s_add_i32 m0, s9, 0xe000
	s_nop 0
	global_load_lds_dwordx4 v[176:177], off
	ds_read_b128 v[176:179], v245
	ds_read_b128 v[180:183], v245 offset:1024
	ds_read_b128 v[184:187], v245 offset:2048
	ds_read_b128 v[188:191], v245 offset:3072
	s_waitcnt lgkmcnt(0)
	s_barrier
	s_setprio 1
	v_mfma_f32_16x16x32_bf16 v[156:159], v[96:99], v[112:115], 0
	v_mfma_f32_16x16x32_bf16 v[60:63], v[104:107], v[112:115], 0
	v_mfma_f32_16x16x32_bf16 v[144:147], v[96:99], v[120:123], 0
	v_mfma_f32_16x16x32_bf16 v[48:51], v[104:107], v[120:123], 0
	v_mfma_f32_16x16x32_bf16 v[136:139], v[96:99], v[160:163], 0
	v_mfma_f32_16x16x32_bf16 v[40:43], v[104:107], v[160:163], 0
	v_mfma_f32_16x16x32_bf16 v[148:151], v[96:99], v[168:171], 0
	v_mfma_f32_16x16x32_bf16 v[52:55], v[104:107], v[168:171], 0
	v_mfma_f32_16x16x32_bf16 v[156:159], v[100:103], v[116:119], v[156:159]
	v_mfma_f32_16x16x32_bf16 v[60:63], v[108:111], v[116:119], v[60:63]
	v_mfma_f32_16x16x32_bf16 v[144:147], v[100:103], v[124:127], v[144:147]
	v_mfma_f32_16x16x32_bf16 v[48:51], v[108:111], v[124:127], v[48:51]
	v_mfma_f32_16x16x32_bf16 v[136:139], v[100:103], v[164:167], v[136:139]
	v_mfma_f32_16x16x32_bf16 v[40:43], v[108:111], v[164:167], v[40:43]
	v_mfma_f32_16x16x32_bf16 v[148:151], v[100:103], v[172:175], v[148:151]
	v_mfma_f32_16x16x32_bf16 v[52:55], v[108:111], v[172:175], v[52:55]
	v_mfma_f32_16x16x32_bf16 v[152:155], v[176:179], v[112:115], 0
	v_mfma_f32_16x16x32_bf16 v[56:59], v[184:187], v[112:115], 0
	v_mfma_f32_16x16x32_bf16 v[36:39], v[184:187], v[120:123], 0
	v_mfma_f32_16x16x32_bf16 v[32:35], v[184:187], v[160:163], 0
	v_mfma_f32_16x16x32_bf16 v[44:47], v[184:187], v[168:171], 0
	v_mfma_f32_16x16x32_bf16 v[152:155], v[180:183], v[116:119], v[152:155]
	v_mfma_f32_16x16x32_bf16 v[56:59], v[188:191], v[116:119], v[56:59]
	v_mfma_f32_16x16x32_bf16 v[112:115], v[176:179], v[120:123], 0
	v_mfma_f32_16x16x32_bf16 v[36:39], v[188:191], v[124:127], v[36:39]
	v_mfma_f32_16x16x32_bf16 v[116:119], v[176:179], v[160:163], 0
	v_mfma_f32_16x16x32_bf16 v[32:35], v[188:191], v[164:167], v[32:35]
	v_mfma_f32_16x16x32_bf16 v[120:123], v[176:179], v[168:171], 0
	v_mfma_f32_16x16x32_bf16 v[44:47], v[188:191], v[172:175], v[44:47]
	v_mfma_f32_16x16x32_bf16 v[112:115], v[180:183], v[124:127], v[112:115]
	v_mfma_f32_16x16x32_bf16 v[116:119], v[180:183], v[164:167], v[116:119]
	v_mfma_f32_16x16x32_bf16 v[120:123], v[180:183], v[172:175], v[120:123]
	s_setprio 0
	s_barrier
	s_nop 1
	ds_read_b128 v[124:127], v244 offset:16384
	ds_read_b128 v[128:131], v244 offset:17408
	ds_read_b128 v[132:135], v244 offset:18432
	ds_read_b128 v[140:143], v244 offset:19456
	ds_read_b128 v[160:163], v244 offset:20480
	ds_read_b128 v[164:167], v244 offset:21504
	ds_read_b128 v[168:171], v244 offset:22528
	ds_read_b128 v[172:175], v244 offset:23552
	s_add_i32 s42, s74, s7
	v_lshl_add_u64 v[196:197], s[46:47], 0, v[214:215]
	s_mov_b32 m0, s42
	s_nop 0
	global_load_lds_dwordx4 v[196:197], off
	v_lshl_add_u64 v[198:199], s[46:47], 0, v[210:211]
	s_add_i32 m0, s42, 0x2000
	s_nop 0
	global_load_lds_dwordx4 v[198:199], off
	s_mov_b32 m0, s9
	v_lshl_add_u64 v[200:201], s[48:49], 0, v[216:217]
	global_load_lds_dwordx4 v[200:201], off
	v_lshl_add_u64 v[202:203], s[48:49], 0, v[212:213]
	s_mov_b32 m0, s63
	s_nop 0
	global_load_lds_dwordx4 v[202:203], off
	s_add_u32 s42, s46, 0x40000
	s_addc_u32 s43, s47, 0
	s_add_i32 s82, s75, s7
	v_lshl_add_u64 v[254:255], s[42:43], 0, v[214:215]
	s_mov_b32 m0, s82
	s_nop 0
	global_load_lds_dwordx4 v[254:255], off
	v_lshl_add_u64 v[254:255], s[42:43], 0, v[210:211]
	s_add_i32 m0, s82, 0x2000
	s_nop 0
	global_load_lds_dwordx4 v[254:255], off
	s_waitcnt vmcnt(6)
	s_waitcnt lgkmcnt(0)
	s_barrier
; #define PG8_STAGE(bufoff, gbase, voff) do { _Pragma("unroll") for (int _i = 0; _i < 2; ++_i) \
;         __builtin_amdgcn_global_load_lds((const unsigned*)((const char*)(gbase) + (voff)[_i]), (LAS unsigned*)(lds + (bufoff) + ldsw + _i * 8192), 16, 0, 0); } while (0)
; #define PG8_LDA(dst, b, h) do { _Pragma("unroll") for (int m = 0; m < 4; ++m) _Pragma("unroll") for (int k = 0; k < 2; ++k) dst[m][k] = *(const LAS bf16x8*)(lds + PG8_SA(b, h) + aoff + m * 2048 + k * 1024); } while (0)
; #define PG8_LDB(dst, b, h) do { _Pragma("unroll") for (int n = 0; n < 2; ++n) _Pragma("unroll") for (int k = 0; k < 2; ++k) dst[n][k] = *(const LAS bf16x8*)(lds + PG8_SB(b, h) + boff + n * 2048 + k * 1024); } while (0)
; #define PG8_MMA(ai, bj, At, Bt) do { __builtin_amdgcn_s_setprio(1); _Pragma("unroll") for (int m = 0; m < 4; ++m) _Pragma("unroll") for (int n = 0; n < 2; ++n) _Pragma("unroll") for (int k = 0; k < 2; ++k) \
;         acc[ai][bj][m][n] = __builtin_amdgcn_mfma_f32_16x16x32_bf16(Bt[n][k], At[m][k], acc[ai][bj][m][n], 0, 0, 0); __builtin_amdgcn_s_setprio(0); } while (0)
; #define PG8_WAIT_V(n) asm volatile("s_waitcnt vmcnt(" #n ")" ::: "memory")
; #define PG8_WAIT_L(n) asm volatile("s_waitcnt lgkmcnt(" #n ")" ::: "memory")
; #define PG8_BAR __builtin_amdgcn_s_barrier()
; #define PG8_SCHED __builtin_amdgcn_sched_barrier(0)
; template <class Epi>
; __device__ __forceinline__ void gemm_phase(LAS unsigned char* lds, const Gemm g, const StaticOrder& S, const Epi& E) {
;     ...
;             PG8_BAR; PG8_WAIT_L(0); PG8_MMA(1, 0, At, B0); PG8_BAR; PG8_SCHED;
;             PG8_STAGE(PG8_SB(0, 1), b2 + hstepB, voffB);
;             PG8_WAIT_V(6); PG8_BAR; PG8_MMA(1, 1, At, B1); PG8_BAR;
;             PG8_LDB(B0, 1, 0); PG8_SCHED; PG8_LDA(At, 1, 0); PG8_STAGE(PG8_SA(0, 1), a2 + hstepA, voffA);
;             PG8_WAIT_L(8); PG8_BAR; PG8_WAIT_L(0); PG8_MMA(0, 0, At, B0); PG8_BAR; PG8_SCHED;
;             PG8_LDB(B1, 1, 1); PG8_STAGE(PG8_SB(1, 0), b3, voffB);
;             PG8_BAR; PG8_WAIT_L(0); PG8_MMA(0, 1, At, B1); PG8_BAR;
	s_setprio 1
	v_mfma_f32_16x16x32_bf16 v[92:95], v[96:99], v[124:127], 0
	v_mfma_f32_16x16x32_bf16 v[28:31], v[104:107], v[124:127], 0
	v_mfma_f32_16x16x32_bf16 v[80:83], v[96:99], v[132:135], 0
	v_mfma_f32_16x16x32_bf16 v[16:19], v[104:107], v[132:135], 0
	v_mfma_f32_16x16x32_bf16 v[76:79], v[96:99], v[160:163], 0
	v_mfma_f32_16x16x32_bf16 v[12:15], v[104:107], v[160:163], 0
	v_mfma_f32_16x16x32_bf16 v[84:87], v[96:99], v[168:171], 0
	v_mfma_f32_16x16x32_bf16 v[20:23], v[104:107], v[168:171], 0
	v_mfma_f32_16x16x32_bf16 v[92:95], v[100:103], v[128:131], v[92:95]
	v_mfma_f32_16x16x32_bf16 v[28:31], v[108:111], v[128:131], v[28:31]
	v_mfma_f32_16x16x32_bf16 v[80:83], v[100:103], v[140:143], v[80:83]
	v_mfma_f32_16x16x32_bf16 v[16:19], v[108:111], v[140:143], v[16:19]
	v_mfma_f32_16x16x32_bf16 v[76:79], v[100:103], v[164:167], v[76:79]
	v_mfma_f32_16x16x32_bf16 v[12:15], v[108:111], v[164:167], v[12:15]
	v_mfma_f32_16x16x32_bf16 v[84:87], v[100:103], v[172:175], v[84:87]
	v_mfma_f32_16x16x32_bf16 v[20:23], v[108:111], v[172:175], v[20:23]
	v_mfma_f32_16x16x32_bf16 v[88:91], v[176:179], v[124:127], 0
	v_mfma_f32_16x16x32_bf16 v[24:27], v[184:187], v[124:127], 0
	v_mfma_f32_16x16x32_bf16 v[68:71], v[176:179], v[132:135], 0
	v_mfma_f32_16x16x32_bf16 v[4:7], v[184:187], v[132:135], 0
	v_mfma_f32_16x16x32_bf16 v[64:67], v[176:179], v[160:163], 0
	v_mfma_f32_16x16x32_bf16 v[0:3], v[184:187], v[160:163], 0
	v_mfma_f32_16x16x32_bf16 v[72:75], v[176:179], v[168:171], 0
	v_mfma_f32_16x16x32_bf16 v[8:11], v[184:187], v[168:171], 0
	v_mfma_f32_16x16x32_bf16 v[88:91], v[180:183], v[128:131], v[88:91]
	v_mfma_f32_16x16x32_bf16 v[24:27], v[188:191], v[128:131], v[24:27]
	v_mfma_f32_16x16x32_bf16 v[68:71], v[180:183], v[140:143], v[68:71]
	v_mfma_f32_16x16x32_bf16 v[4:7], v[188:191], v[140:143], v[4:7]
	v_mfma_f32_16x16x32_bf16 v[64:67], v[180:183], v[164:167], v[64:67]
	v_mfma_f32_16x16x32_bf16 v[0:3], v[188:191], v[164:167], v[0:3]
	v_mfma_f32_16x16x32_bf16 v[72:75], v[180:183], v[172:175], v[72:75]
	v_mfma_f32_16x16x32_bf16 v[8:11], v[188:191], v[172:175], v[8:11]
	s_setprio 0
	s_add_i32 s82, 0, 0x18000
	v_add_u32_e32 v108, s82, v235
	s_barrier
	ds_read_b128 v[96:99], v108
	ds_read_b128 v[100:103], v108 offset:1024
	ds_read_b128 v[104:107], v108 offset:2048
	ds_read_b128 v[108:111], v108 offset:3072
	s_add_u32 s42, s48, 0x40000
	s_addc_u32 s43, s49, 0
	s_mov_b32 m0, s68
	v_lshl_add_u64 v[132:133], s[42:43], 0, v[216:217]
	ds_read_b128 v[124:127], v244 offset:32768
	ds_read_b128 v[128:131], v244 offset:33792
	ds_read_b128 v[140:143], v244 offset:34816
	ds_read_b128 v[160:163], v244 offset:35840
	ds_read_b128 v[164:167], v244 offset:36864
	ds_read_b128 v[168:171], v244 offset:37888
	ds_read_b128 v[172:175], v244 offset:38912
	ds_read_b128 v[176:179], v244 offset:39936
	global_load_lds_dwordx4 v[132:133], off
	v_lshl_add_u64 v[132:133], s[42:43], 0, v[212:213]
	s_mov_b32 m0, s69
	s_nop 0
	global_load_lds_dwordx4 v[132:133], off
	s_add_i32 s48, 0, 0x1c000
	v_add_u32_e32 v132, s48, v235
	ds_read_b128 v[180:183], v132
	ds_read_b128 v[184:187], v132 offset:1024
	ds_read_b128 v[188:191], v132 offset:2048
	ds_read_b128 v[192:195], v132 offset:3072
	s_waitcnt lgkmcnt(0)
	s_barrier
	s_setprio 1
	v_mfma_f32_16x16x32_bf16 v[132:135], v[96:99], v[124:127], v[156:159]
	v_mfma_f32_16x16x32_bf16 v[156:159], v[100:103], v[128:131], v[132:135]
	v_mfma_f32_16x16x32_bf16 v[132:135], v[96:99], v[140:143], v[144:147]
	v_mfma_f32_16x16x32_bf16 v[144:147], v[100:103], v[160:163], v[132:135]
	v_mfma_f32_16x16x32_bf16 v[132:135], v[96:99], v[164:167], v[136:139]
	v_mfma_f32_16x16x32_bf16 v[60:63], v[104:107], v[124:127], v[60:63]
	v_mfma_f32_16x16x32_bf16 v[48:51], v[104:107], v[140:143], v[48:51]
	v_mfma_f32_16x16x32_bf16 v[136:139], v[100:103], v[168:171], v[132:135]
	v_mfma_f32_16x16x32_bf16 v[40:43], v[104:107], v[164:167], v[40:43]
	v_mfma_f32_16x16x32_bf16 v[132:135], v[96:99], v[172:175], v[148:151]
	v_mfma_f32_16x16x32_bf16 v[52:55], v[104:107], v[172:175], v[52:55]
	v_mfma_f32_16x16x32_bf16 v[60:63], v[108:111], v[128:131], v[60:63]
	v_mfma_f32_16x16x32_bf16 v[48:51], v[108:111], v[160:163], v[48:51]
	v_mfma_f32_16x16x32_bf16 v[40:43], v[108:111], v[168:171], v[40:43]
	v_mfma_f32_16x16x32_bf16 v[148:151], v[100:103], v[176:179], v[132:135]
	v_mfma_f32_16x16x32_bf16 v[52:55], v[108:111], v[176:179], v[52:55]
	v_mfma_f32_16x16x32_bf16 v[132:135], v[180:183], v[124:127], v[152:155]
	v_mfma_f32_16x16x32_bf16 v[112:115], v[180:183], v[140:143], v[112:115]
	v_mfma_f32_16x16x32_bf16 v[152:155], v[184:187], v[128:131], v[132:135]
	v_mfma_f32_16x16x32_bf16 v[56:59], v[188:191], v[124:127], v[56:59]
	v_mfma_f32_16x16x32_bf16 v[132:135], v[184:187], v[160:163], v[112:115]
	v_mfma_f32_16x16x32_bf16 v[112:115], v[180:183], v[164:167], v[116:119]
	v_mfma_f32_16x16x32_bf16 v[56:59], v[192:195], v[128:131], v[56:59]
	v_mfma_f32_16x16x32_bf16 v[36:39], v[188:191], v[140:143], v[36:39]
	v_mfma_f32_16x16x32_bf16 v[128:131], v[184:187], v[168:171], v[112:115]
	v_mfma_f32_16x16x32_bf16 v[32:35], v[188:191], v[164:167], v[32:35]
	v_mfma_f32_16x16x32_bf16 v[112:115], v[180:183], v[172:175], v[120:123]
	v_mfma_f32_16x16x32_bf16 v[44:47], v[188:191], v[172:175], v[44:47]
	v_mfma_f32_16x16x32_bf16 v[36:39], v[192:195], v[160:163], v[36:39]
	v_mfma_f32_16x16x32_bf16 v[32:35], v[192:195], v[168:171], v[32:35]
	v_mfma_f32_16x16x32_bf16 v[140:143], v[184:187], v[176:179], v[112:115]
	v_mfma_f32_16x16x32_bf16 v[44:47], v[192:195], v[176:179], v[44:47]
	s_setprio 0
	s_barrier
; #define PG8_STAGE(bufoff, gbase, voff) do { _Pragma("unroll") for (int _i = 0; _i < 2; ++_i) \
;         __builtin_amdgcn_global_load_lds((const unsigned*)((const char*)(gbase) + (voff)[_i]), (LAS unsigned*)(lds + (bufoff) + ldsw + _i * 8192), 16, 0, 0); } while (0)
; #define PG8_LDA(dst, b, h) do { _Pragma("unroll") for (int m = 0; m < 4; ++m) _Pragma("unroll") for (int k = 0; k < 2; ++k) dst[m][k] = *(const LAS bf16x8*)(lds + PG8_SA(b, h) + aoff + m * 2048 + k * 1024); } while (0)
; #define PG8_MMA(ai, bj, At, Bt) do { __builtin_amdgcn_s_setprio(1); _Pragma("unroll") for (int m = 0; m < 4; ++m) _Pragma("unroll") for (int n = 0; n < 2; ++n) _Pragma("unroll") for (int k = 0; k < 2; ++k) \
;         acc[ai][bj][m][n] = __builtin_amdgcn_mfma_f32_16x16x32_bf16(Bt[n][k], At[m][k], acc[ai][bj][m][n], 0, 0, 0); __builtin_amdgcn_s_setprio(0); } while (0)
; #define PG8_WAIT_V(n) asm volatile("s_waitcnt vmcnt(" #n ")" ::: "memory")
; #define PG8_WAIT_L(n) asm volatile("s_waitcnt lgkmcnt(" #n ")" ::: "memory")
; #define PG8_BAR __builtin_amdgcn_s_barrier()
; #define PG8_SCHED __builtin_amdgcn_sched_barrier(0)
; template <class Epi>
; __device__ __forceinline__ void gemm_phase(LAS unsigned char* lds, const Gemm g, const StaticOrder& S, const Epi& E) {
;     ...
;             PG8_LDA(At, 1, 1); PG8_STAGE(PG8_SA(1, 0), a3, voffA);
;             PG8_BAR; PG8_WAIT_L(0); PG8_MMA(1, 0, At, B0); PG8_BAR; PG8_SCHED;
;             PG8_STAGE(PG8_SB(1, 1), b3 + hstepB, voffB);
;             PG8_WAIT_V(6); PG8_BAR; PG8_MMA(1, 1, At, B1); PG8_BAR;
	s_nop 1
	ds_read_b128 v[112:115], v244 offset:49152
	ds_read_b128 v[116:119], v244 offset:50176
	ds_read_b128 v[120:123], v244 offset:51200
	ds_read_b128 v[124:127], v244 offset:52224
	ds_read_b128 v[160:163], v244 offset:53248
	ds_read_b128 v[164:167], v244 offset:54272
	ds_read_b128 v[168:171], v244 offset:55296
	ds_read_b128 v[172:175], v244 offset:56320
	s_add_i32 s42, s82, s7
	v_lshl_add_u64 v[254:255], v[196:197], 0, s[20:21]
	s_mov_b32 m0, s42
	s_nop 0
	global_load_lds_dwordx4 v[254:255], off
	v_lshl_add_u64 v[254:255], v[198:199], 0, s[20:21]
	s_add_i32 m0, s42, 0x2000
	s_nop 0
	global_load_lds_dwordx4 v[254:255], off
	s_mov_b32 m0, s72
	v_lshl_add_u64 v[254:255], v[200:201], 0, s[20:21]
	global_load_lds_dwordx4 v[254:255], off
	v_lshl_add_u64 v[254:255], v[202:203], 0, s[20:21]
	s_mov_b32 m0, s73
	s_nop 0
	global_load_lds_dwordx4 v[254:255], off
	s_add_u32 s42, s46, 0x40080
	s_addc_u32 s43, s47, 0
	s_add_i32 s46, s48, s7
	v_lshl_add_u64 v[254:255], s[42:43], 0, v[214:215]
	s_mov_b32 m0, s46
	s_nop 0
	global_load_lds_dwordx4 v[254:255], off
	v_lshl_add_u64 v[254:255], s[42:43], 0, v[210:211]
	s_add_i32 m0, s46, 0x2000
	s_nop 0
	global_load_lds_dwordx4 v[254:255], off
	s_waitcnt vmcnt(6)
	s_waitcnt lgkmcnt(0)
	s_barrier
	s_setprio 1
	v_mfma_f32_16x16x32_bf16 v[92:95], v[96:99], v[112:115], v[92:95]
	v_mfma_f32_16x16x32_bf16 v[28:31], v[104:107], v[112:115], v[28:31]
	v_mfma_f32_16x16x32_bf16 v[80:83], v[96:99], v[120:123], v[80:83]
	v_mfma_f32_16x16x32_bf16 v[16:19], v[104:107], v[120:123], v[16:19]
	v_mfma_f32_16x16x32_bf16 v[76:79], v[96:99], v[160:163], v[76:79]
	v_mfma_f32_16x16x32_bf16 v[12:15], v[104:107], v[160:163], v[12:15]
	v_mfma_f32_16x16x32_bf16 v[84:87], v[96:99], v[168:171], v[84:87]
	v_mfma_f32_16x16x32_bf16 v[20:23], v[104:107], v[168:171], v[20:23]
	v_mfma_f32_16x16x32_bf16 v[92:95], v[100:103], v[116:119], v[92:95]
	v_mfma_f32_16x16x32_bf16 v[28:31], v[108:111], v[116:119], v[28:31]
	v_mfma_f32_16x16x32_bf16 v[80:83], v[100:103], v[124:127], v[80:83]
	v_mfma_f32_16x16x32_bf16 v[16:19], v[108:111], v[124:127], v[16:19]
	v_mfma_f32_16x16x32_bf16 v[76:79], v[100:103], v[164:167], v[76:79]
	v_mfma_f32_16x16x32_bf16 v[12:15], v[108:111], v[164:167], v[12:15]
	v_mfma_f32_16x16x32_bf16 v[84:87], v[100:103], v[172:175], v[84:87]
	v_mfma_f32_16x16x32_bf16 v[20:23], v[108:111], v[172:175], v[20:23]
	v_mfma_f32_16x16x32_bf16 v[88:91], v[180:183], v[112:115], v[88:91]
	v_mfma_f32_16x16x32_bf16 v[24:27], v[188:191], v[112:115], v[24:27]
	v_mfma_f32_16x16x32_bf16 v[68:71], v[180:183], v[120:123], v[68:71]
	v_mfma_f32_16x16x32_bf16 v[4:7], v[188:191], v[120:123], v[4:7]
	v_mfma_f32_16x16x32_bf16 v[64:67], v[180:183], v[160:163], v[64:67]
	v_mfma_f32_16x16x32_bf16 v[0:3], v[188:191], v[160:163], v[0:3]
	v_mfma_f32_16x16x32_bf16 v[72:75], v[180:183], v[168:171], v[72:75]
	v_mfma_f32_16x16x32_bf16 v[8:11], v[188:191], v[168:171], v[8:11]
	v_mfma_f32_16x16x32_bf16 v[88:91], v[184:187], v[116:119], v[88:91]
	v_mfma_f32_16x16x32_bf16 v[24:27], v[192:195], v[116:119], v[24:27]
	v_mfma_f32_16x16x32_bf16 v[68:71], v[184:187], v[124:127], v[68:71]
	v_mfma_f32_16x16x32_bf16 v[4:7], v[192:195], v[124:127], v[4:7]
	v_mfma_f32_16x16x32_bf16 v[64:67], v[184:187], v[164:167], v[64:67]
	v_mfma_f32_16x16x32_bf16 v[0:3], v[192:195], v[164:167], v[0:3]
	v_mfma_f32_16x16x32_bf16 v[72:75], v[184:187], v[172:175], v[72:75]
	v_mfma_f32_16x16x32_bf16 v[8:11], v[192:195], v[172:175], v[8:11]
	s_setprio 0
	s_add_i32 s81, s81, 2
	s_add_u32 s79, s79, 0x100
	s_addc_u32 s80, s80, 0
	s_cmp_gt_u32 s81, 13
	s_mov_b64 s[42:43], s[44:45]
	s_barrier
	.p2alignl 6, 3212836864

; #define PG8_STAGE(bufoff, gbase, voff) do { _Pragma("unroll") for (int _i = 0; _i < 2; ++_i) \
;         __builtin_amdgcn_global_load_lds((const unsigned*)((const char*)(gbase) + (voff)[_i]), (LAS unsigned*)(lds + (bufoff) + ldsw + _i * 8192), 16, 0, 0); } while (0)
; #define PG8_LDA(dst, b, h) do { _Pragma("unroll") for (int m = 0; m < 4; ++m) _Pragma("unroll") for (int k = 0; k < 2; ++k) dst[m][k] = *(const LAS bf16x8*)(lds + PG8_SA(b, h) + aoff + m * 2048 + k * 1024); } while (0)
; #define PG8_LDB(dst, b, h) do { _Pragma("unroll") for (int n = 0; n < 2; ++n) _Pragma("unroll") for (int k = 0; k < 2; ++k) dst[n][k] = *(const LAS bf16x8*)(lds + PG8_SB(b, h) + boff + n * 2048 + k * 1024); } while (0)
; #define PG8_MMA(ai, bj, At, Bt) do { __builtin_amdgcn_s_setprio(1); _Pragma("unroll") for (int m = 0; m < 4; ++m) _Pragma("unroll") for (int n = 0; n < 2; ++n) _Pragma("unroll") for (int k = 0; k < 2; ++k) \
;         acc[ai][bj][m][n] = __builtin_amdgcn_mfma_f32_16x16x32_bf16(Bt[n][k], At[m][k], acc[ai][bj][m][n], 0, 0, 0); __builtin_amdgcn_s_setprio(0); } while (0)
; #define PG8_WAIT_L(n) asm volatile("s_waitcnt lgkmcnt(" #n ")" ::: "memory")
; #define PG8_BAR __builtin_amdgcn_s_barrier()
; #define PG8_SCHED __builtin_amdgcn_sched_barrier(0)
; template <class Epi>
; __device__ __forceinline__ void gemm_phase(LAS unsigned char* lds, const Gemm g, const StaticOrder& S, const Epi& E) {
;     ...
;         for (int t = 0; t < nt; t += 2) {
;             const bool last = (t == nt - 2);
;             const char* a1 = cA + (size_t)(t + 1) * kstep;
;             const char* a2 = last ? nA : cA + (size_t)(t + 2) * kstep; const char* b2 = last ? nB : cB + (size_t)(t + 2) * kstep;
;             const char* a3 = a2 + kstep; const char* b3 = b2 + kstep;
;             PG8_LDB(B0, 0, 0); PG8_SCHED; PG8_LDA(At, 0, 0); PG8_STAGE(PG8_SA(1, 1), a1 + hstepA, voffA);
;             PG8_WAIT_L(8); PG8_BAR; PG8_WAIT_L(0); PG8_MMA(0, 0, At, B0); PG8_BAR; PG8_SCHED;
;             PG8_LDB(B1, 0, 1); PG8_STAGE(PG8_SB(0, 0), b2, voffB);
;             PG8_BAR; PG8_WAIT_L(0); PG8_MMA(0, 1, At, B1); PG8_BAR;
;             PG8_LDA(At, 0, 1); PG8_STAGE(PG8_SA(0, 0), a2, voffA);
;             PG8_BAR; PG8_WAIT_L(0); PG8_MMA(1, 0, At, B0); PG8_BAR; PG8_SCHED;
.LBB0_859:
	s_add_u32 s49, s30, 0x100
	s_addc_u32 s63, s31, 0
	s_mov_b32 s68, -2
	ds_read_b128 v[140:143], v149
	ds_read_b128 v[152:155], v149 offset:1024
	ds_read_b128 v[156:159], v149 offset:2048
	ds_read_b128 v[160:163], v149 offset:3072
	s_add_u32 s30, s28, 0x100
	s_addc_u32 s31, s29, 0
	s_cmp_eq_u32 s68, 40
	s_cselect_b32 s37, s13, s31
	s_cselect_b32 s36, s12, s30
	s_cselect_b32 s35, s15, s63
	s_cselect_b32 s34, s14, s49
	v_lshl_add_u64 v[144:145], s[28:29], 0, v[132:133]
	s_add_i32 m0, s8, 0xc000
	ds_read_b128 v[164:167], v150
	ds_read_b128 v[168:171], v150 offset:1024
	ds_read_b128 v[172:175], v150 offset:2048
	ds_read_b128 v[176:179], v150 offset:3072
	ds_read_b128 v[180:183], v150 offset:4096
	ds_read_b128 v[184:187], v150 offset:5120
	ds_read_b128 v[188:191], v150 offset:6144
	ds_read_b128 v[192:195], v150 offset:7168
	global_load_lds_dwordx4 v[144:145], off
	v_lshl_add_u64 v[144:145], s[28:29], 0, v[134:135]
	s_add_i32 m0, s8, 0xe000
	s_nop 0
	global_load_lds_dwordx4 v[144:145], off
	ds_read_b128 v[196:199], v151
	ds_read_b128 v[200:203], v151 offset:1024
	ds_read_b128 v[204:207], v151 offset:2048
	ds_read_b128 v[208:211], v151 offset:3072
	s_waitcnt lgkmcnt(0)
	s_barrier
	s_setprio 1
	v_mfma_f32_16x16x32_bf16 v[124:127], v[140:143], v[164:167], 0
	v_mfma_f32_16x16x32_bf16 v[120:123], v[156:159], v[164:167], 0
	v_mfma_f32_16x16x32_bf16 v[112:115], v[140:143], v[172:175], 0
	v_mfma_f32_16x16x32_bf16 v[104:107], v[156:159], v[172:175], 0
	v_mfma_f32_16x16x32_bf16 v[92:95], v[140:143], v[180:183], 0
	v_mfma_f32_16x16x32_bf16 v[88:91], v[156:159], v[180:183], 0
	v_mfma_f32_16x16x32_bf16 v[80:83], v[140:143], v[188:191], 0
	v_mfma_f32_16x16x32_bf16 v[72:75], v[156:159], v[188:191], 0
	v_mfma_f32_16x16x32_bf16 v[124:127], v[152:155], v[168:171], v[124:127]
	v_mfma_f32_16x16x32_bf16 v[120:123], v[160:163], v[168:171], v[120:123]
	v_mfma_f32_16x16x32_bf16 v[112:115], v[152:155], v[176:179], v[112:115]
	v_mfma_f32_16x16x32_bf16 v[104:107], v[160:163], v[176:179], v[104:107]
	v_mfma_f32_16x16x32_bf16 v[92:95], v[152:155], v[184:187], v[92:95]
	v_mfma_f32_16x16x32_bf16 v[88:91], v[160:163], v[184:187], v[88:91]
	v_mfma_f32_16x16x32_bf16 v[80:83], v[152:155], v[192:195], v[80:83]
	v_mfma_f32_16x16x32_bf16 v[72:75], v[160:163], v[192:195], v[72:75]
	v_mfma_f32_16x16x32_bf16 v[116:119], v[196:199], v[164:167], 0
	v_mfma_f32_16x16x32_bf16 v[108:111], v[204:207], v[164:167], 0
	v_mfma_f32_16x16x32_bf16 v[100:103], v[196:199], v[172:175], 0
	v_mfma_f32_16x16x32_bf16 v[96:99], v[204:207], v[172:175], 0
	v_mfma_f32_16x16x32_bf16 v[84:87], v[196:199], v[180:183], 0
	v_mfma_f32_16x16x32_bf16 v[76:79], v[204:207], v[180:183], 0
	v_mfma_f32_16x16x32_bf16 v[68:71], v[196:199], v[188:191], 0
	v_mfma_f32_16x16x32_bf16 v[64:67], v[204:207], v[188:191], 0
	v_mfma_f32_16x16x32_bf16 v[116:119], v[200:203], v[168:171], v[116:119]
	v_mfma_f32_16x16x32_bf16 v[108:111], v[208:211], v[168:171], v[108:111]
	v_mfma_f32_16x16x32_bf16 v[100:103], v[200:203], v[176:179], v[100:103]
	v_mfma_f32_16x16x32_bf16 v[96:99], v[208:211], v[176:179], v[96:99]
	v_mfma_f32_16x16x32_bf16 v[84:87], v[200:203], v[184:187], v[84:87]
	v_mfma_f32_16x16x32_bf16 v[76:79], v[208:211], v[184:187], v[76:79]
	v_mfma_f32_16x16x32_bf16 v[68:71], v[200:203], v[192:195], v[68:71]
	v_mfma_f32_16x16x32_bf16 v[64:67], v[208:211], v[192:195], v[64:67]
	s_setprio 0
	s_barrier
	s_nop 1
	ds_read_b128 v[164:167], v150 offset:16384
	ds_read_b128 v[168:171], v150 offset:17408
	ds_read_b128 v[172:175], v150 offset:18432
	ds_read_b128 v[176:179], v150 offset:19456
	ds_read_b128 v[180:183], v150 offset:20480
	ds_read_b128 v[184:187], v150 offset:21504
	ds_read_b128 v[188:191], v150 offset:22528
	ds_read_b128 v[192:195], v150 offset:23552
	s_add_i32 s28, s43, s7
	v_lshl_add_u64 v[144:145], s[34:35], 0, v[128:129]
	s_mov_b32 m0, s28
	s_nop 0
	global_load_lds_dwordx4 v[144:145], off
	v_lshl_add_u64 v[212:213], s[34:35], 0, v[130:131]
	s_add_i32 m0, s28, 0x2000
	s_nop 0
	global_load_lds_dwordx4 v[212:213], off
	s_mov_b32 m0, s8
	v_lshl_add_u64 v[214:215], s[36:37], 0, v[128:129]
	global_load_lds_dwordx4 v[214:215], off
	v_lshl_add_u64 v[216:217], s[36:37], 0, v[130:131]
	s_mov_b32 m0, s9
	s_nop 0
	global_load_lds_dwordx4 v[216:217], off
	s_add_u32 s28, s34, 0xb0000
	s_addc_u32 s29, s35, 0
	s_add_i32 s69, s44, s7
	v_lshl_add_u64 v[254:255], s[28:29], 0, v[128:129]
	s_mov_b32 m0, s69
	s_nop 0
	global_load_lds_dwordx4 v[254:255], off
	v_lshl_add_u64 v[254:255], s[28:29], 0, v[130:131]
	s_add_i32 m0, s69, 0x2000
	s_nop 0
	global_load_lds_dwordx4 v[254:255], off
	s_waitcnt vmcnt(6)
	s_waitcnt lgkmcnt(0)
	s_barrier
; #define PG8_STAGE(bufoff, gbase, voff) do { _Pragma("unroll") for (int _i = 0; _i < 2; ++_i) \
;         __builtin_amdgcn_global_load_lds((const unsigned*)((const char*)(gbase) + (voff)[_i]), (LAS unsigned*)(lds + (bufoff) + ldsw + _i * 8192), 16, 0, 0); } while (0)
; #define PG8_LDA(dst, b, h) do { _Pragma("unroll") for (int m = 0; m < 4; ++m) _Pragma("unroll") for (int k = 0; k < 2; ++k) dst[m][k] = *(const LAS bf16x8*)(lds + PG8_SA(b, h) + aoff + m * 2048 + k * 1024); } while (0)
; #define PG8_LDB(dst, b, h) do { _Pragma("unroll") for (int n = 0; n < 2; ++n) _Pragma("unroll") for (int k = 0; k < 2; ++k) dst[n][k] = *(const LAS bf16x8*)(lds + PG8_SB(b, h) + boff + n * 2048 + k * 1024); } while (0)
; #define PG8_MMA(ai, bj, At, Bt) do { __builtin_amdgcn_s_setprio(1); _Pragma("unroll") for (int m = 0; m < 4; ++m) _Pragma("unroll") for (int n = 0; n < 2; ++n) _Pragma("unroll") for (int k = 0; k < 2; ++k) \
;         acc[ai][bj][m][n] = __builtin_amdgcn_mfma_f32_16x16x32_bf16(Bt[n][k], At[m][k], acc[ai][bj][m][n], 0, 0, 0); __builtin_amdgcn_s_setprio(0); } while (0)
; #define PG8_WAIT_V(n) asm volatile("s_waitcnt vmcnt(" #n ")" ::: "memory")
; #define PG8_WAIT_L(n) asm volatile("s_waitcnt lgkmcnt(" #n ")" ::: "memory")
; #define PG8_BAR __builtin_amdgcn_s_barrier()
; #define PG8_SCHED __builtin_amdgcn_sched_barrier(0)
; template <class Epi>
; __device__ __forceinline__ void gemm_phase(LAS unsigned char* lds, const Gemm g, const StaticOrder& S, const Epi& E) {
;     ...
;             PG8_BAR; PG8_WAIT_L(0); PG8_MMA(1, 0, At, B0); PG8_BAR; PG8_SCHED;
;             PG8_STAGE(PG8_SB(0, 1), b2 + hstepB, voffB);
;             PG8_WAIT_V(6); PG8_BAR; PG8_MMA(1, 1, At, B1); PG8_BAR;
;             PG8_LDB(B0, 1, 0); PG8_SCHED; PG8_LDA(At, 1, 0); PG8_STAGE(PG8_SA(0, 1), a2 + hstepA, voffA);
;             PG8_WAIT_L(8); PG8_BAR; PG8_WAIT_L(0); PG8_MMA(0, 0, At, B0); PG8_BAR; PG8_SCHED;
;             PG8_LDB(B1, 1, 1); PG8_STAGE(PG8_SB(1, 0), b3, voffB);
;             PG8_BAR; PG8_WAIT_L(0); PG8_MMA(0, 1, At, B1); PG8_BAR;
	s_setprio 1
	v_mfma_f32_16x16x32_bf16 v[60:63], v[140:143], v[164:167], 0
	v_mfma_f32_16x16x32_bf16 v[56:59], v[156:159], v[164:167], 0
	v_mfma_f32_16x16x32_bf16 v[48:51], v[140:143], v[172:175], 0
	v_mfma_f32_16x16x32_bf16 v[40:43], v[156:159], v[172:175], 0
	v_mfma_f32_16x16x32_bf16 v[28:31], v[140:143], v[180:183], 0
	v_mfma_f32_16x16x32_bf16 v[24:27], v[156:159], v[180:183], 0
	v_mfma_f32_16x16x32_bf16 v[16:19], v[140:143], v[188:191], 0
	v_mfma_f32_16x16x32_bf16 v[8:11], v[156:159], v[188:191], 0
	v_mfma_f32_16x16x32_bf16 v[60:63], v[152:155], v[168:171], v[60:63]
	v_mfma_f32_16x16x32_bf16 v[56:59], v[160:163], v[168:171], v[56:59]
	v_mfma_f32_16x16x32_bf16 v[48:51], v[152:155], v[176:179], v[48:51]
	v_mfma_f32_16x16x32_bf16 v[40:43], v[160:163], v[176:179], v[40:43]
	v_mfma_f32_16x16x32_bf16 v[28:31], v[152:155], v[184:187], v[28:31]
	v_mfma_f32_16x16x32_bf16 v[24:27], v[160:163], v[184:187], v[24:27]
	v_mfma_f32_16x16x32_bf16 v[16:19], v[152:155], v[192:195], v[16:19]
	v_mfma_f32_16x16x32_bf16 v[8:11], v[160:163], v[192:195], v[8:11]
	v_mfma_f32_16x16x32_bf16 v[52:55], v[196:199], v[164:167], 0
	v_mfma_f32_16x16x32_bf16 v[44:47], v[204:207], v[164:167], 0
	v_mfma_f32_16x16x32_bf16 v[36:39], v[196:199], v[172:175], 0
	v_mfma_f32_16x16x32_bf16 v[32:35], v[204:207], v[172:175], 0
	v_mfma_f32_16x16x32_bf16 v[20:23], v[196:199], v[180:183], 0
	v_mfma_f32_16x16x32_bf16 v[12:15], v[204:207], v[180:183], 0
	v_mfma_f32_16x16x32_bf16 v[4:7], v[196:199], v[188:191], 0
	v_mfma_f32_16x16x32_bf16 v[0:3], v[204:207], v[188:191], 0
	v_mfma_f32_16x16x32_bf16 v[52:55], v[200:203], v[168:171], v[52:55]
	v_mfma_f32_16x16x32_bf16 v[44:47], v[208:211], v[168:171], v[44:47]
	v_mfma_f32_16x16x32_bf16 v[36:39], v[200:203], v[176:179], v[36:39]
	v_mfma_f32_16x16x32_bf16 v[32:35], v[208:211], v[176:179], v[32:35]
	v_mfma_f32_16x16x32_bf16 v[20:23], v[200:203], v[184:187], v[20:23]
	v_mfma_f32_16x16x32_bf16 v[12:15], v[208:211], v[184:187], v[12:15]
	v_mfma_f32_16x16x32_bf16 v[4:7], v[200:203], v[192:195], v[4:7]
	v_mfma_f32_16x16x32_bf16 v[0:3], v[208:211], v[192:195], v[0:3]
	s_setprio 0
	s_add_i32 s69, 0, 0x18000
	v_add_u32_e32 v160, s69, v147
	s_barrier
	ds_read_b128 v[140:143], v160
	ds_read_b128 v[152:155], v160 offset:1024
	ds_read_b128 v[156:159], v160 offset:2048
	ds_read_b128 v[160:163], v160 offset:3072
	s_add_u32 s28, s36, 0xb0000
	s_addc_u32 s29, s37, 0
	s_mov_b32 m0, s38
	v_lshl_add_u64 v[196:197], s[28:29], 0, v[128:129]
	ds_read_b128 v[164:167], v150 offset:32768
	ds_read_b128 v[168:171], v150 offset:33792
	ds_read_b128 v[172:175], v150 offset:34816
	ds_read_b128 v[176:179], v150 offset:35840
	ds_read_b128 v[180:183], v150 offset:36864
	ds_read_b128 v[184:187], v150 offset:37888
	ds_read_b128 v[188:191], v150 offset:38912
	ds_read_b128 v[192:195], v150 offset:39936
	global_load_lds_dwordx4 v[196:197], off
	v_lshl_add_u64 v[196:197], s[28:29], 0, v[130:131]
	s_mov_b32 m0, s39
	s_nop 0
	global_load_lds_dwordx4 v[196:197], off
	s_add_i32 s36, 0, 0x1c000
	v_add_u32_e32 v208, s36, v147
	ds_read_b128 v[196:199], v208
	ds_read_b128 v[200:203], v208 offset:1024
	ds_read_b128 v[204:207], v208 offset:2048
	ds_read_b128 v[208:211], v208 offset:3072
	s_waitcnt lgkmcnt(0)
	s_barrier
	s_setprio 1
	v_mfma_f32_16x16x32_bf16 v[124:127], v[140:143], v[164:167], v[124:127]
	v_mfma_f32_16x16x32_bf16 v[120:123], v[156:159], v[164:167], v[120:123]
	v_mfma_f32_16x16x32_bf16 v[112:115], v[140:143], v[172:175], v[112:115]
	v_mfma_f32_16x16x32_bf16 v[104:107], v[156:159], v[172:175], v[104:107]
	v_mfma_f32_16x16x32_bf16 v[92:95], v[140:143], v[180:183], v[92:95]
	v_mfma_f32_16x16x32_bf16 v[88:91], v[156:159], v[180:183], v[88:91]
	v_mfma_f32_16x16x32_bf16 v[80:83], v[140:143], v[188:191], v[80:83]
	v_mfma_f32_16x16x32_bf16 v[72:75], v[156:159], v[188:191], v[72:75]
	v_mfma_f32_16x16x32_bf16 v[124:127], v[152:155], v[168:171], v[124:127]
	v_mfma_f32_16x16x32_bf16 v[120:123], v[160:163], v[168:171], v[120:123]
	v_mfma_f32_16x16x32_bf16 v[112:115], v[152:155], v[176:179], v[112:115]
	v_mfma_f32_16x16x32_bf16 v[104:107], v[160:163], v[176:179], v[104:107]
	v_mfma_f32_16x16x32_bf16 v[92:95], v[152:155], v[184:187], v[92:95]
	v_mfma_f32_16x16x32_bf16 v[88:91], v[160:163], v[184:187], v[88:91]
	v_mfma_f32_16x16x32_bf16 v[80:83], v[152:155], v[192:195], v[80:83]
	v_mfma_f32_16x16x32_bf16 v[72:75], v[160:163], v[192:195], v[72:75]
	v_mfma_f32_16x16x32_bf16 v[116:119], v[196:199], v[164:167], v[116:119]
	v_mfma_f32_16x16x32_bf16 v[108:111], v[204:207], v[164:167], v[108:111]
	v_mfma_f32_16x16x32_bf16 v[100:103], v[196:199], v[172:175], v[100:103]
	v_mfma_f32_16x16x32_bf16 v[96:99], v[204:207], v[172:175], v[96:99]
	v_mfma_f32_16x16x32_bf16 v[84:87], v[196:199], v[180:183], v[84:87]
	v_mfma_f32_16x16x32_bf16 v[76:79], v[204:207], v[180:183], v[76:79]
	v_mfma_f32_16x16x32_bf16 v[68:71], v[196:199], v[188:191], v[68:71]
	v_mfma_f32_16x16x32_bf16 v[64:67], v[204:207], v[188:191], v[64:67]
	v_mfma_f32_16x16x32_bf16 v[116:119], v[200:203], v[168:171], v[116:119]
	v_mfma_f32_16x16x32_bf16 v[108:111], v[208:211], v[168:171], v[108:111]
	v_mfma_f32_16x16x32_bf16 v[100:103], v[200:203], v[176:179], v[100:103]
	v_mfma_f32_16x16x32_bf16 v[96:99], v[208:211], v[176:179], v[96:99]
	v_mfma_f32_16x16x32_bf16 v[84:87], v[200:203], v[184:187], v[84:87]
	v_mfma_f32_16x16x32_bf16 v[76:79], v[208:211], v[184:187], v[76:79]
	v_mfma_f32_16x16x32_bf16 v[68:71], v[200:203], v[192:195], v[68:71]
	v_mfma_f32_16x16x32_bf16 v[64:67], v[208:211], v[192:195], v[64:67]
	s_setprio 0
	s_barrier
; #define PG8_STAGE(bufoff, gbase, voff) do { _Pragma("unroll") for (int _i = 0; _i < 2; ++_i) \
;         __builtin_amdgcn_global_load_lds((const unsigned*)((const char*)(gbase) + (voff)[_i]), (LAS unsigned*)(lds + (bufoff) + ldsw + _i * 8192), 16, 0, 0); } while (0)
; #define PG8_LDA(dst, b, h) do { _Pragma("unroll") for (int m = 0; m < 4; ++m) _Pragma("unroll") for (int k = 0; k < 2; ++k) dst[m][k] = *(const LAS bf16x8*)(lds + PG8_SA(b, h) + aoff + m * 2048 + k * 1024); } while (0)
; #define PG8_MMA(ai, bj, At, Bt) do { __builtin_amdgcn_s_setprio(1); _Pragma("unroll") for (int m = 0; m < 4; ++m) _Pragma("unroll") for (int n = 0; n < 2; ++n) _Pragma("unroll") for (int k = 0; k < 2; ++k) \
;         acc[ai][bj][m][n] = __builtin_amdgcn_mfma_f32_16x16x32_bf16(Bt[n][k], At[m][k], acc[ai][bj][m][n], 0, 0, 0); __builtin_amdgcn_s_setprio(0); } while (0)
; #define PG8_WAIT_V(n) asm volatile("s_waitcnt vmcnt(" #n ")" ::: "memory")
; #define PG8_WAIT_L(n) asm volatile("s_waitcnt lgkmcnt(" #n ")" ::: "memory")
; #define PG8_BAR __builtin_amdgcn_s_barrier()
; #define PG8_SCHED __builtin_amdgcn_sched_barrier(0)
; template <class Epi>
; __device__ __forceinline__ void gemm_phase(LAS unsigned char* lds, const Gemm g, const StaticOrder& S, const Epi& E) {
;     ...
;             PG8_LDA(At, 1, 1); PG8_STAGE(PG8_SA(1, 0), a3, voffA);
;             PG8_BAR; PG8_WAIT_L(0); PG8_MMA(1, 0, At, B0); PG8_BAR; PG8_SCHED;
;             PG8_STAGE(PG8_SB(1, 1), b3 + hstepB, voffB);
;             PG8_WAIT_V(6); PG8_BAR; PG8_MMA(1, 1, At, B1); PG8_BAR;
	s_nop 1
	ds_read_b128 v[164:167], v150 offset:49152
	ds_read_b128 v[168:171], v150 offset:50176
	ds_read_b128 v[172:175], v150 offset:51200
	ds_read_b128 v[176:179], v150 offset:52224
	ds_read_b128 v[180:183], v150 offset:53248
	ds_read_b128 v[184:187], v150 offset:54272
	ds_read_b128 v[188:191], v150 offset:55296
	ds_read_b128 v[192:195], v150 offset:56320
	s_add_i32 s28, s69, s7
	v_lshl_add_u64 v[254:255], v[144:145], 0, s[20:21]
	s_mov_b32 m0, s28
	s_nop 0
	global_load_lds_dwordx4 v[254:255], off
	v_lshl_add_u64 v[254:255], v[212:213], 0, s[20:21]
	s_add_i32 m0, s28, 0x2000
	s_nop 0
	global_load_lds_dwordx4 v[254:255], off
	s_mov_b32 m0, s41
	v_lshl_add_u64 v[254:255], v[214:215], 0, s[20:21]
	global_load_lds_dwordx4 v[254:255], off
	v_lshl_add_u64 v[144:145], v[216:217], 0, s[20:21]
	s_mov_b32 m0, s42
	s_nop 0
	global_load_lds_dwordx4 v[144:145], off
	s_add_u32 s28, s34, 0xb0080
	s_addc_u32 s29, s35, 0
	s_add_i32 s34, s36, s7
	v_lshl_add_u64 v[254:255], s[28:29], 0, v[128:129]
	s_mov_b32 m0, s34
	s_nop 0
	global_load_lds_dwordx4 v[254:255], off
	v_lshl_add_u64 v[254:255], s[28:29], 0, v[130:131]
	s_add_i32 m0, s34, 0x2000
	s_nop 0
	global_load_lds_dwordx4 v[254:255], off
	s_waitcnt vmcnt(6)
	s_waitcnt lgkmcnt(0)
	s_barrier
	s_setprio 1
	v_mfma_f32_16x16x32_bf16 v[60:63], v[140:143], v[164:167], v[60:63]
	v_mfma_f32_16x16x32_bf16 v[56:59], v[156:159], v[164:167], v[56:59]
	v_mfma_f32_16x16x32_bf16 v[48:51], v[140:143], v[172:175], v[48:51]
	v_mfma_f32_16x16x32_bf16 v[40:43], v[156:159], v[172:175], v[40:43]
	v_mfma_f32_16x16x32_bf16 v[28:31], v[140:143], v[180:183], v[28:31]
	v_mfma_f32_16x16x32_bf16 v[24:27], v[156:159], v[180:183], v[24:27]
	v_mfma_f32_16x16x32_bf16 v[16:19], v[140:143], v[188:191], v[16:19]
	v_mfma_f32_16x16x32_bf16 v[8:11], v[156:159], v[188:191], v[8:11]
	v_mfma_f32_16x16x32_bf16 v[60:63], v[152:155], v[168:171], v[60:63]
	v_mfma_f32_16x16x32_bf16 v[56:59], v[160:163], v[168:171], v[56:59]
	v_mfma_f32_16x16x32_bf16 v[48:51], v[152:155], v[176:179], v[48:51]
	v_mfma_f32_16x16x32_bf16 v[40:43], v[160:163], v[176:179], v[40:43]
	v_mfma_f32_16x16x32_bf16 v[28:31], v[152:155], v[184:187], v[28:31]
	v_mfma_f32_16x16x32_bf16 v[24:27], v[160:163], v[184:187], v[24:27]
	v_mfma_f32_16x16x32_bf16 v[16:19], v[152:155], v[192:195], v[16:19]
	v_mfma_f32_16x16x32_bf16 v[8:11], v[160:163], v[192:195], v[8:11]
	v_mfma_f32_16x16x32_bf16 v[52:55], v[196:199], v[164:167], v[52:55]
	v_mfma_f32_16x16x32_bf16 v[44:47], v[204:207], v[164:167], v[44:47]
	v_mfma_f32_16x16x32_bf16 v[36:39], v[196:199], v[172:175], v[36:39]
	v_mfma_f32_16x16x32_bf16 v[32:35], v[204:207], v[172:175], v[32:35]
	v_mfma_f32_16x16x32_bf16 v[20:23], v[196:199], v[180:183], v[20:23]
	v_mfma_f32_16x16x32_bf16 v[12:15], v[204:207], v[180:183], v[12:15]
	v_mfma_f32_16x16x32_bf16 v[4:7], v[196:199], v[188:191], v[4:7]
	v_mfma_f32_16x16x32_bf16 v[0:3], v[204:207], v[188:191], v[0:3]
	v_mfma_f32_16x16x32_bf16 v[52:55], v[200:203], v[168:171], v[52:55]
	v_mfma_f32_16x16x32_bf16 v[44:47], v[208:211], v[168:171], v[44:47]
	v_mfma_f32_16x16x32_bf16 v[36:39], v[200:203], v[176:179], v[36:39]
	v_mfma_f32_16x16x32_bf16 v[32:35], v[208:211], v[176:179], v[32:35]
	v_mfma_f32_16x16x32_bf16 v[20:23], v[200:203], v[184:187], v[20:23]
	v_mfma_f32_16x16x32_bf16 v[12:15], v[208:211], v[184:187], v[12:15]
	v_mfma_f32_16x16x32_bf16 v[4:7], v[200:203], v[192:195], v[4:7]
	v_mfma_f32_16x16x32_bf16 v[0:3], v[208:211], v[192:195], v[0:3]
	s_setprio 0
	s_add_i32 s68, s68, 2
	s_add_u32 s49, s49, 0x100
	s_addc_u32 s63, s63, 0
	s_cmp_gt_u32 s68, 41
	s_mov_b64 s[28:29], s[30:31]
	s_barrier
	.p2alignl 6, 3212836864

; #define PG8_STAGE(bufoff, gbase, voff) do { _Pragma("unroll") for (int _i = 0; _i < 2; ++_i) \
;         __builtin_amdgcn_global_load_lds((const unsigned*)((const char*)(gbase) + (voff)[_i]), (LAS unsigned*)(lds + (bufoff) + ldsw + _i * 8192), 16, 0, 0); } while (0)
; #define PG8_LDA(dst, b, h) do { _Pragma("unroll") for (int m = 0; m < 4; ++m) _Pragma("unroll") for (int k = 0; k < 2; ++k) dst[m][k] = *(const LAS bf16x8*)(lds + PG8_SA(b, h) + aoff + m * 2048 + k * 1024); } while (0)
; #define PG8_LDB(dst, b, h) do { _Pragma("unroll") for (int n = 0; n < 2; ++n) _Pragma("unroll") for (int k = 0; k < 2; ++k) dst[n][k] = *(const LAS bf16x8*)(lds + PG8_SB(b, h) + boff + n * 2048 + k * 1024); } while (0)
; #define PG8_MMA(ai, bj, At, Bt) do { __builtin_amdgcn_s_setprio(1); _Pragma("unroll") for (int m = 0; m < 4; ++m) _Pragma("unroll") for (int n = 0; n < 2; ++n) _Pragma("unroll") for (int k = 0; k < 2; ++k) \
;         acc[ai][bj][m][n] = __builtin_amdgcn_mfma_f32_16x16x32_bf16(Bt[n][k], At[m][k], acc[ai][bj][m][n], 0, 0, 0); __builtin_amdgcn_s_setprio(0); } while (0)
; #define PG8_WAIT_L(n) asm volatile("s_waitcnt lgkmcnt(" #n ")" ::: "memory")
; #define PG8_BAR __builtin_amdgcn_s_barrier()
; template <class Epi>
; __device__ __forceinline__ void gemm_phase(LAS unsigned char* lds, const Gemm g, const StaticOrder& S, const Epi& E) {
;     ...
;         const bool has_next = S.next(ui + 1, nxt);
;         const char* nA = has_next ? (const char*)g.A + (size_t)nxt.pm * tstepA + (size_t)(nxt.pn >> g.a_shift) * g.a_step : cA; const char* nB = has_next ? (const char*)g.Bt + (size_t)nxt.pn * tstepB : cB;
;         for (int t = 0; t < nt; t += 2) {
;             const bool last = (t == nt - 2);
;             const char* a1 = cA + (size_t)(t + 1) * kstep;
;             const char* a2 = last ? nA : cA + (size_t)(t + 2) * kstep; const char* b2 = last ? nB : cB + (size_t)(t + 2) * kstep;
;             const char* a3 = a2 + kstep; const char* b3 = b2 + kstep;
;             PG8_LDB(B0, 0, 0); PG8_SCHED; PG8_LDA(At, 0, 0); PG8_STAGE(PG8_SA(1, 1), a1 + hstepA, voffA);
;             PG8_WAIT_L(8); PG8_BAR; PG8_WAIT_L(0); PG8_MMA(0, 0, At, B0); PG8_BAR; PG8_SCHED;
;             PG8_LDB(B1, 0, 1); PG8_STAGE(PG8_SB(0, 0), b2, voffB);
;             PG8_BAR; PG8_WAIT_L(0); PG8_MMA(0, 1, At, B1); PG8_BAR;
;             PG8_LDA(At, 0, 1); PG8_STAGE(PG8_SA(0, 0), a2, voffA);
.LBB0_989:
	s_ashr_i32 s71, s70, 31
	s_lshl_b64 s[10:11], s[70:71], 19
	v_cmp_lt_i64_e32 vcc, s[72:73], v[178:179]
	s_add_u32 s72, s66, s10
	s_addc_u32 s73, s67, s11
	s_and_b64 s[10:11], vcc, exec
	s_cselect_b32 s71, s73, s81
	s_cselect_b32 s77, s72, s80
	s_ashr_i32 s69, s68, 31
	s_lshl_b64 s[10:11], s[68:69], 19
	s_add_u32 s74, s88, s10
	s_addc_u32 s75, s89, s11
	s_and_b64 s[10:11], vcc, exec
	s_cselect_b32 s69, s75, s83
	s_cselect_b32 s79, s74, s82
	s_add_u32 vcc_lo, s82, 0x100
	s_addc_u32 vcc_hi, s83, 0
	s_mov_b32 s10, -2
	ds_read_b128 v[128:131], v214
	ds_read_b128 v[132:135], v214 offset:1024
	ds_read_b128 v[136:139], v214 offset:2048
	ds_read_b128 v[140:143], v214 offset:3072
	s_add_u32 s82, s80, 0x100
	s_addc_u32 s83, s81, 0
	s_cmp_eq_u32 s10, 12
	s_cselect_b32 s87, s71, s83
	s_cselect_b32 s86, s77, s82
	s_cselect_b32 s85, s69, vcc_hi
	s_cselect_b32 s84, s79, vcc_lo
	v_lshl_add_u64 v[160:161], s[80:81], 0, v[174:175]
	s_add_i32 m0, s91, 0xc000
	ds_read_b128 v[144:147], v215
	ds_read_b128 v[148:151], v215 offset:1024
	ds_read_b128 v[152:155], v215 offset:2048
	ds_read_b128 v[156:159], v215 offset:3072
	ds_read_b128 v[182:185], v215 offset:4096
	ds_read_b128 v[186:189], v215 offset:5120
	ds_read_b128 v[190:193], v215 offset:6144
	ds_read_b128 v[194:197], v215 offset:7168
	global_load_lds_dwordx4 v[160:161], off
	v_lshl_add_u64 v[160:161], s[80:81], 0, v[176:177]
	s_add_i32 m0, s91, 0xe000
	s_nop 0
	global_load_lds_dwordx4 v[160:161], off
	ds_read_b128 v[198:201], v216
	ds_read_b128 v[220:223], v216 offset:1024
	ds_read_b128 v[224:227], v216 offset:2048
	ds_read_b128 v[228:231], v216 offset:3072
	s_waitcnt lgkmcnt(0)
	s_barrier
	s_setprio 1
	v_mfma_f32_16x16x32_bf16 v[124:127], v[128:131], v[144:147], 0
	v_mfma_f32_16x16x32_bf16 v[120:123], v[136:139], v[144:147], 0
	v_mfma_f32_16x16x32_bf16 v[108:111], v[128:131], v[152:155], 0
	v_mfma_f32_16x16x32_bf16 v[104:107], v[136:139], v[152:155], 0
	v_mfma_f32_16x16x32_bf16 v[92:95], v[128:131], v[182:185], 0
	v_mfma_f32_16x16x32_bf16 v[88:91], v[136:139], v[182:185], 0
	v_mfma_f32_16x16x32_bf16 v[76:79], v[128:131], v[190:193], 0
	v_mfma_f32_16x16x32_bf16 v[72:75], v[136:139], v[190:193], 0
	v_mfma_f32_16x16x32_bf16 v[124:127], v[132:135], v[148:151], v[124:127]
	v_mfma_f32_16x16x32_bf16 v[120:123], v[140:143], v[148:151], v[120:123]
	v_mfma_f32_16x16x32_bf16 v[108:111], v[132:135], v[156:159], v[108:111]
	v_mfma_f32_16x16x32_bf16 v[104:107], v[140:143], v[156:159], v[104:107]
	v_mfma_f32_16x16x32_bf16 v[92:95], v[132:135], v[186:189], v[92:95]
	v_mfma_f32_16x16x32_bf16 v[88:91], v[140:143], v[186:189], v[88:91]
	v_mfma_f32_16x16x32_bf16 v[76:79], v[132:135], v[194:197], v[76:79]
	v_mfma_f32_16x16x32_bf16 v[72:75], v[140:143], v[194:197], v[72:75]
	v_mfma_f32_16x16x32_bf16 v[116:119], v[198:201], v[144:147], 0
	v_mfma_f32_16x16x32_bf16 v[112:115], v[224:227], v[144:147], 0
	v_mfma_f32_16x16x32_bf16 v[100:103], v[198:201], v[152:155], 0
	v_mfma_f32_16x16x32_bf16 v[96:99], v[224:227], v[152:155], 0
	v_mfma_f32_16x16x32_bf16 v[84:87], v[198:201], v[182:185], 0
	v_mfma_f32_16x16x32_bf16 v[80:83], v[224:227], v[182:185], 0
	v_mfma_f32_16x16x32_bf16 v[68:71], v[198:201], v[190:193], 0
	v_mfma_f32_16x16x32_bf16 v[64:67], v[224:227], v[190:193], 0
	v_mfma_f32_16x16x32_bf16 v[116:119], v[220:223], v[148:151], v[116:119]
	v_mfma_f32_16x16x32_bf16 v[112:115], v[228:231], v[148:151], v[112:115]
	v_mfma_f32_16x16x32_bf16 v[100:103], v[220:223], v[156:159], v[100:103]
	v_mfma_f32_16x16x32_bf16 v[96:99], v[228:231], v[156:159], v[96:99]
	v_mfma_f32_16x16x32_bf16 v[84:87], v[220:223], v[186:189], v[84:87]
	v_mfma_f32_16x16x32_bf16 v[80:83], v[228:231], v[186:189], v[80:83]
	v_mfma_f32_16x16x32_bf16 v[68:71], v[220:223], v[194:197], v[68:71]
	v_mfma_f32_16x16x32_bf16 v[64:67], v[228:231], v[194:197], v[64:67]
	s_setprio 0
	s_barrier
	s_nop 1
	ds_read_b128 v[144:147], v215 offset:16384
	ds_read_b128 v[148:151], v215 offset:17408
	ds_read_b128 v[152:155], v215 offset:18432
	ds_read_b128 v[156:159], v215 offset:19456
	ds_read_b128 v[182:185], v215 offset:20480
	ds_read_b128 v[186:189], v215 offset:21504
	ds_read_b128 v[190:193], v215 offset:22528
	ds_read_b128 v[194:197], v215 offset:23552
	s_add_i32 s11, s93, s90
	v_lshl_add_u64 v[160:161], s[84:85], 0, v[164:165]
	s_mov_b32 m0, s11
	s_nop 0
	global_load_lds_dwordx4 v[160:161], off
	v_lshl_add_u64 v[202:203], s[84:85], 0, v[168:169]
	s_add_i32 m0, s11, 0x2000
	s_nop 0
	global_load_lds_dwordx4 v[202:203], off
	s_mov_b32 m0, s91
	v_lshl_add_u64 v[232:233], s[86:87], 0, v[162:163]
	global_load_lds_dwordx4 v[232:233], off
	v_lshl_add_u64 v[236:237], s[86:87], 0, v[166:167]
	s_mov_b32 m0, s97
	s_nop 0
	global_load_lds_dwordx4 v[236:237], off
	s_add_u32 s80, s84, 0x40000
	s_addc_u32 s81, s85, 0
	s_add_i32 s11, s96, s90
	v_lshl_add_u64 v[254:255], s[80:81], 0, v[164:165]
	s_mov_b32 m0, s11
	s_nop 0
	global_load_lds_dwordx4 v[254:255], off
	v_lshl_add_u64 v[254:255], s[80:81], 0, v[168:169]
	s_add_i32 m0, s11, 0x2000
	s_nop 0
	global_load_lds_dwordx4 v[254:255], off
	s_waitcnt vmcnt(6)
	s_waitcnt lgkmcnt(0)
	s_barrier
; #define PG8_STAGE(bufoff, gbase, voff) do { _Pragma("unroll") for (int _i = 0; _i < 2; ++_i) \
;         __builtin_amdgcn_global_load_lds((const unsigned*)((const char*)(gbase) + (voff)[_i]), (LAS unsigned*)(lds + (bufoff) + ldsw + _i * 8192), 16, 0, 0); } while (0)
; #define PG8_LDA(dst, b, h) do { _Pragma("unroll") for (int m = 0; m < 4; ++m) _Pragma("unroll") for (int k = 0; k < 2; ++k) dst[m][k] = *(const LAS bf16x8*)(lds + PG8_SA(b, h) + aoff + m * 2048 + k * 1024); } while (0)
; #define PG8_LDB(dst, b, h) do { _Pragma("unroll") for (int n = 0; n < 2; ++n) _Pragma("unroll") for (int k = 0; k < 2; ++k) dst[n][k] = *(const LAS bf16x8*)(lds + PG8_SB(b, h) + boff + n * 2048 + k * 1024); } while (0)
; #define PG8_MMA(ai, bj, At, Bt) do { __builtin_amdgcn_s_setprio(1); _Pragma("unroll") for (int m = 0; m < 4; ++m) _Pragma("unroll") for (int n = 0; n < 2; ++n) _Pragma("unroll") for (int k = 0; k < 2; ++k) \
;         acc[ai][bj][m][n] = __builtin_amdgcn_mfma_f32_16x16x32_bf16(Bt[n][k], At[m][k], acc[ai][bj][m][n], 0, 0, 0); __builtin_amdgcn_s_setprio(0); } while (0)
; #define PG8_WAIT_V(n) asm volatile("s_waitcnt vmcnt(" #n ")" ::: "memory")
; #define PG8_WAIT_L(n) asm volatile("s_waitcnt lgkmcnt(" #n ")" ::: "memory")
; #define PG8_BAR __builtin_amdgcn_s_barrier()
; #define PG8_SCHED __builtin_amdgcn_sched_barrier(0)
; template <class Epi>
; __device__ __forceinline__ void gemm_phase(LAS unsigned char* lds, const Gemm g, const StaticOrder& S, const Epi& E) {
;     ...
;             PG8_BAR; PG8_WAIT_L(0); PG8_MMA(1, 0, At, B0); PG8_BAR; PG8_SCHED;
;             PG8_STAGE(PG8_SB(0, 1), b2 + hstepB, voffB);
;             PG8_WAIT_V(6); PG8_BAR; PG8_MMA(1, 1, At, B1); PG8_BAR;
;             PG8_LDB(B0, 1, 0); PG8_SCHED; PG8_LDA(At, 1, 0); PG8_STAGE(PG8_SA(0, 1), a2 + hstepA, voffA);
;             PG8_WAIT_L(8); PG8_BAR; PG8_WAIT_L(0); PG8_MMA(0, 0, At, B0); PG8_BAR; PG8_SCHED;
;             PG8_LDB(B1, 1, 1); PG8_STAGE(PG8_SB(1, 0), b3, voffB);
;             PG8_BAR; PG8_WAIT_L(0); PG8_MMA(0, 1, At, B1); PG8_BAR;
	s_setprio 1
	v_mfma_f32_16x16x32_bf16 v[60:63], v[128:131], v[144:147], 0
	v_mfma_f32_16x16x32_bf16 v[56:59], v[136:139], v[144:147], 0
	v_mfma_f32_16x16x32_bf16 v[44:47], v[128:131], v[152:155], 0
	v_mfma_f32_16x16x32_bf16 v[40:43], v[136:139], v[152:155], 0
	v_mfma_f32_16x16x32_bf16 v[28:31], v[128:131], v[182:185], 0
	v_mfma_f32_16x16x32_bf16 v[24:27], v[136:139], v[182:185], 0
	v_mfma_f32_16x16x32_bf16 v[12:15], v[128:131], v[190:193], 0
	v_mfma_f32_16x16x32_bf16 v[8:11], v[136:139], v[190:193], 0
	v_mfma_f32_16x16x32_bf16 v[60:63], v[132:135], v[148:151], v[60:63]
	v_mfma_f32_16x16x32_bf16 v[56:59], v[140:143], v[148:151], v[56:59]
	v_mfma_f32_16x16x32_bf16 v[44:47], v[132:135], v[156:159], v[44:47]
	v_mfma_f32_16x16x32_bf16 v[40:43], v[140:143], v[156:159], v[40:43]
	v_mfma_f32_16x16x32_bf16 v[28:31], v[132:135], v[186:189], v[28:31]
	v_mfma_f32_16x16x32_bf16 v[24:27], v[140:143], v[186:189], v[24:27]
	v_mfma_f32_16x16x32_bf16 v[12:15], v[132:135], v[194:197], v[12:15]
	v_mfma_f32_16x16x32_bf16 v[8:11], v[140:143], v[194:197], v[8:11]
	v_mfma_f32_16x16x32_bf16 v[52:55], v[198:201], v[144:147], 0
	v_mfma_f32_16x16x32_bf16 v[48:51], v[224:227], v[144:147], 0
	v_mfma_f32_16x16x32_bf16 v[36:39], v[198:201], v[152:155], 0
	v_mfma_f32_16x16x32_bf16 v[32:35], v[224:227], v[152:155], 0
	v_mfma_f32_16x16x32_bf16 v[20:23], v[198:201], v[182:185], 0
	v_mfma_f32_16x16x32_bf16 v[16:19], v[224:227], v[182:185], 0
	v_mfma_f32_16x16x32_bf16 v[4:7], v[198:201], v[190:193], 0
	v_mfma_f32_16x16x32_bf16 v[0:3], v[224:227], v[190:193], 0
	v_mfma_f32_16x16x32_bf16 v[52:55], v[220:223], v[148:151], v[52:55]
	v_mfma_f32_16x16x32_bf16 v[48:51], v[228:231], v[148:151], v[48:51]
	v_mfma_f32_16x16x32_bf16 v[36:39], v[220:223], v[156:159], v[36:39]
	v_mfma_f32_16x16x32_bf16 v[32:35], v[228:231], v[156:159], v[32:35]
	v_mfma_f32_16x16x32_bf16 v[20:23], v[220:223], v[186:189], v[20:23]
	v_mfma_f32_16x16x32_bf16 v[16:19], v[228:231], v[186:189], v[16:19]
	v_mfma_f32_16x16x32_bf16 v[4:7], v[220:223], v[194:197], v[4:7]
	v_mfma_f32_16x16x32_bf16 v[0:3], v[228:231], v[194:197], v[0:3]
	s_setprio 0
	s_add_i32 s11, 0, 0x18000
	v_add_u32_e32 v140, s11, v173
	s_barrier
	ds_read_b128 v[128:131], v140
	ds_read_b128 v[132:135], v140 offset:1024
	ds_read_b128 v[136:139], v140 offset:2048
	ds_read_b128 v[140:143], v140 offset:3072
	s_add_u32 s80, s86, 0x40000
	s_addc_u32 s81, s87, 0
	s_mov_b32 m0, s8
	v_lshl_add_u64 v[198:199], s[80:81], 0, v[162:163]
	ds_read_b128 v[144:147], v215 offset:32768
	ds_read_b128 v[148:151], v215 offset:33792
	ds_read_b128 v[152:155], v215 offset:34816
	ds_read_b128 v[156:159], v215 offset:35840
	ds_read_b128 v[182:185], v215 offset:36864
	ds_read_b128 v[186:189], v215 offset:37888
	ds_read_b128 v[190:193], v215 offset:38912
	ds_read_b128 v[194:197], v215 offset:39936
	global_load_lds_dwordx4 v[198:199], off
	v_lshl_add_u64 v[198:199], s[80:81], 0, v[166:167]
	s_mov_b32 m0, s9
	s_nop 0
	global_load_lds_dwordx4 v[198:199], off
	s_add_i32 s86, 0, 0x1c000
	v_add_u32_e32 v170, s86, v173
	ds_read_b128 v[198:201], v170
	ds_read_b128 v[220:223], v170 offset:1024
	ds_read_b128 v[224:227], v170 offset:2048
	ds_read_b128 v[228:231], v170 offset:3072
	s_waitcnt lgkmcnt(0)
	s_barrier
	s_setprio 1
	v_mfma_f32_16x16x32_bf16 v[124:127], v[128:131], v[144:147], v[124:127]
	v_mfma_f32_16x16x32_bf16 v[120:123], v[136:139], v[144:147], v[120:123]
	v_mfma_f32_16x16x32_bf16 v[108:111], v[128:131], v[152:155], v[108:111]
	v_mfma_f32_16x16x32_bf16 v[104:107], v[136:139], v[152:155], v[104:107]
	v_mfma_f32_16x16x32_bf16 v[92:95], v[128:131], v[182:185], v[92:95]
	v_mfma_f32_16x16x32_bf16 v[88:91], v[136:139], v[182:185], v[88:91]
	v_mfma_f32_16x16x32_bf16 v[76:79], v[128:131], v[190:193], v[76:79]
	v_mfma_f32_16x16x32_bf16 v[72:75], v[136:139], v[190:193], v[72:75]
	v_mfma_f32_16x16x32_bf16 v[124:127], v[132:135], v[148:151], v[124:127]
	v_mfma_f32_16x16x32_bf16 v[120:123], v[140:143], v[148:151], v[120:123]
	v_mfma_f32_16x16x32_bf16 v[108:111], v[132:135], v[156:159], v[108:111]
	v_mfma_f32_16x16x32_bf16 v[104:107], v[140:143], v[156:159], v[104:107]
	v_mfma_f32_16x16x32_bf16 v[92:95], v[132:135], v[186:189], v[92:95]
	v_mfma_f32_16x16x32_bf16 v[88:91], v[140:143], v[186:189], v[88:91]
	v_mfma_f32_16x16x32_bf16 v[76:79], v[132:135], v[194:197], v[76:79]
	v_mfma_f32_16x16x32_bf16 v[72:75], v[140:143], v[194:197], v[72:75]
	v_mfma_f32_16x16x32_bf16 v[116:119], v[198:201], v[144:147], v[116:119]
	v_mfma_f32_16x16x32_bf16 v[112:115], v[224:227], v[144:147], v[112:115]
	v_mfma_f32_16x16x32_bf16 v[100:103], v[198:201], v[152:155], v[100:103]
	v_mfma_f32_16x16x32_bf16 v[96:99], v[224:227], v[152:155], v[96:99]
	v_mfma_f32_16x16x32_bf16 v[84:87], v[198:201], v[182:185], v[84:87]
	v_mfma_f32_16x16x32_bf16 v[80:83], v[224:227], v[182:185], v[80:83]
	v_mfma_f32_16x16x32_bf16 v[68:71], v[198:201], v[190:193], v[68:71]
	v_mfma_f32_16x16x32_bf16 v[64:67], v[224:227], v[190:193], v[64:67]
	v_mfma_f32_16x16x32_bf16 v[116:119], v[220:223], v[148:151], v[116:119]
	v_mfma_f32_16x16x32_bf16 v[112:115], v[228:231], v[148:151], v[112:115]
	v_mfma_f32_16x16x32_bf16 v[100:103], v[220:223], v[156:159], v[100:103]
	v_mfma_f32_16x16x32_bf16 v[96:99], v[228:231], v[156:159], v[96:99]
	v_mfma_f32_16x16x32_bf16 v[84:87], v[220:223], v[186:189], v[84:87]
	v_mfma_f32_16x16x32_bf16 v[80:83], v[228:231], v[186:189], v[80:83]
	v_mfma_f32_16x16x32_bf16 v[68:71], v[220:223], v[194:197], v[68:71]
	v_mfma_f32_16x16x32_bf16 v[64:67], v[228:231], v[194:197], v[64:67]
	s_setprio 0
	s_barrier
; #define PG8_STAGE(bufoff, gbase, voff) do { _Pragma("unroll") for (int _i = 0; _i < 2; ++_i) \
;         __builtin_amdgcn_global_load_lds((const unsigned*)((const char*)(gbase) + (voff)[_i]), (LAS unsigned*)(lds + (bufoff) + ldsw + _i * 8192), 16, 0, 0); } while (0)
; #define PG8_LDA(dst, b, h) do { _Pragma("unroll") for (int m = 0; m < 4; ++m) _Pragma("unroll") for (int k = 0; k < 2; ++k) dst[m][k] = *(const LAS bf16x8*)(lds + PG8_SA(b, h) + aoff + m * 2048 + k * 1024); } while (0)
; #define PG8_MMA(ai, bj, At, Bt) do { __builtin_amdgcn_s_setprio(1); _Pragma("unroll") for (int m = 0; m < 4; ++m) _Pragma("unroll") for (int n = 0; n < 2; ++n) _Pragma("unroll") for (int k = 0; k < 2; ++k) \
;         acc[ai][bj][m][n] = __builtin_amdgcn_mfma_f32_16x16x32_bf16(Bt[n][k], At[m][k], acc[ai][bj][m][n], 0, 0, 0); __builtin_amdgcn_s_setprio(0); } while (0)
; #define PG8_WAIT_V(n) asm volatile("s_waitcnt vmcnt(" #n ")" ::: "memory")
; #define PG8_WAIT_L(n) asm volatile("s_waitcnt lgkmcnt(" #n ")" ::: "memory")
; #define PG8_BAR __builtin_amdgcn_s_barrier()
; #define PG8_SCHED __builtin_amdgcn_sched_barrier(0)
; template <class Epi>
; __device__ __forceinline__ void gemm_phase(LAS unsigned char* lds, const Gemm g, const StaticOrder& S, const Epi& E) {
;     ...
;             PG8_LDA(At, 1, 1); PG8_STAGE(PG8_SA(1, 0), a3, voffA);
;             PG8_BAR; PG8_WAIT_L(0); PG8_MMA(1, 0, At, B0); PG8_BAR; PG8_SCHED;
;             PG8_STAGE(PG8_SB(1, 1), b3 + hstepB, voffB);
;             PG8_WAIT_V(6); PG8_BAR; PG8_MMA(1, 1, At, B1); PG8_BAR;
	s_nop 1
	ds_read_b128 v[144:147], v215 offset:49152
	ds_read_b128 v[148:151], v215 offset:50176
	ds_read_b128 v[152:155], v215 offset:51200
	ds_read_b128 v[156:159], v215 offset:52224
	ds_read_b128 v[182:185], v215 offset:53248
	ds_read_b128 v[186:189], v215 offset:54272
	ds_read_b128 v[190:193], v215 offset:55296
	ds_read_b128 v[194:197], v215 offset:56320
	s_add_i32 s11, s11, s90
	v_lshl_add_u64 v[254:255], v[160:161], 0, s[28:29]
	s_mov_b32 m0, s11
	s_nop 0
	global_load_lds_dwordx4 v[254:255], off
	v_lshl_add_u64 v[254:255], v[202:203], 0, s[28:29]
	s_add_i32 m0, s11, 0x2000
	s_nop 0
	global_load_lds_dwordx4 v[254:255], off
	s_mov_b32 m0, s4
	v_lshl_add_u64 v[254:255], v[232:233], 0, s[28:29]
	global_load_lds_dwordx4 v[254:255], off
	v_lshl_add_u64 v[160:161], v[236:237], 0, s[28:29]
	s_mov_b32 m0, s5
	s_nop 0
	global_load_lds_dwordx4 v[160:161], off
	s_add_u32 s80, s84, 0x40080
	s_addc_u32 s81, s85, 0
	s_add_i32 s11, s86, s90
	v_lshl_add_u64 v[254:255], s[80:81], 0, v[164:165]
	s_mov_b32 m0, s11
	s_nop 0
	global_load_lds_dwordx4 v[254:255], off
	v_lshl_add_u64 v[254:255], s[80:81], 0, v[168:169]
	s_add_i32 m0, s11, 0x2000
	s_nop 0
	global_load_lds_dwordx4 v[254:255], off
	s_waitcnt vmcnt(6)
	s_waitcnt lgkmcnt(0)
	s_barrier
	s_setprio 1
	v_mfma_f32_16x16x32_bf16 v[60:63], v[128:131], v[144:147], v[60:63]
	v_mfma_f32_16x16x32_bf16 v[56:59], v[136:139], v[144:147], v[56:59]
	v_mfma_f32_16x16x32_bf16 v[44:47], v[128:131], v[152:155], v[44:47]
	v_mfma_f32_16x16x32_bf16 v[40:43], v[136:139], v[152:155], v[40:43]
	v_mfma_f32_16x16x32_bf16 v[28:31], v[128:131], v[182:185], v[28:31]
	v_mfma_f32_16x16x32_bf16 v[24:27], v[136:139], v[182:185], v[24:27]
	v_mfma_f32_16x16x32_bf16 v[12:15], v[128:131], v[190:193], v[12:15]
	v_mfma_f32_16x16x32_bf16 v[8:11], v[136:139], v[190:193], v[8:11]
	v_mfma_f32_16x16x32_bf16 v[60:63], v[132:135], v[148:151], v[60:63]
	v_mfma_f32_16x16x32_bf16 v[56:59], v[140:143], v[148:151], v[56:59]
	v_mfma_f32_16x16x32_bf16 v[44:47], v[132:135], v[156:159], v[44:47]
	v_mfma_f32_16x16x32_bf16 v[40:43], v[140:143], v[156:159], v[40:43]
	v_mfma_f32_16x16x32_bf16 v[28:31], v[132:135], v[186:189], v[28:31]
	v_mfma_f32_16x16x32_bf16 v[24:27], v[140:143], v[186:189], v[24:27]
	v_mfma_f32_16x16x32_bf16 v[12:15], v[132:135], v[194:197], v[12:15]
	v_mfma_f32_16x16x32_bf16 v[8:11], v[140:143], v[194:197], v[8:11]
	v_mfma_f32_16x16x32_bf16 v[52:55], v[198:201], v[144:147], v[52:55]
	v_mfma_f32_16x16x32_bf16 v[48:51], v[224:227], v[144:147], v[48:51]
	v_mfma_f32_16x16x32_bf16 v[36:39], v[198:201], v[152:155], v[36:39]
	v_mfma_f32_16x16x32_bf16 v[32:35], v[224:227], v[152:155], v[32:35]
	v_mfma_f32_16x16x32_bf16 v[20:23], v[198:201], v[182:185], v[20:23]
	v_mfma_f32_16x16x32_bf16 v[16:19], v[224:227], v[182:185], v[16:19]
	v_mfma_f32_16x16x32_bf16 v[4:7], v[198:201], v[190:193], v[4:7]
	v_mfma_f32_16x16x32_bf16 v[0:3], v[224:227], v[190:193], v[0:3]
	v_mfma_f32_16x16x32_bf16 v[52:55], v[220:223], v[148:151], v[52:55]
	v_mfma_f32_16x16x32_bf16 v[48:51], v[228:231], v[148:151], v[48:51]
	v_mfma_f32_16x16x32_bf16 v[36:39], v[220:223], v[156:159], v[36:39]
	v_mfma_f32_16x16x32_bf16 v[32:35], v[228:231], v[156:159], v[32:35]
	v_mfma_f32_16x16x32_bf16 v[20:23], v[220:223], v[186:189], v[20:23]
	v_mfma_f32_16x16x32_bf16 v[16:19], v[228:231], v[186:189], v[16:19]
	v_mfma_f32_16x16x32_bf16 v[4:7], v[220:223], v[194:197], v[4:7]
	v_mfma_f32_16x16x32_bf16 v[0:3], v[228:231], v[194:197], v[0:3]
	s_setprio 0
	s_add_i32 s10, s10, 2
	s_add_u32 vcc_lo, vcc_lo, 0x100
	s_addc_u32 vcc_hi, vcc_hi, 0
	s_cmp_gt_u32 s10, 13
	s_mov_b64 s[80:81], s[82:83]
	s_barrier
	.p2alignl 6, 3212836864

; #define PG8_STAGE(bufoff, gbase, voff) do { _Pragma("unroll") for (int _i = 0; _i < 2; ++_i) \
;         __builtin_amdgcn_global_load_lds((const unsigned*)((const char*)(gbase) + (voff)[_i]), (LAS unsigned*)(lds + (bufoff) + ldsw + _i * 8192), 16, 0, 0); } while (0)
; #define PG8_LDA(dst, b, h) do { _Pragma("unroll") for (int m = 0; m < 4; ++m) _Pragma("unroll") for (int k = 0; k < 2; ++k) dst[m][k] = *(const LAS bf16x8*)(lds + PG8_SA(b, h) + aoff + m * 2048 + k * 1024); } while (0)
; #define PG8_LDB(dst, b, h) do { _Pragma("unroll") for (int n = 0; n < 2; ++n) _Pragma("unroll") for (int k = 0; k < 2; ++k) dst[n][k] = *(const LAS bf16x8*)(lds + PG8_SB(b, h) + boff + n * 2048 + k * 1024); } while (0)
; #define PG8_MMA(ai, bj, At, Bt) do { __builtin_amdgcn_s_setprio(1); _Pragma("unroll") for (int m = 0; m < 4; ++m) _Pragma("unroll") for (int n = 0; n < 2; ++n) _Pragma("unroll") for (int k = 0; k < 2; ++k) \
;         acc[ai][bj][m][n] = __builtin_amdgcn_mfma_f32_16x16x32_bf16(Bt[n][k], At[m][k], acc[ai][bj][m][n], 0, 0, 0); __builtin_amdgcn_s_setprio(0); } while (0)
; #define PG8_WAIT_L(n) asm volatile("s_waitcnt lgkmcnt(" #n ")" ::: "memory")
; #define PG8_BAR __builtin_amdgcn_s_barrier()
; template <class Epi>
; __device__ __forceinline__ void gemm_phase(LAS unsigned char* lds, const Gemm g, const StaticOrder& S, const Epi& E) {
;     ...
;         const bool has_next = S.next(ui + 1, nxt);
;         const char* nA = has_next ? (const char*)g.A + (size_t)nxt.pm * tstepA + (size_t)(nxt.pn >> g.a_shift) * g.a_step : cA; const char* nB = has_next ? (const char*)g.Bt + (size_t)nxt.pn * tstepB : cB;
;         for (int t = 0; t < nt; t += 2) {
;             const bool last = (t == nt - 2);
;             const char* a1 = cA + (size_t)(t + 1) * kstep;
;             const char* a2 = last ? nA : cA + (size_t)(t + 2) * kstep; const char* b2 = last ? nB : cB + (size_t)(t + 2) * kstep;
;             const char* a3 = a2 + kstep; const char* b3 = b2 + kstep;
;             PG8_LDB(B0, 0, 0); PG8_SCHED; PG8_LDA(At, 0, 0); PG8_STAGE(PG8_SA(1, 1), a1 + hstepA, voffA);
;             PG8_WAIT_L(8); PG8_BAR; PG8_WAIT_L(0); PG8_MMA(0, 0, At, B0); PG8_BAR; PG8_SCHED;
;             PG8_LDB(B1, 0, 1); PG8_STAGE(PG8_SB(0, 0), b2, voffB);
;             PG8_BAR; PG8_WAIT_L(0); PG8_MMA(0, 1, At, B1); PG8_BAR;
;             PG8_LDA(At, 0, 1); PG8_STAGE(PG8_SA(0, 0), a2, voffA);
.LBB0_1238:
	s_ashr_i32 s29, s28, 31
	v_cmp_lt_i64_e32 vcc, s[30:31], v[136:137]
	s_lshl_b64 s[30:31], s[28:29], 19
	s_add_u32 s30, s60, s30
	s_addc_u32 s31, s61, s31
	s_and_b64 s[34:35], vcc, exec
	s_cselect_b32 s29, s31, s39
	s_cselect_b32 s72, s30, s38
	s_ashr_i32 s27, s26, 31
	s_lshl_b64 s[34:35], s[26:27], 19
	s_add_u32 s34, s5, s34
	s_addc_u32 s35, s6, s35
	s_and_b64 s[42:43], vcc, exec
	s_cselect_b32 s27, s35, s41
	s_cselect_b32 s73, s34, s40
	s_add_u32 s38, s38, 0x40080
	s_addc_u32 s39, s39, 0
	s_add_u32 s74, s40, 0x100
	s_addc_u32 s75, s41, 0
	s_mov_b32 s76, -2
	ds_read_b128 v[140:143], v149
	ds_read_b128 v[152:155], v149 offset:1024
	ds_read_b128 v[156:159], v149 offset:2048
	ds_read_b128 v[160:163], v149 offset:3072
	s_add_u32 s40, s38, 0xfffc0080
	s_addc_u32 s41, s39, -1
	s_cmp_eq_u32 s76, 12
	s_cselect_b32 s43, s29, s41
	s_cselect_b32 s42, s72, s40
	s_cselect_b32 s41, s27, s75
	s_cselect_b32 s40, s73, s74
	v_lshl_add_u64 v[144:145], s[38:39], 0, v[132:133]
	s_add_i32 m0, s8, 0xc000
	ds_read_b128 v[164:167], v150
	ds_read_b128 v[168:171], v150 offset:1024
	ds_read_b128 v[172:175], v150 offset:2048
	ds_read_b128 v[176:179], v150 offset:3072
	ds_read_b128 v[180:183], v150 offset:4096
	ds_read_b128 v[184:187], v150 offset:5120
	ds_read_b128 v[188:191], v150 offset:6144
	ds_read_b128 v[192:195], v150 offset:7168
	global_load_lds_dwordx4 v[144:145], off
	v_lshl_add_u64 v[144:145], s[38:39], 0, v[134:135]
	s_add_i32 m0, s8, 0xe000
	s_nop 0
	global_load_lds_dwordx4 v[144:145], off
	ds_read_b128 v[196:199], v151
	ds_read_b128 v[200:203], v151 offset:1024
	ds_read_b128 v[204:207], v151 offset:2048
	ds_read_b128 v[208:211], v151 offset:3072
	s_waitcnt lgkmcnt(0)
	s_barrier
	s_setprio 1
	v_mfma_f32_16x16x32_bf16 v[124:127], v[140:143], v[164:167], 0
	v_mfma_f32_16x16x32_bf16 v[120:123], v[156:159], v[164:167], 0
	v_mfma_f32_16x16x32_bf16 v[112:115], v[140:143], v[172:175], 0
	v_mfma_f32_16x16x32_bf16 v[104:107], v[156:159], v[172:175], 0
	v_mfma_f32_16x16x32_bf16 v[92:95], v[140:143], v[180:183], 0
	v_mfma_f32_16x16x32_bf16 v[88:91], v[156:159], v[180:183], 0
	v_mfma_f32_16x16x32_bf16 v[80:83], v[140:143], v[188:191], 0
	v_mfma_f32_16x16x32_bf16 v[72:75], v[156:159], v[188:191], 0
	v_mfma_f32_16x16x32_bf16 v[124:127], v[152:155], v[168:171], v[124:127]
	v_mfma_f32_16x16x32_bf16 v[120:123], v[160:163], v[168:171], v[120:123]
	v_mfma_f32_16x16x32_bf16 v[112:115], v[152:155], v[176:179], v[112:115]
	v_mfma_f32_16x16x32_bf16 v[104:107], v[160:163], v[176:179], v[104:107]
	v_mfma_f32_16x16x32_bf16 v[92:95], v[152:155], v[184:187], v[92:95]
	v_mfma_f32_16x16x32_bf16 v[88:91], v[160:163], v[184:187], v[88:91]
	v_mfma_f32_16x16x32_bf16 v[80:83], v[152:155], v[192:195], v[80:83]
	v_mfma_f32_16x16x32_bf16 v[72:75], v[160:163], v[192:195], v[72:75]
	v_mfma_f32_16x16x32_bf16 v[116:119], v[196:199], v[164:167], 0
	v_mfma_f32_16x16x32_bf16 v[108:111], v[204:207], v[164:167], 0
	v_mfma_f32_16x16x32_bf16 v[100:103], v[196:199], v[172:175], 0
	v_mfma_f32_16x16x32_bf16 v[96:99], v[204:207], v[172:175], 0
	v_mfma_f32_16x16x32_bf16 v[84:87], v[196:199], v[180:183], 0
	v_mfma_f32_16x16x32_bf16 v[76:79], v[204:207], v[180:183], 0
	v_mfma_f32_16x16x32_bf16 v[68:71], v[196:199], v[188:191], 0
	v_mfma_f32_16x16x32_bf16 v[64:67], v[204:207], v[188:191], 0
	v_mfma_f32_16x16x32_bf16 v[116:119], v[200:203], v[168:171], v[116:119]
	v_mfma_f32_16x16x32_bf16 v[108:111], v[208:211], v[168:171], v[108:111]
	v_mfma_f32_16x16x32_bf16 v[100:103], v[200:203], v[176:179], v[100:103]
	v_mfma_f32_16x16x32_bf16 v[96:99], v[208:211], v[176:179], v[96:99]
	v_mfma_f32_16x16x32_bf16 v[84:87], v[200:203], v[184:187], v[84:87]
	v_mfma_f32_16x16x32_bf16 v[76:79], v[208:211], v[184:187], v[76:79]
	v_mfma_f32_16x16x32_bf16 v[68:71], v[200:203], v[192:195], v[68:71]
	v_mfma_f32_16x16x32_bf16 v[64:67], v[208:211], v[192:195], v[64:67]
	s_setprio 0
	s_barrier
	s_nop 1
	ds_read_b128 v[164:167], v150 offset:16384
	ds_read_b128 v[168:171], v150 offset:17408
	ds_read_b128 v[172:175], v150 offset:18432
	ds_read_b128 v[176:179], v150 offset:19456
	ds_read_b128 v[180:183], v150 offset:20480
	ds_read_b128 v[184:187], v150 offset:21504
	ds_read_b128 v[188:191], v150 offset:22528
	ds_read_b128 v[192:195], v150 offset:23552
	s_add_i32 s77, s48, s7
	v_lshl_add_u64 v[144:145], s[40:41], 0, v[128:129]
	s_mov_b32 m0, s77
	s_nop 0
	global_load_lds_dwordx4 v[144:145], off
	v_lshl_add_u64 v[212:213], s[40:41], 0, v[130:131]
	s_add_i32 m0, s77, 0x2000
	s_nop 0
	global_load_lds_dwordx4 v[212:213], off
	s_mov_b32 m0, s8
	v_lshl_add_u64 v[214:215], s[42:43], 0, v[128:129]
	global_load_lds_dwordx4 v[214:215], off
	v_lshl_add_u64 v[216:217], s[42:43], 0, v[130:131]
	s_mov_b32 m0, s9
	s_nop 0
	global_load_lds_dwordx4 v[216:217], off
	s_add_u32 s78, s40, 0x40000
	s_addc_u32 s79, s41, 0
	s_add_i32 s77, s49, s7
	v_lshl_add_u64 v[254:255], s[78:79], 0, v[128:129]
	s_mov_b32 m0, s77
	s_nop 0
	global_load_lds_dwordx4 v[254:255], off
	v_lshl_add_u64 v[254:255], s[78:79], 0, v[130:131]
	s_add_i32 m0, s77, 0x2000
	s_nop 0
	global_load_lds_dwordx4 v[254:255], off
	s_waitcnt vmcnt(6)
	s_waitcnt lgkmcnt(0)
	s_barrier
; #define PG8_STAGE(bufoff, gbase, voff) do { _Pragma("unroll") for (int _i = 0; _i < 2; ++_i) \
;         __builtin_amdgcn_global_load_lds((const unsigned*)((const char*)(gbase) + (voff)[_i]), (LAS unsigned*)(lds + (bufoff) + ldsw + _i * 8192), 16, 0, 0); } while (0)
; #define PG8_LDA(dst, b, h) do { _Pragma("unroll") for (int m = 0; m < 4; ++m) _Pragma("unroll") for (int k = 0; k < 2; ++k) dst[m][k] = *(const LAS bf16x8*)(lds + PG8_SA(b, h) + aoff + m * 2048 + k * 1024); } while (0)
; #define PG8_LDB(dst, b, h) do { _Pragma("unroll") for (int n = 0; n < 2; ++n) _Pragma("unroll") for (int k = 0; k < 2; ++k) dst[n][k] = *(const LAS bf16x8*)(lds + PG8_SB(b, h) + boff + n * 2048 + k * 1024); } while (0)
; #define PG8_MMA(ai, bj, At, Bt) do { __builtin_amdgcn_s_setprio(1); _Pragma("unroll") for (int m = 0; m < 4; ++m) _Pragma("unroll") for (int n = 0; n < 2; ++n) _Pragma("unroll") for (int k = 0; k < 2; ++k) \
;         acc[ai][bj][m][n] = __builtin_amdgcn_mfma_f32_16x16x32_bf16(Bt[n][k], At[m][k], acc[ai][bj][m][n], 0, 0, 0); __builtin_amdgcn_s_setprio(0); } while (0)
; #define PG8_WAIT_V(n) asm volatile("s_waitcnt vmcnt(" #n ")" ::: "memory")
; #define PG8_WAIT_L(n) asm volatile("s_waitcnt lgkmcnt(" #n ")" ::: "memory")
; #define PG8_BAR __builtin_amdgcn_s_barrier()
; #define PG8_SCHED __builtin_amdgcn_sched_barrier(0)
; template <class Epi>
; __device__ __forceinline__ void gemm_phase(LAS unsigned char* lds, const Gemm g, const StaticOrder& S, const Epi& E) {
;     ...
;             PG8_BAR; PG8_WAIT_L(0); PG8_MMA(1, 0, At, B0); PG8_BAR; PG8_SCHED;
;             PG8_STAGE(PG8_SB(0, 1), b2 + hstepB, voffB);
;             PG8_WAIT_V(6); PG8_BAR; PG8_MMA(1, 1, At, B1); PG8_BAR;
;             PG8_LDB(B0, 1, 0); PG8_SCHED; PG8_LDA(At, 1, 0); PG8_STAGE(PG8_SA(0, 1), a2 + hstepA, voffA);
;             PG8_WAIT_L(8); PG8_BAR; PG8_WAIT_L(0); PG8_MMA(0, 0, At, B0); PG8_BAR; PG8_SCHED;
;             PG8_LDB(B1, 1, 1); PG8_STAGE(PG8_SB(1, 0), b3, voffB);
;             PG8_BAR; PG8_WAIT_L(0); PG8_MMA(0, 1, At, B1); PG8_BAR;
	s_setprio 1
	v_mfma_f32_16x16x32_bf16 v[60:63], v[140:143], v[164:167], 0
	v_mfma_f32_16x16x32_bf16 v[56:59], v[156:159], v[164:167], 0
	v_mfma_f32_16x16x32_bf16 v[48:51], v[140:143], v[172:175], 0
	v_mfma_f32_16x16x32_bf16 v[40:43], v[156:159], v[172:175], 0
	v_mfma_f32_16x16x32_bf16 v[28:31], v[140:143], v[180:183], 0
	v_mfma_f32_16x16x32_bf16 v[24:27], v[156:159], v[180:183], 0
	v_mfma_f32_16x16x32_bf16 v[16:19], v[140:143], v[188:191], 0
	v_mfma_f32_16x16x32_bf16 v[8:11], v[156:159], v[188:191], 0
	v_mfma_f32_16x16x32_bf16 v[60:63], v[152:155], v[168:171], v[60:63]
	v_mfma_f32_16x16x32_bf16 v[56:59], v[160:163], v[168:171], v[56:59]
	v_mfma_f32_16x16x32_bf16 v[48:51], v[152:155], v[176:179], v[48:51]
	v_mfma_f32_16x16x32_bf16 v[40:43], v[160:163], v[176:179], v[40:43]
	v_mfma_f32_16x16x32_bf16 v[28:31], v[152:155], v[184:187], v[28:31]
	v_mfma_f32_16x16x32_bf16 v[24:27], v[160:163], v[184:187], v[24:27]
	v_mfma_f32_16x16x32_bf16 v[16:19], v[152:155], v[192:195], v[16:19]
	v_mfma_f32_16x16x32_bf16 v[8:11], v[160:163], v[192:195], v[8:11]
	v_mfma_f32_16x16x32_bf16 v[52:55], v[196:199], v[164:167], 0
	v_mfma_f32_16x16x32_bf16 v[44:47], v[204:207], v[164:167], 0
	v_mfma_f32_16x16x32_bf16 v[36:39], v[196:199], v[172:175], 0
	v_mfma_f32_16x16x32_bf16 v[32:35], v[204:207], v[172:175], 0
	v_mfma_f32_16x16x32_bf16 v[20:23], v[196:199], v[180:183], 0
	v_mfma_f32_16x16x32_bf16 v[12:15], v[204:207], v[180:183], 0
	v_mfma_f32_16x16x32_bf16 v[4:7], v[196:199], v[188:191], 0
	v_mfma_f32_16x16x32_bf16 v[0:3], v[204:207], v[188:191], 0
	v_mfma_f32_16x16x32_bf16 v[52:55], v[200:203], v[168:171], v[52:55]
	v_mfma_f32_16x16x32_bf16 v[44:47], v[208:211], v[168:171], v[44:47]
	v_mfma_f32_16x16x32_bf16 v[36:39], v[200:203], v[176:179], v[36:39]
	v_mfma_f32_16x16x32_bf16 v[32:35], v[208:211], v[176:179], v[32:35]
	v_mfma_f32_16x16x32_bf16 v[20:23], v[200:203], v[184:187], v[20:23]
	v_mfma_f32_16x16x32_bf16 v[12:15], v[208:211], v[184:187], v[12:15]
	v_mfma_f32_16x16x32_bf16 v[4:7], v[200:203], v[192:195], v[4:7]
	v_mfma_f32_16x16x32_bf16 v[0:3], v[208:211], v[192:195], v[0:3]
	s_setprio 0
	s_add_i32 s77, 0, 0x18000
	v_add_u32_e32 v160, s77, v147
	s_barrier
	ds_read_b128 v[140:143], v160
	ds_read_b128 v[152:155], v160 offset:1024
	ds_read_b128 v[156:159], v160 offset:2048
	ds_read_b128 v[160:163], v160 offset:3072
	s_add_u32 s42, s42, 0x40000
	s_addc_u32 s43, s43, 0
	s_mov_b32 m0, s37
	v_lshl_add_u64 v[196:197], s[42:43], 0, v[128:129]
	ds_read_b128 v[164:167], v150 offset:32768
	ds_read_b128 v[168:171], v150 offset:33792
	ds_read_b128 v[172:175], v150 offset:34816
	ds_read_b128 v[176:179], v150 offset:35840
	ds_read_b128 v[180:183], v150 offset:36864
	ds_read_b128 v[184:187], v150 offset:37888
	ds_read_b128 v[188:191], v150 offset:38912
	ds_read_b128 v[192:195], v150 offset:39936
	global_load_lds_dwordx4 v[196:197], off
	v_lshl_add_u64 v[196:197], s[42:43], 0, v[130:131]
	s_mov_b32 m0, s44
	s_nop 0
	global_load_lds_dwordx4 v[196:197], off
	s_add_i32 s42, 0, 0x1c000
	v_add_u32_e32 v208, s42, v147
	ds_read_b128 v[196:199], v208
	ds_read_b128 v[200:203], v208 offset:1024
	ds_read_b128 v[204:207], v208 offset:2048
	ds_read_b128 v[208:211], v208 offset:3072
	s_waitcnt lgkmcnt(0)
	s_barrier
	s_setprio 1
	v_mfma_f32_16x16x32_bf16 v[124:127], v[140:143], v[164:167], v[124:127]
	v_mfma_f32_16x16x32_bf16 v[120:123], v[156:159], v[164:167], v[120:123]
	v_mfma_f32_16x16x32_bf16 v[112:115], v[140:143], v[172:175], v[112:115]
	v_mfma_f32_16x16x32_bf16 v[104:107], v[156:159], v[172:175], v[104:107]
	v_mfma_f32_16x16x32_bf16 v[92:95], v[140:143], v[180:183], v[92:95]
	v_mfma_f32_16x16x32_bf16 v[88:91], v[156:159], v[180:183], v[88:91]
	v_mfma_f32_16x16x32_bf16 v[80:83], v[140:143], v[188:191], v[80:83]
	v_mfma_f32_16x16x32_bf16 v[72:75], v[156:159], v[188:191], v[72:75]
	v_mfma_f32_16x16x32_bf16 v[124:127], v[152:155], v[168:171], v[124:127]
	v_mfma_f32_16x16x32_bf16 v[120:123], v[160:163], v[168:171], v[120:123]
	v_mfma_f32_16x16x32_bf16 v[112:115], v[152:155], v[176:179], v[112:115]
	v_mfma_f32_16x16x32_bf16 v[104:107], v[160:163], v[176:179], v[104:107]
	v_mfma_f32_16x16x32_bf16 v[92:95], v[152:155], v[184:187], v[92:95]
	v_mfma_f32_16x16x32_bf16 v[88:91], v[160:163], v[184:187], v[88:91]
	v_mfma_f32_16x16x32_bf16 v[80:83], v[152:155], v[192:195], v[80:83]
	v_mfma_f32_16x16x32_bf16 v[72:75], v[160:163], v[192:195], v[72:75]
	v_mfma_f32_16x16x32_bf16 v[116:119], v[196:199], v[164:167], v[116:119]
	v_mfma_f32_16x16x32_bf16 v[108:111], v[204:207], v[164:167], v[108:111]
	v_mfma_f32_16x16x32_bf16 v[100:103], v[196:199], v[172:175], v[100:103]
	v_mfma_f32_16x16x32_bf16 v[96:99], v[204:207], v[172:175], v[96:99]
	v_mfma_f32_16x16x32_bf16 v[84:87], v[196:199], v[180:183], v[84:87]
	v_mfma_f32_16x16x32_bf16 v[76:79], v[204:207], v[180:183], v[76:79]
	v_mfma_f32_16x16x32_bf16 v[68:71], v[196:199], v[188:191], v[68:71]
	v_mfma_f32_16x16x32_bf16 v[64:67], v[204:207], v[188:191], v[64:67]
	v_mfma_f32_16x16x32_bf16 v[116:119], v[200:203], v[168:171], v[116:119]
	v_mfma_f32_16x16x32_bf16 v[108:111], v[208:211], v[168:171], v[108:111]
	v_mfma_f32_16x16x32_bf16 v[100:103], v[200:203], v[176:179], v[100:103]
	v_mfma_f32_16x16x32_bf16 v[96:99], v[208:211], v[176:179], v[96:99]
	v_mfma_f32_16x16x32_bf16 v[84:87], v[200:203], v[184:187], v[84:87]
	v_mfma_f32_16x16x32_bf16 v[76:79], v[208:211], v[184:187], v[76:79]
	v_mfma_f32_16x16x32_bf16 v[68:71], v[200:203], v[192:195], v[68:71]
	v_mfma_f32_16x16x32_bf16 v[64:67], v[208:211], v[192:195], v[64:67]
	s_setprio 0
	s_barrier
; #define PG8_STAGE(bufoff, gbase, voff) do { _Pragma("unroll") for (int _i = 0; _i < 2; ++_i) \
;         __builtin_amdgcn_global_load_lds((const unsigned*)((const char*)(gbase) + (voff)[_i]), (LAS unsigned*)(lds + (bufoff) + ldsw + _i * 8192), 16, 0, 0); } while (0)
; #define PG8_LDA(dst, b, h) do { _Pragma("unroll") for (int m = 0; m < 4; ++m) _Pragma("unroll") for (int k = 0; k < 2; ++k) dst[m][k] = *(const LAS bf16x8*)(lds + PG8_SA(b, h) + aoff + m * 2048 + k * 1024); } while (0)
; #define PG8_MMA(ai, bj, At, Bt) do { __builtin_amdgcn_s_setprio(1); _Pragma("unroll") for (int m = 0; m < 4; ++m) _Pragma("unroll") for (int n = 0; n < 2; ++n) _Pragma("unroll") for (int k = 0; k < 2; ++k) \
;         acc[ai][bj][m][n] = __builtin_amdgcn_mfma_f32_16x16x32_bf16(Bt[n][k], At[m][k], acc[ai][bj][m][n], 0, 0, 0); __builtin_amdgcn_s_setprio(0); } while (0)
; #define PG8_WAIT_V(n) asm volatile("s_waitcnt vmcnt(" #n ")" ::: "memory")
; #define PG8_WAIT_L(n) asm volatile("s_waitcnt lgkmcnt(" #n ")" ::: "memory")
; #define PG8_BAR __builtin_amdgcn_s_barrier()
; #define PG8_SCHED __builtin_amdgcn_sched_barrier(0)
; template <class Epi>
; __device__ __forceinline__ void gemm_phase(LAS unsigned char* lds, const Gemm g, const StaticOrder& S, const Epi& E) {
;     ...
;             PG8_LDA(At, 1, 1); PG8_STAGE(PG8_SA(1, 0), a3, voffA);
;             PG8_BAR; PG8_WAIT_L(0); PG8_MMA(1, 0, At, B0); PG8_BAR; PG8_SCHED;
;             PG8_STAGE(PG8_SB(1, 1), b3 + hstepB, voffB);
;             PG8_WAIT_V(6); PG8_BAR; PG8_MMA(1, 1, At, B1); PG8_BAR;
	s_nop 1
	ds_read_b128 v[164:167], v150 offset:49152
	ds_read_b128 v[168:171], v150 offset:50176
	ds_read_b128 v[172:175], v150 offset:51200
	ds_read_b128 v[176:179], v150 offset:52224
	ds_read_b128 v[180:183], v150 offset:53248
	ds_read_b128 v[184:187], v150 offset:54272
	ds_read_b128 v[188:191], v150 offset:55296
	ds_read_b128 v[192:195], v150 offset:56320
	s_add_i32 s43, s77, s7
	v_lshl_add_u64 v[254:255], v[144:145], 0, s[12:13]
	s_mov_b32 m0, s43
	s_nop 0
	global_load_lds_dwordx4 v[254:255], off
	v_lshl_add_u64 v[254:255], v[212:213], 0, s[12:13]
	s_add_i32 m0, s43, 0x2000
	s_nop 0
	global_load_lds_dwordx4 v[254:255], off
	s_mov_b32 m0, s46
	v_lshl_add_u64 v[254:255], v[214:215], 0, s[12:13]
	global_load_lds_dwordx4 v[254:255], off
	v_lshl_add_u64 v[144:145], v[216:217], 0, s[12:13]
	s_mov_b32 m0, s47
	s_nop 0
	global_load_lds_dwordx4 v[144:145], off
	s_add_u32 s40, s40, 0x40080
	s_addc_u32 s41, s41, 0
	s_add_i32 s42, s42, s7
	v_lshl_add_u64 v[254:255], s[40:41], 0, v[128:129]
	s_mov_b32 m0, s42
	s_nop 0
	global_load_lds_dwordx4 v[254:255], off
	v_lshl_add_u64 v[254:255], s[40:41], 0, v[130:131]
	s_add_i32 m0, s42, 0x2000
	s_nop 0
	global_load_lds_dwordx4 v[254:255], off
	s_waitcnt vmcnt(6)
	s_waitcnt lgkmcnt(0)
	s_barrier
	s_setprio 1
	v_mfma_f32_16x16x32_bf16 v[60:63], v[140:143], v[164:167], v[60:63]
	v_mfma_f32_16x16x32_bf16 v[56:59], v[156:159], v[164:167], v[56:59]
	v_mfma_f32_16x16x32_bf16 v[48:51], v[140:143], v[172:175], v[48:51]
	v_mfma_f32_16x16x32_bf16 v[40:43], v[156:159], v[172:175], v[40:43]
	v_mfma_f32_16x16x32_bf16 v[28:31], v[140:143], v[180:183], v[28:31]
	v_mfma_f32_16x16x32_bf16 v[24:27], v[156:159], v[180:183], v[24:27]
	v_mfma_f32_16x16x32_bf16 v[16:19], v[140:143], v[188:191], v[16:19]
	v_mfma_f32_16x16x32_bf16 v[8:11], v[156:159], v[188:191], v[8:11]
	v_mfma_f32_16x16x32_bf16 v[60:63], v[152:155], v[168:171], v[60:63]
	v_mfma_f32_16x16x32_bf16 v[56:59], v[160:163], v[168:171], v[56:59]
	v_mfma_f32_16x16x32_bf16 v[48:51], v[152:155], v[176:179], v[48:51]
	v_mfma_f32_16x16x32_bf16 v[40:43], v[160:163], v[176:179], v[40:43]
	v_mfma_f32_16x16x32_bf16 v[28:31], v[152:155], v[184:187], v[28:31]
	v_mfma_f32_16x16x32_bf16 v[24:27], v[160:163], v[184:187], v[24:27]
	v_mfma_f32_16x16x32_bf16 v[16:19], v[152:155], v[192:195], v[16:19]
	v_mfma_f32_16x16x32_bf16 v[8:11], v[160:163], v[192:195], v[8:11]
	v_mfma_f32_16x16x32_bf16 v[52:55], v[196:199], v[164:167], v[52:55]
	v_mfma_f32_16x16x32_bf16 v[44:47], v[204:207], v[164:167], v[44:47]
	v_mfma_f32_16x16x32_bf16 v[36:39], v[196:199], v[172:175], v[36:39]
	v_mfma_f32_16x16x32_bf16 v[32:35], v[204:207], v[172:175], v[32:35]
	v_mfma_f32_16x16x32_bf16 v[20:23], v[196:199], v[180:183], v[20:23]
	v_mfma_f32_16x16x32_bf16 v[12:15], v[204:207], v[180:183], v[12:15]
	v_mfma_f32_16x16x32_bf16 v[4:7], v[196:199], v[188:191], v[4:7]
	v_mfma_f32_16x16x32_bf16 v[0:3], v[204:207], v[188:191], v[0:3]
	v_mfma_f32_16x16x32_bf16 v[52:55], v[200:203], v[168:171], v[52:55]
	v_mfma_f32_16x16x32_bf16 v[44:47], v[208:211], v[168:171], v[44:47]
	v_mfma_f32_16x16x32_bf16 v[36:39], v[200:203], v[176:179], v[36:39]
	v_mfma_f32_16x16x32_bf16 v[32:35], v[208:211], v[176:179], v[32:35]
	v_mfma_f32_16x16x32_bf16 v[20:23], v[200:203], v[184:187], v[20:23]
	v_mfma_f32_16x16x32_bf16 v[12:15], v[208:211], v[184:187], v[12:15]
	v_mfma_f32_16x16x32_bf16 v[4:7], v[200:203], v[192:195], v[4:7]
	v_mfma_f32_16x16x32_bf16 v[0:3], v[208:211], v[192:195], v[0:3]
	s_setprio 0
	s_add_i32 s76, s76, 2
	s_add_u32 s38, s38, 0x100
	s_addc_u32 s39, s39, 0
	s_add_u32 s74, s74, 0x100
	s_addc_u32 s75, s75, 0
	s_cmp_gt_u32 s76, 13
	s_barrier
	.p2alignl 6, 3212836864

; #define PG8_STAGE(bufoff, gbase, voff) do { _Pragma("unroll") for (int _i = 0; _i < 2; ++_i) \
;         __builtin_amdgcn_global_load_lds((const unsigned*)((const char*)(gbase) + (voff)[_i]), (LAS unsigned*)(lds + (bufoff) + ldsw + _i * 8192), 16, 0, 0); } while (0)
; #define PG8_LDA(dst, b, h) do { _Pragma("unroll") for (int m = 0; m < 4; ++m) _Pragma("unroll") for (int k = 0; k < 2; ++k) dst[m][k] = *(const LAS bf16x8*)(lds + PG8_SA(b, h) + aoff + m * 2048 + k * 1024); } while (0)
; #define PG8_LDB(dst, b, h) do { _Pragma("unroll") for (int n = 0; n < 2; ++n) _Pragma("unroll") for (int k = 0; k < 2; ++k) dst[n][k] = *(const LAS bf16x8*)(lds + PG8_SB(b, h) + boff + n * 2048 + k * 1024); } while (0)
; #define PG8_MMA(ai, bj, At, Bt) do { __builtin_amdgcn_s_setprio(1); _Pragma("unroll") for (int m = 0; m < 4; ++m) _Pragma("unroll") for (int n = 0; n < 2; ++n) _Pragma("unroll") for (int k = 0; k < 2; ++k) \
;         acc[ai][bj][m][n] = __builtin_amdgcn_mfma_f32_16x16x32_bf16(Bt[n][k], At[m][k], acc[ai][bj][m][n], 0, 0, 0); __builtin_amdgcn_s_setprio(0); } while (0)
; #define PG8_WAIT_L(n) asm volatile("s_waitcnt lgkmcnt(" #n ")" ::: "memory")
; #define PG8_BAR __builtin_amdgcn_s_barrier()
; template <class Epi>
; __device__ __forceinline__ void gemm_phase(LAS unsigned char* lds, const Gemm g, const StaticOrder& S, const Epi& E) {
;     ...
;         const bool has_next = S.next(ui + 1, nxt);
;         const char* nA = has_next ? (const char*)g.A + (size_t)nxt.pm * tstepA + (size_t)(nxt.pn >> g.a_shift) * g.a_step : cA; const char* nB = has_next ? (const char*)g.Bt + (size_t)nxt.pn * tstepB : cB;
;         for (int t = 0; t < nt; t += 2) {
;             const bool last = (t == nt - 2);
;             const char* a1 = cA + (size_t)(t + 1) * kstep;
;             const char* a2 = last ? nA : cA + (size_t)(t + 2) * kstep; const char* b2 = last ? nB : cB + (size_t)(t + 2) * kstep;
;             const char* a3 = a2 + kstep; const char* b3 = b2 + kstep;
;             PG8_LDB(B0, 0, 0); PG8_SCHED; PG8_LDA(At, 0, 0); PG8_STAGE(PG8_SA(1, 1), a1 + hstepA, voffA);
;             PG8_WAIT_L(8); PG8_BAR; PG8_WAIT_L(0); PG8_MMA(0, 0, At, B0); PG8_BAR; PG8_SCHED;
;             PG8_LDB(B1, 0, 1); PG8_STAGE(PG8_SB(0, 0), b2, voffB);
;             PG8_BAR; PG8_WAIT_L(0); PG8_MMA(0, 1, At, B1); PG8_BAR;
;             PG8_LDA(At, 0, 1); PG8_STAGE(PG8_SA(0, 0), a2, voffA);
.LBB0_1358:
	s_ashr_i32 s37, s36, 31
	v_cmp_lt_i64_e32 vcc, s[38:39], v[228:229]
	s_lshl_b64 s[38:39], s[36:37], 19
	s_add_u32 s38, s66, s38
	s_addc_u32 s39, s67, s39
	s_and_b64 s[40:41], vcc, exec
	s_cselect_b32 s37, s39, s45
	s_cselect_b32 s83, s38, s44
	s_ashr_i32 s35, s34, 31
	s_lshl_b64 s[40:41], s[34:35], 19
	s_add_u32 s40, s5, s40
	s_addc_u32 s41, s6, s41
	s_and_b64 s[48:49], vcc, exec
	s_cselect_b32 s35, s41, s47
	s_cselect_b32 s84, s40, s46
	s_add_u32 s85, s46, 0x100
	s_addc_u32 s86, s47, 0
	s_mov_b32 s87, -2
	ds_read_b128 v[96:99], v243
	ds_read_b128 v[100:103], v243 offset:1024
	ds_read_b128 v[104:107], v243 offset:2048
	ds_read_b128 v[108:111], v243 offset:3072
	s_add_u32 s46, s44, 0x100
	s_addc_u32 s47, s45, 0
	s_cmp_eq_u32 s87, 12
	s_cselect_b32 s73, s37, s47
	s_cselect_b32 s72, s83, s46
	s_cselect_b32 s49, s35, s86
	s_cselect_b32 s48, s84, s85
	v_lshl_add_u64 v[176:177], s[44:45], 0, v[224:225]
	s_add_i32 m0, s9, 0xc000
	ds_read_b128 v[112:115], v244
	ds_read_b128 v[116:119], v244 offset:1024
	ds_read_b128 v[120:123], v244 offset:2048
	ds_read_b128 v[124:127], v244 offset:3072
	ds_read_b128 v[160:163], v244 offset:4096
	ds_read_b128 v[164:167], v244 offset:5120
	ds_read_b128 v[168:171], v244 offset:6144
	ds_read_b128 v[172:175], v244 offset:7168
	global_load_lds_dwordx4 v[176:177], off
	v_lshl_add_u64 v[176:177], s[44:45], 0, v[226:227]
	s_add_i32 m0, s9, 0xe000
	s_nop 0
	global_load_lds_dwordx4 v[176:177], off
	ds_read_b128 v[176:179], v245
	ds_read_b128 v[180:183], v245 offset:1024
	ds_read_b128 v[184:187], v245 offset:2048
	ds_read_b128 v[188:191], v245 offset:3072
	s_waitcnt lgkmcnt(0)
	s_barrier
	s_setprio 1
	v_mfma_f32_16x16x32_bf16 v[156:159], v[96:99], v[112:115], 0
	v_mfma_f32_16x16x32_bf16 v[60:63], v[104:107], v[112:115], 0
	v_mfma_f32_16x16x32_bf16 v[144:147], v[96:99], v[120:123], 0
	v_mfma_f32_16x16x32_bf16 v[48:51], v[104:107], v[120:123], 0
	v_mfma_f32_16x16x32_bf16 v[136:139], v[96:99], v[160:163], 0
	v_mfma_f32_16x16x32_bf16 v[40:43], v[104:107], v[160:163], 0
	v_mfma_f32_16x16x32_bf16 v[148:151], v[96:99], v[168:171], 0
	v_mfma_f32_16x16x32_bf16 v[52:55], v[104:107], v[168:171], 0
	v_mfma_f32_16x16x32_bf16 v[156:159], v[100:103], v[116:119], v[156:159]
	v_mfma_f32_16x16x32_bf16 v[60:63], v[108:111], v[116:119], v[60:63]
	v_mfma_f32_16x16x32_bf16 v[144:147], v[100:103], v[124:127], v[144:147]
	v_mfma_f32_16x16x32_bf16 v[48:51], v[108:111], v[124:127], v[48:51]
	v_mfma_f32_16x16x32_bf16 v[136:139], v[100:103], v[164:167], v[136:139]
	v_mfma_f32_16x16x32_bf16 v[40:43], v[108:111], v[164:167], v[40:43]
	v_mfma_f32_16x16x32_bf16 v[148:151], v[100:103], v[172:175], v[148:151]
	v_mfma_f32_16x16x32_bf16 v[52:55], v[108:111], v[172:175], v[52:55]
	v_mfma_f32_16x16x32_bf16 v[152:155], v[176:179], v[112:115], 0
	v_mfma_f32_16x16x32_bf16 v[56:59], v[184:187], v[112:115], 0
	v_mfma_f32_16x16x32_bf16 v[36:39], v[184:187], v[120:123], 0
	v_mfma_f32_16x16x32_bf16 v[32:35], v[184:187], v[160:163], 0
	v_mfma_f32_16x16x32_bf16 v[44:47], v[184:187], v[168:171], 0
	v_mfma_f32_16x16x32_bf16 v[152:155], v[180:183], v[116:119], v[152:155]
	v_mfma_f32_16x16x32_bf16 v[56:59], v[188:191], v[116:119], v[56:59]
	v_mfma_f32_16x16x32_bf16 v[112:115], v[176:179], v[120:123], 0
	v_mfma_f32_16x16x32_bf16 v[36:39], v[188:191], v[124:127], v[36:39]
	v_mfma_f32_16x16x32_bf16 v[116:119], v[176:179], v[160:163], 0
	v_mfma_f32_16x16x32_bf16 v[32:35], v[188:191], v[164:167], v[32:35]
	v_mfma_f32_16x16x32_bf16 v[120:123], v[176:179], v[168:171], 0
	v_mfma_f32_16x16x32_bf16 v[44:47], v[188:191], v[172:175], v[44:47]
	v_mfma_f32_16x16x32_bf16 v[112:115], v[180:183], v[124:127], v[112:115]
	v_mfma_f32_16x16x32_bf16 v[116:119], v[180:183], v[164:167], v[116:119]
	v_mfma_f32_16x16x32_bf16 v[120:123], v[180:183], v[172:175], v[120:123]
	s_setprio 0
	s_barrier
	s_nop 1
	ds_read_b128 v[124:127], v244 offset:16384
	ds_read_b128 v[128:131], v244 offset:17408
	ds_read_b128 v[132:135], v244 offset:18432
	ds_read_b128 v[140:143], v244 offset:19456
	ds_read_b128 v[160:163], v244 offset:20480
	ds_read_b128 v[164:167], v244 offset:21504
	ds_read_b128 v[168:171], v244 offset:22528
	ds_read_b128 v[172:175], v244 offset:23552
	s_add_i32 s44, s80, s7
	v_lshl_add_u64 v[196:197], s[48:49], 0, v[214:215]
	s_mov_b32 m0, s44
	s_nop 0
	global_load_lds_dwordx4 v[196:197], off
	v_lshl_add_u64 v[198:199], s[48:49], 0, v[210:211]
	s_add_i32 m0, s44, 0x2000
	s_nop 0
	global_load_lds_dwordx4 v[198:199], off
	s_mov_b32 m0, s9
	v_lshl_add_u64 v[200:201], s[72:73], 0, v[216:217]
	global_load_lds_dwordx4 v[200:201], off
	v_lshl_add_u64 v[202:203], s[72:73], 0, v[212:213]
	s_mov_b32 m0, s63
	s_nop 0
	global_load_lds_dwordx4 v[202:203], off
	s_add_u32 s44, s48, 0x40000
	s_addc_u32 s45, s49, 0
	s_add_i32 s88, s81, s7
	v_lshl_add_u64 v[254:255], s[44:45], 0, v[214:215]
	s_mov_b32 m0, s88
	s_nop 0
	global_load_lds_dwordx4 v[254:255], off
	v_lshl_add_u64 v[254:255], s[44:45], 0, v[210:211]
	s_add_i32 m0, s88, 0x2000
	s_nop 0
	global_load_lds_dwordx4 v[254:255], off
	s_waitcnt vmcnt(6)
	s_waitcnt lgkmcnt(0)
	s_barrier
; #define PG8_STAGE(bufoff, gbase, voff) do { _Pragma("unroll") for (int _i = 0; _i < 2; ++_i) \
;         __builtin_amdgcn_global_load_lds((const unsigned*)((const char*)(gbase) + (voff)[_i]), (LAS unsigned*)(lds + (bufoff) + ldsw + _i * 8192), 16, 0, 0); } while (0)
; #define PG8_LDA(dst, b, h) do { _Pragma("unroll") for (int m = 0; m < 4; ++m) _Pragma("unroll") for (int k = 0; k < 2; ++k) dst[m][k] = *(const LAS bf16x8*)(lds + PG8_SA(b, h) + aoff + m * 2048 + k * 1024); } while (0)
; #define PG8_LDB(dst, b, h) do { _Pragma("unroll") for (int n = 0; n < 2; ++n) _Pragma("unroll") for (int k = 0; k < 2; ++k) dst[n][k] = *(const LAS bf16x8*)(lds + PG8_SB(b, h) + boff + n * 2048 + k * 1024); } while (0)
; #define PG8_MMA(ai, bj, At, Bt) do { __builtin_amdgcn_s_setprio(1); _Pragma("unroll") for (int m = 0; m < 4; ++m) _Pragma("unroll") for (int n = 0; n < 2; ++n) _Pragma("unroll") for (int k = 0; k < 2; ++k) \
;         acc[ai][bj][m][n] = __builtin_amdgcn_mfma_f32_16x16x32_bf16(Bt[n][k], At[m][k], acc[ai][bj][m][n], 0, 0, 0); __builtin_amdgcn_s_setprio(0); } while (0)
; #define PG8_WAIT_V(n) asm volatile("s_waitcnt vmcnt(" #n ")" ::: "memory")
; #define PG8_WAIT_L(n) asm volatile("s_waitcnt lgkmcnt(" #n ")" ::: "memory")
; #define PG8_BAR __builtin_amdgcn_s_barrier()
; #define PG8_SCHED __builtin_amdgcn_sched_barrier(0)
; template <class Epi>
; __device__ __forceinline__ void gemm_phase(LAS unsigned char* lds, const Gemm g, const StaticOrder& S, const Epi& E) {
;     ...
;             PG8_BAR; PG8_WAIT_L(0); PG8_MMA(1, 0, At, B0); PG8_BAR; PG8_SCHED;
;             PG8_STAGE(PG8_SB(0, 1), b2 + hstepB, voffB);
;             PG8_WAIT_V(6); PG8_BAR; PG8_MMA(1, 1, At, B1); PG8_BAR;
;             PG8_LDB(B0, 1, 0); PG8_SCHED; PG8_LDA(At, 1, 0); PG8_STAGE(PG8_SA(0, 1), a2 + hstepA, voffA);
;             PG8_WAIT_L(8); PG8_BAR; PG8_WAIT_L(0); PG8_MMA(0, 0, At, B0); PG8_BAR; PG8_SCHED;
;             PG8_LDB(B1, 1, 1); PG8_STAGE(PG8_SB(1, 0), b3, voffB);
;             PG8_BAR; PG8_WAIT_L(0); PG8_MMA(0, 1, At, B1); PG8_BAR;
	s_setprio 1
	v_mfma_f32_16x16x32_bf16 v[92:95], v[96:99], v[124:127], 0
	v_mfma_f32_16x16x32_bf16 v[28:31], v[104:107], v[124:127], 0
	v_mfma_f32_16x16x32_bf16 v[80:83], v[96:99], v[132:135], 0
	v_mfma_f32_16x16x32_bf16 v[16:19], v[104:107], v[132:135], 0
	v_mfma_f32_16x16x32_bf16 v[76:79], v[96:99], v[160:163], 0
	v_mfma_f32_16x16x32_bf16 v[12:15], v[104:107], v[160:163], 0
	v_mfma_f32_16x16x32_bf16 v[84:87], v[96:99], v[168:171], 0
	v_mfma_f32_16x16x32_bf16 v[20:23], v[104:107], v[168:171], 0
	v_mfma_f32_16x16x32_bf16 v[92:95], v[100:103], v[128:131], v[92:95]
	v_mfma_f32_16x16x32_bf16 v[28:31], v[108:111], v[128:131], v[28:31]
	v_mfma_f32_16x16x32_bf16 v[80:83], v[100:103], v[140:143], v[80:83]
	v_mfma_f32_16x16x32_bf16 v[16:19], v[108:111], v[140:143], v[16:19]
	v_mfma_f32_16x16x32_bf16 v[76:79], v[100:103], v[164:167], v[76:79]
	v_mfma_f32_16x16x32_bf16 v[12:15], v[108:111], v[164:167], v[12:15]
	v_mfma_f32_16x16x32_bf16 v[84:87], v[100:103], v[172:175], v[84:87]
	v_mfma_f32_16x16x32_bf16 v[20:23], v[108:111], v[172:175], v[20:23]
	v_mfma_f32_16x16x32_bf16 v[88:91], v[176:179], v[124:127], 0
	v_mfma_f32_16x16x32_bf16 v[24:27], v[184:187], v[124:127], 0
	v_mfma_f32_16x16x32_bf16 v[68:71], v[176:179], v[132:135], 0
	v_mfma_f32_16x16x32_bf16 v[4:7], v[184:187], v[132:135], 0
	v_mfma_f32_16x16x32_bf16 v[64:67], v[176:179], v[160:163], 0
	v_mfma_f32_16x16x32_bf16 v[0:3], v[184:187], v[160:163], 0
	v_mfma_f32_16x16x32_bf16 v[72:75], v[176:179], v[168:171], 0
	v_mfma_f32_16x16x32_bf16 v[8:11], v[184:187], v[168:171], 0
	v_mfma_f32_16x16x32_bf16 v[88:91], v[180:183], v[128:131], v[88:91]
	v_mfma_f32_16x16x32_bf16 v[24:27], v[188:191], v[128:131], v[24:27]
	v_mfma_f32_16x16x32_bf16 v[68:71], v[180:183], v[140:143], v[68:71]
	v_mfma_f32_16x16x32_bf16 v[4:7], v[188:191], v[140:143], v[4:7]
	v_mfma_f32_16x16x32_bf16 v[64:67], v[180:183], v[164:167], v[64:67]
	v_mfma_f32_16x16x32_bf16 v[0:3], v[188:191], v[164:167], v[0:3]
	v_mfma_f32_16x16x32_bf16 v[72:75], v[180:183], v[172:175], v[72:75]
	v_mfma_f32_16x16x32_bf16 v[8:11], v[188:191], v[172:175], v[8:11]
	s_setprio 0
	s_add_i32 s88, 0, 0x18000
	v_add_u32_e32 v108, s88, v235
	s_barrier
	ds_read_b128 v[96:99], v108
	ds_read_b128 v[100:103], v108 offset:1024
	ds_read_b128 v[104:107], v108 offset:2048
	ds_read_b128 v[108:111], v108 offset:3072
	s_add_u32 s44, s72, 0x40000
	s_addc_u32 s45, s73, 0
	s_mov_b32 m0, s74
	v_lshl_add_u64 v[132:133], s[44:45], 0, v[216:217]
	ds_read_b128 v[124:127], v244 offset:32768
	ds_read_b128 v[128:131], v244 offset:33792
	ds_read_b128 v[140:143], v244 offset:34816
	ds_read_b128 v[160:163], v244 offset:35840
	ds_read_b128 v[164:167], v244 offset:36864
	ds_read_b128 v[168:171], v244 offset:37888
	ds_read_b128 v[172:175], v244 offset:38912
	ds_read_b128 v[176:179], v244 offset:39936
	global_load_lds_dwordx4 v[132:133], off
	v_lshl_add_u64 v[132:133], s[44:45], 0, v[212:213]
	s_mov_b32 m0, s75
	s_nop 0
	global_load_lds_dwordx4 v[132:133], off
	s_add_i32 s72, 0, 0x1c000
	v_add_u32_e32 v132, s72, v235
	ds_read_b128 v[180:183], v132
	ds_read_b128 v[184:187], v132 offset:1024
	ds_read_b128 v[188:191], v132 offset:2048
	ds_read_b128 v[192:195], v132 offset:3072
	s_waitcnt lgkmcnt(0)
	s_barrier
	s_setprio 1
	v_mfma_f32_16x16x32_bf16 v[132:135], v[96:99], v[124:127], v[156:159]
	v_mfma_f32_16x16x32_bf16 v[156:159], v[100:103], v[128:131], v[132:135]
	v_mfma_f32_16x16x32_bf16 v[132:135], v[96:99], v[140:143], v[144:147]
	v_mfma_f32_16x16x32_bf16 v[144:147], v[100:103], v[160:163], v[132:135]
	v_mfma_f32_16x16x32_bf16 v[132:135], v[96:99], v[164:167], v[136:139]
	v_mfma_f32_16x16x32_bf16 v[60:63], v[104:107], v[124:127], v[60:63]
	v_mfma_f32_16x16x32_bf16 v[48:51], v[104:107], v[140:143], v[48:51]
	v_mfma_f32_16x16x32_bf16 v[136:139], v[100:103], v[168:171], v[132:135]
	v_mfma_f32_16x16x32_bf16 v[40:43], v[104:107], v[164:167], v[40:43]
	v_mfma_f32_16x16x32_bf16 v[132:135], v[96:99], v[172:175], v[148:151]
	v_mfma_f32_16x16x32_bf16 v[52:55], v[104:107], v[172:175], v[52:55]
	v_mfma_f32_16x16x32_bf16 v[60:63], v[108:111], v[128:131], v[60:63]
	v_mfma_f32_16x16x32_bf16 v[48:51], v[108:111], v[160:163], v[48:51]
	v_mfma_f32_16x16x32_bf16 v[40:43], v[108:111], v[168:171], v[40:43]
	v_mfma_f32_16x16x32_bf16 v[148:151], v[100:103], v[176:179], v[132:135]
	v_mfma_f32_16x16x32_bf16 v[52:55], v[108:111], v[176:179], v[52:55]
	v_mfma_f32_16x16x32_bf16 v[132:135], v[180:183], v[124:127], v[152:155]
	v_mfma_f32_16x16x32_bf16 v[112:115], v[180:183], v[140:143], v[112:115]
	v_mfma_f32_16x16x32_bf16 v[152:155], v[184:187], v[128:131], v[132:135]
	v_mfma_f32_16x16x32_bf16 v[56:59], v[188:191], v[124:127], v[56:59]
	v_mfma_f32_16x16x32_bf16 v[132:135], v[184:187], v[160:163], v[112:115]
	v_mfma_f32_16x16x32_bf16 v[112:115], v[180:183], v[164:167], v[116:119]
	v_mfma_f32_16x16x32_bf16 v[56:59], v[192:195], v[128:131], v[56:59]
	v_mfma_f32_16x16x32_bf16 v[36:39], v[188:191], v[140:143], v[36:39]
	v_mfma_f32_16x16x32_bf16 v[128:131], v[184:187], v[168:171], v[112:115]
	v_mfma_f32_16x16x32_bf16 v[32:35], v[188:191], v[164:167], v[32:35]
	v_mfma_f32_16x16x32_bf16 v[112:115], v[180:183], v[172:175], v[120:123]
	v_mfma_f32_16x16x32_bf16 v[44:47], v[188:191], v[172:175], v[44:47]
	v_mfma_f32_16x16x32_bf16 v[36:39], v[192:195], v[160:163], v[36:39]
	v_mfma_f32_16x16x32_bf16 v[32:35], v[192:195], v[168:171], v[32:35]
	v_mfma_f32_16x16x32_bf16 v[140:143], v[184:187], v[176:179], v[112:115]
	v_mfma_f32_16x16x32_bf16 v[44:47], v[192:195], v[176:179], v[44:47]
	s_setprio 0
	s_barrier
; #define PG8_STAGE(bufoff, gbase, voff) do { _Pragma("unroll") for (int _i = 0; _i < 2; ++_i) \
;         __builtin_amdgcn_global_load_lds((const unsigned*)((const char*)(gbase) + (voff)[_i]), (LAS unsigned*)(lds + (bufoff) + ldsw + _i * 8192), 16, 0, 0); } while (0)
; #define PG8_LDA(dst, b, h) do { _Pragma("unroll") for (int m = 0; m < 4; ++m) _Pragma("unroll") for (int k = 0; k < 2; ++k) dst[m][k] = *(const LAS bf16x8*)(lds + PG8_SA(b, h) + aoff + m * 2048 + k * 1024); } while (0)
; #define PG8_MMA(ai, bj, At, Bt) do { __builtin_amdgcn_s_setprio(1); _Pragma("unroll") for (int m = 0; m < 4; ++m) _Pragma("unroll") for (int n = 0; n < 2; ++n) _Pragma("unroll") for (int k = 0; k < 2; ++k) \
;         acc[ai][bj][m][n] = __builtin_amdgcn_mfma_f32_16x16x32_bf16(Bt[n][k], At[m][k], acc[ai][bj][m][n], 0, 0, 0); __builtin_amdgcn_s_setprio(0); } while (0)
; #define PG8_WAIT_V(n) asm volatile("s_waitcnt vmcnt(" #n ")" ::: "memory")
; #define PG8_WAIT_L(n) asm volatile("s_waitcnt lgkmcnt(" #n ")" ::: "memory")
; #define PG8_BAR __builtin_amdgcn_s_barrier()
; #define PG8_SCHED __builtin_amdgcn_sched_barrier(0)
; template <class Epi>
; __device__ __forceinline__ void gemm_phase(LAS unsigned char* lds, const Gemm g, const StaticOrder& S, const Epi& E) {
;     ...
;             PG8_LDA(At, 1, 1); PG8_STAGE(PG8_SA(1, 0), a3, voffA);
;             PG8_BAR; PG8_WAIT_L(0); PG8_MMA(1, 0, At, B0); PG8_BAR; PG8_SCHED;
;             PG8_STAGE(PG8_SB(1, 1), b3 + hstepB, voffB);
;             PG8_WAIT_V(6); PG8_BAR; PG8_MMA(1, 1, At, B1); PG8_BAR;
	s_nop 1
	ds_read_b128 v[112:115], v244 offset:49152
	ds_read_b128 v[116:119], v244 offset:50176
	ds_read_b128 v[120:123], v244 offset:51200
	ds_read_b128 v[124:127], v244 offset:52224
	ds_read_b128 v[160:163], v244 offset:53248
	ds_read_b128 v[164:167], v244 offset:54272
	ds_read_b128 v[168:171], v244 offset:55296
	ds_read_b128 v[172:175], v244 offset:56320
	s_add_i32 s44, s88, s7
	v_lshl_add_u64 v[254:255], v[196:197], 0, s[24:25]
	s_mov_b32 m0, s44
	s_nop 0
	global_load_lds_dwordx4 v[254:255], off
	v_lshl_add_u64 v[254:255], v[198:199], 0, s[24:25]
	s_add_i32 m0, s44, 0x2000
	s_nop 0
	global_load_lds_dwordx4 v[254:255], off
	s_mov_b32 m0, s78
	v_lshl_add_u64 v[254:255], v[200:201], 0, s[24:25]
	global_load_lds_dwordx4 v[254:255], off
	v_lshl_add_u64 v[254:255], v[202:203], 0, s[24:25]
	s_mov_b32 m0, s79
	s_nop 0
	global_load_lds_dwordx4 v[254:255], off
	s_add_u32 s44, s48, 0x40080
	s_addc_u32 s45, s49, 0
	s_add_i32 s48, s72, s7
	v_lshl_add_u64 v[254:255], s[44:45], 0, v[214:215]
	s_mov_b32 m0, s48
	s_nop 0
	global_load_lds_dwordx4 v[254:255], off
	v_lshl_add_u64 v[254:255], s[44:45], 0, v[210:211]
	s_add_i32 m0, s48, 0x2000
	s_nop 0
	global_load_lds_dwordx4 v[254:255], off
	s_waitcnt vmcnt(6)
	s_waitcnt lgkmcnt(0)
	s_barrier
	s_setprio 1
	v_mfma_f32_16x16x32_bf16 v[92:95], v[96:99], v[112:115], v[92:95]
	v_mfma_f32_16x16x32_bf16 v[28:31], v[104:107], v[112:115], v[28:31]
	v_mfma_f32_16x16x32_bf16 v[80:83], v[96:99], v[120:123], v[80:83]
	v_mfma_f32_16x16x32_bf16 v[16:19], v[104:107], v[120:123], v[16:19]
	v_mfma_f32_16x16x32_bf16 v[76:79], v[96:99], v[160:163], v[76:79]
	v_mfma_f32_16x16x32_bf16 v[12:15], v[104:107], v[160:163], v[12:15]
	v_mfma_f32_16x16x32_bf16 v[84:87], v[96:99], v[168:171], v[84:87]
	v_mfma_f32_16x16x32_bf16 v[20:23], v[104:107], v[168:171], v[20:23]
	v_mfma_f32_16x16x32_bf16 v[92:95], v[100:103], v[116:119], v[92:95]
	v_mfma_f32_16x16x32_bf16 v[28:31], v[108:111], v[116:119], v[28:31]
	v_mfma_f32_16x16x32_bf16 v[80:83], v[100:103], v[124:127], v[80:83]
	v_mfma_f32_16x16x32_bf16 v[16:19], v[108:111], v[124:127], v[16:19]
	v_mfma_f32_16x16x32_bf16 v[76:79], v[100:103], v[164:167], v[76:79]
	v_mfma_f32_16x16x32_bf16 v[12:15], v[108:111], v[164:167], v[12:15]
	v_mfma_f32_16x16x32_bf16 v[84:87], v[100:103], v[172:175], v[84:87]
	v_mfma_f32_16x16x32_bf16 v[20:23], v[108:111], v[172:175], v[20:23]
	v_mfma_f32_16x16x32_bf16 v[88:91], v[180:183], v[112:115], v[88:91]
	v_mfma_f32_16x16x32_bf16 v[24:27], v[188:191], v[112:115], v[24:27]
	v_mfma_f32_16x16x32_bf16 v[68:71], v[180:183], v[120:123], v[68:71]
	v_mfma_f32_16x16x32_bf16 v[4:7], v[188:191], v[120:123], v[4:7]
	v_mfma_f32_16x16x32_bf16 v[64:67], v[180:183], v[160:163], v[64:67]
	v_mfma_f32_16x16x32_bf16 v[0:3], v[188:191], v[160:163], v[0:3]
	v_mfma_f32_16x16x32_bf16 v[72:75], v[180:183], v[168:171], v[72:75]
	v_mfma_f32_16x16x32_bf16 v[8:11], v[188:191], v[168:171], v[8:11]
	v_mfma_f32_16x16x32_bf16 v[88:91], v[184:187], v[116:119], v[88:91]
	v_mfma_f32_16x16x32_bf16 v[24:27], v[192:195], v[116:119], v[24:27]
	v_mfma_f32_16x16x32_bf16 v[68:71], v[184:187], v[124:127], v[68:71]
	v_mfma_f32_16x16x32_bf16 v[4:7], v[192:195], v[124:127], v[4:7]
	v_mfma_f32_16x16x32_bf16 v[64:67], v[184:187], v[164:167], v[64:67]
	v_mfma_f32_16x16x32_bf16 v[0:3], v[192:195], v[164:167], v[0:3]
	v_mfma_f32_16x16x32_bf16 v[72:75], v[184:187], v[172:175], v[72:75]
	v_mfma_f32_16x16x32_bf16 v[8:11], v[192:195], v[172:175], v[8:11]
	s_setprio 0
	s_add_i32 s87, s87, 2
	s_add_u32 s85, s85, 0x100
	s_addc_u32 s86, s86, 0
	s_cmp_gt_u32 s87, 13
	s_mov_b64 s[44:45], s[46:47]
	s_barrier
	.p2alignl 6, 3212836864

; #define PG8_STAGE(bufoff, gbase, voff) do { _Pragma("unroll") for (int _i = 0; _i < 2; ++_i) \
;         __builtin_amdgcn_global_load_lds((const unsigned*)((const char*)(gbase) + (voff)[_i]), (LAS unsigned*)(lds + (bufoff) + ldsw + _i * 8192), 16, 0, 0); } while (0)
; #define PG8_LDA(dst, b, h) do { _Pragma("unroll") for (int m = 0; m < 4; ++m) _Pragma("unroll") for (int k = 0; k < 2; ++k) dst[m][k] = *(const LAS bf16x8*)(lds + PG8_SA(b, h) + aoff + m * 2048 + k * 1024); } while (0)
; #define PG8_LDB(dst, b, h) do { _Pragma("unroll") for (int n = 0; n < 2; ++n) _Pragma("unroll") for (int k = 0; k < 2; ++k) dst[n][k] = *(const LAS bf16x8*)(lds + PG8_SB(b, h) + boff + n * 2048 + k * 1024); } while (0)
; #define PG8_MMA(ai, bj, At, Bt) do { __builtin_amdgcn_s_setprio(1); _Pragma("unroll") for (int m = 0; m < 4; ++m) _Pragma("unroll") for (int n = 0; n < 2; ++n) _Pragma("unroll") for (int k = 0; k < 2; ++k) \
;         acc[ai][bj][m][n] = __builtin_amdgcn_mfma_f32_16x16x32_bf16(Bt[n][k], At[m][k], acc[ai][bj][m][n], 0, 0, 0); __builtin_amdgcn_s_setprio(0); } while (0)
; #define PG8_WAIT_L(n) asm volatile("s_waitcnt lgkmcnt(" #n ")" ::: "memory")
; #define PG8_BAR __builtin_amdgcn_s_barrier()
; #define PG8_SCHED __builtin_amdgcn_sched_barrier(0)
; template <class Epi>
; __device__ __forceinline__ void gemm_phase(LAS unsigned char* lds, const Gemm g, const StaticOrder& S, const Epi& E) {
;     ...
;             const bool last = (t == nt - 2);
;             const char* a1 = cA + (size_t)(t + 1) * kstep;
;             const char* a2 = last ? nA : cA + (size_t)(t + 2) * kstep; const char* b2 = last ? nB : cB + (size_t)(t + 2) * kstep;
;             const char* a3 = a2 + kstep; const char* b3 = b2 + kstep;
;             PG8_LDB(B0, 0, 0); PG8_SCHED; PG8_LDA(At, 0, 0); PG8_STAGE(PG8_SA(1, 1), a1 + hstepA, voffA);
;             PG8_WAIT_L(8); PG8_BAR; PG8_WAIT_L(0); PG8_MMA(0, 0, At, B0); PG8_BAR; PG8_SCHED;
;             PG8_LDB(B1, 0, 1); PG8_STAGE(PG8_SB(0, 0), b2, voffB);
;             PG8_BAR; PG8_WAIT_L(0); PG8_MMA(0, 1, At, B1); PG8_BAR;
;             PG8_LDA(At, 0, 1); PG8_STAGE(PG8_SA(0, 0), a2, voffA);
.LBB0_1460:
	s_add_u32 s72, s34, 0x100
	s_addc_u32 s73, s35, 0
	s_mov_b32 s74, -2
	ds_read_b128 v[140:143], v149
	ds_read_b128 v[152:155], v149 offset:1024
	ds_read_b128 v[156:159], v149 offset:2048
	ds_read_b128 v[160:163], v149 offset:3072
	s_add_u32 s34, s30, 0x100
	s_addc_u32 s35, s31, 0
	s_cmp_eq_u32 s74, 40
	s_cselect_b32 s39, s13, s35
	s_cselect_b32 s38, s12, s34
	s_cselect_b32 s37, s15, s73
	s_cselect_b32 s36, s14, s72
	v_lshl_add_u64 v[144:145], s[30:31], 0, v[132:133]
	s_add_i32 m0, s8, 0xc000
	ds_read_b128 v[164:167], v150
	ds_read_b128 v[168:171], v150 offset:1024
	ds_read_b128 v[172:175], v150 offset:2048
	ds_read_b128 v[176:179], v150 offset:3072
	ds_read_b128 v[180:183], v150 offset:4096
	ds_read_b128 v[184:187], v150 offset:5120
	ds_read_b128 v[188:191], v150 offset:6144
	ds_read_b128 v[192:195], v150 offset:7168
	global_load_lds_dwordx4 v[144:145], off
	v_lshl_add_u64 v[144:145], s[30:31], 0, v[134:135]
	s_add_i32 m0, s8, 0xe000
	s_nop 0
	global_load_lds_dwordx4 v[144:145], off
	ds_read_b128 v[196:199], v151
	ds_read_b128 v[200:203], v151 offset:1024
	ds_read_b128 v[204:207], v151 offset:2048
	ds_read_b128 v[208:211], v151 offset:3072
	s_waitcnt lgkmcnt(0)
	s_barrier
	s_setprio 1
	v_mfma_f32_16x16x32_bf16 v[124:127], v[140:143], v[164:167], 0
	v_mfma_f32_16x16x32_bf16 v[120:123], v[156:159], v[164:167], 0
	v_mfma_f32_16x16x32_bf16 v[112:115], v[140:143], v[172:175], 0
	v_mfma_f32_16x16x32_bf16 v[104:107], v[156:159], v[172:175], 0
	v_mfma_f32_16x16x32_bf16 v[92:95], v[140:143], v[180:183], 0
	v_mfma_f32_16x16x32_bf16 v[88:91], v[156:159], v[180:183], 0
	v_mfma_f32_16x16x32_bf16 v[80:83], v[140:143], v[188:191], 0
	v_mfma_f32_16x16x32_bf16 v[72:75], v[156:159], v[188:191], 0
	v_mfma_f32_16x16x32_bf16 v[124:127], v[152:155], v[168:171], v[124:127]
	v_mfma_f32_16x16x32_bf16 v[120:123], v[160:163], v[168:171], v[120:123]
	v_mfma_f32_16x16x32_bf16 v[112:115], v[152:155], v[176:179], v[112:115]
	v_mfma_f32_16x16x32_bf16 v[104:107], v[160:163], v[176:179], v[104:107]
	v_mfma_f32_16x16x32_bf16 v[92:95], v[152:155], v[184:187], v[92:95]
	v_mfma_f32_16x16x32_bf16 v[88:91], v[160:163], v[184:187], v[88:91]
	v_mfma_f32_16x16x32_bf16 v[80:83], v[152:155], v[192:195], v[80:83]
	v_mfma_f32_16x16x32_bf16 v[72:75], v[160:163], v[192:195], v[72:75]
	v_mfma_f32_16x16x32_bf16 v[116:119], v[196:199], v[164:167], 0
	v_mfma_f32_16x16x32_bf16 v[108:111], v[204:207], v[164:167], 0
	v_mfma_f32_16x16x32_bf16 v[100:103], v[196:199], v[172:175], 0
	v_mfma_f32_16x16x32_bf16 v[96:99], v[204:207], v[172:175], 0
	v_mfma_f32_16x16x32_bf16 v[84:87], v[196:199], v[180:183], 0
	v_mfma_f32_16x16x32_bf16 v[76:79], v[204:207], v[180:183], 0
	v_mfma_f32_16x16x32_bf16 v[68:71], v[196:199], v[188:191], 0
	v_mfma_f32_16x16x32_bf16 v[64:67], v[204:207], v[188:191], 0
	v_mfma_f32_16x16x32_bf16 v[116:119], v[200:203], v[168:171], v[116:119]
	v_mfma_f32_16x16x32_bf16 v[108:111], v[208:211], v[168:171], v[108:111]
	v_mfma_f32_16x16x32_bf16 v[100:103], v[200:203], v[176:179], v[100:103]
	v_mfma_f32_16x16x32_bf16 v[96:99], v[208:211], v[176:179], v[96:99]
	v_mfma_f32_16x16x32_bf16 v[84:87], v[200:203], v[184:187], v[84:87]
	v_mfma_f32_16x16x32_bf16 v[76:79], v[208:211], v[184:187], v[76:79]
	v_mfma_f32_16x16x32_bf16 v[68:71], v[200:203], v[192:195], v[68:71]
	v_mfma_f32_16x16x32_bf16 v[64:67], v[208:211], v[192:195], v[64:67]
	s_setprio 0
	s_barrier
	s_nop 1
	ds_read_b128 v[164:167], v150 offset:16384
	ds_read_b128 v[168:171], v150 offset:17408
	ds_read_b128 v[172:175], v150 offset:18432
	ds_read_b128 v[176:179], v150 offset:19456
	ds_read_b128 v[180:183], v150 offset:20480
	ds_read_b128 v[184:187], v150 offset:21504
	ds_read_b128 v[188:191], v150 offset:22528
	ds_read_b128 v[192:195], v150 offset:23552
	s_add_i32 s30, s45, s7
	v_lshl_add_u64 v[144:145], s[36:37], 0, v[128:129]
	s_mov_b32 m0, s30
	s_nop 0
	global_load_lds_dwordx4 v[144:145], off
	v_lshl_add_u64 v[212:213], s[36:37], 0, v[130:131]
	s_add_i32 m0, s30, 0x2000
	s_nop 0
	global_load_lds_dwordx4 v[212:213], off
	s_mov_b32 m0, s8
	v_lshl_add_u64 v[214:215], s[38:39], 0, v[128:129]
	global_load_lds_dwordx4 v[214:215], off
	v_lshl_add_u64 v[216:217], s[38:39], 0, v[130:131]
	s_mov_b32 m0, s9
	s_nop 0
	global_load_lds_dwordx4 v[216:217], off
	s_add_u32 s30, s36, 0xb0000
	s_addc_u32 s31, s37, 0
	s_add_i32 s75, s46, s7
	v_lshl_add_u64 v[254:255], s[30:31], 0, v[128:129]
	s_mov_b32 m0, s75
	s_nop 0
	global_load_lds_dwordx4 v[254:255], off
	v_lshl_add_u64 v[254:255], s[30:31], 0, v[130:131]
	s_add_i32 m0, s75, 0x2000
	s_nop 0
	global_load_lds_dwordx4 v[254:255], off
	s_waitcnt vmcnt(6)
	s_waitcnt lgkmcnt(0)
	s_barrier
; #define PG8_STAGE(bufoff, gbase, voff) do { _Pragma("unroll") for (int _i = 0; _i < 2; ++_i) \
;         __builtin_amdgcn_global_load_lds((const unsigned*)((const char*)(gbase) + (voff)[_i]), (LAS unsigned*)(lds + (bufoff) + ldsw + _i * 8192), 16, 0, 0); } while (0)
; #define PG8_LDA(dst, b, h) do { _Pragma("unroll") for (int m = 0; m < 4; ++m) _Pragma("unroll") for (int k = 0; k < 2; ++k) dst[m][k] = *(const LAS bf16x8*)(lds + PG8_SA(b, h) + aoff + m * 2048 + k * 1024); } while (0)
; #define PG8_LDB(dst, b, h) do { _Pragma("unroll") for (int n = 0; n < 2; ++n) _Pragma("unroll") for (int k = 0; k < 2; ++k) dst[n][k] = *(const LAS bf16x8*)(lds + PG8_SB(b, h) + boff + n * 2048 + k * 1024); } while (0)
; #define PG8_MMA(ai, bj, At, Bt) do { __builtin_amdgcn_s_setprio(1); _Pragma("unroll") for (int m = 0; m < 4; ++m) _Pragma("unroll") for (int n = 0; n < 2; ++n) _Pragma("unroll") for (int k = 0; k < 2; ++k) \
;         acc[ai][bj][m][n] = __builtin_amdgcn_mfma_f32_16x16x32_bf16(Bt[n][k], At[m][k], acc[ai][bj][m][n], 0, 0, 0); __builtin_amdgcn_s_setprio(0); } while (0)
; #define PG8_WAIT_V(n) asm volatile("s_waitcnt vmcnt(" #n ")" ::: "memory")
; #define PG8_WAIT_L(n) asm volatile("s_waitcnt lgkmcnt(" #n ")" ::: "memory")
; #define PG8_BAR __builtin_amdgcn_s_barrier()
; #define PG8_SCHED __builtin_amdgcn_sched_barrier(0)
; template <class Epi>
; __device__ __forceinline__ void gemm_phase(LAS unsigned char* lds, const Gemm g, const StaticOrder& S, const Epi& E) {
;     ...
;             PG8_BAR; PG8_WAIT_L(0); PG8_MMA(1, 0, At, B0); PG8_BAR; PG8_SCHED;
;             PG8_STAGE(PG8_SB(0, 1), b2 + hstepB, voffB);
;             PG8_WAIT_V(6); PG8_BAR; PG8_MMA(1, 1, At, B1); PG8_BAR;
;             PG8_LDB(B0, 1, 0); PG8_SCHED; PG8_LDA(At, 1, 0); PG8_STAGE(PG8_SA(0, 1), a2 + hstepA, voffA);
;             PG8_WAIT_L(8); PG8_BAR; PG8_WAIT_L(0); PG8_MMA(0, 0, At, B0); PG8_BAR; PG8_SCHED;
;             PG8_LDB(B1, 1, 1); PG8_STAGE(PG8_SB(1, 0), b3, voffB);
;             PG8_BAR; PG8_WAIT_L(0); PG8_MMA(0, 1, At, B1); PG8_BAR;
	s_setprio 1
	v_mfma_f32_16x16x32_bf16 v[60:63], v[140:143], v[164:167], 0
	v_mfma_f32_16x16x32_bf16 v[56:59], v[156:159], v[164:167], 0
	v_mfma_f32_16x16x32_bf16 v[48:51], v[140:143], v[172:175], 0
	v_mfma_f32_16x16x32_bf16 v[40:43], v[156:159], v[172:175], 0
	v_mfma_f32_16x16x32_bf16 v[28:31], v[140:143], v[180:183], 0
	v_mfma_f32_16x16x32_bf16 v[24:27], v[156:159], v[180:183], 0
	v_mfma_f32_16x16x32_bf16 v[16:19], v[140:143], v[188:191], 0
	v_mfma_f32_16x16x32_bf16 v[8:11], v[156:159], v[188:191], 0
	v_mfma_f32_16x16x32_bf16 v[60:63], v[152:155], v[168:171], v[60:63]
	v_mfma_f32_16x16x32_bf16 v[56:59], v[160:163], v[168:171], v[56:59]
	v_mfma_f32_16x16x32_bf16 v[48:51], v[152:155], v[176:179], v[48:51]
	v_mfma_f32_16x16x32_bf16 v[40:43], v[160:163], v[176:179], v[40:43]
	v_mfma_f32_16x16x32_bf16 v[28:31], v[152:155], v[184:187], v[28:31]
	v_mfma_f32_16x16x32_bf16 v[24:27], v[160:163], v[184:187], v[24:27]
	v_mfma_f32_16x16x32_bf16 v[16:19], v[152:155], v[192:195], v[16:19]
	v_mfma_f32_16x16x32_bf16 v[8:11], v[160:163], v[192:195], v[8:11]
	v_mfma_f32_16x16x32_bf16 v[52:55], v[196:199], v[164:167], 0
	v_mfma_f32_16x16x32_bf16 v[44:47], v[204:207], v[164:167], 0
	v_mfma_f32_16x16x32_bf16 v[36:39], v[196:199], v[172:175], 0
	v_mfma_f32_16x16x32_bf16 v[32:35], v[204:207], v[172:175], 0
	v_mfma_f32_16x16x32_bf16 v[20:23], v[196:199], v[180:183], 0
	v_mfma_f32_16x16x32_bf16 v[12:15], v[204:207], v[180:183], 0
	v_mfma_f32_16x16x32_bf16 v[4:7], v[196:199], v[188:191], 0
	v_mfma_f32_16x16x32_bf16 v[0:3], v[204:207], v[188:191], 0
	v_mfma_f32_16x16x32_bf16 v[52:55], v[200:203], v[168:171], v[52:55]
	v_mfma_f32_16x16x32_bf16 v[44:47], v[208:211], v[168:171], v[44:47]
	v_mfma_f32_16x16x32_bf16 v[36:39], v[200:203], v[176:179], v[36:39]
	v_mfma_f32_16x16x32_bf16 v[32:35], v[208:211], v[176:179], v[32:35]
	v_mfma_f32_16x16x32_bf16 v[20:23], v[200:203], v[184:187], v[20:23]
	v_mfma_f32_16x16x32_bf16 v[12:15], v[208:211], v[184:187], v[12:15]
	v_mfma_f32_16x16x32_bf16 v[4:7], v[200:203], v[192:195], v[4:7]
	v_mfma_f32_16x16x32_bf16 v[0:3], v[208:211], v[192:195], v[0:3]
	s_setprio 0
	s_add_i32 s75, 0, 0x18000
	v_add_u32_e32 v160, s75, v147
	s_barrier
	ds_read_b128 v[140:143], v160
	ds_read_b128 v[152:155], v160 offset:1024
	ds_read_b128 v[156:159], v160 offset:2048
	ds_read_b128 v[160:163], v160 offset:3072
	s_add_u32 s30, s38, 0xb0000
	s_addc_u32 s31, s39, 0
	s_mov_b32 m0, s40
	v_lshl_add_u64 v[196:197], s[30:31], 0, v[128:129]
	ds_read_b128 v[164:167], v150 offset:32768
	ds_read_b128 v[168:171], v150 offset:33792
	ds_read_b128 v[172:175], v150 offset:34816
	ds_read_b128 v[176:179], v150 offset:35840
	ds_read_b128 v[180:183], v150 offset:36864
	ds_read_b128 v[184:187], v150 offset:37888
	ds_read_b128 v[188:191], v150 offset:38912
	ds_read_b128 v[192:195], v150 offset:39936
	global_load_lds_dwordx4 v[196:197], off
	v_lshl_add_u64 v[196:197], s[30:31], 0, v[130:131]
	s_mov_b32 m0, s41
	s_nop 0
	global_load_lds_dwordx4 v[196:197], off
	s_add_i32 s38, 0, 0x1c000
	v_add_u32_e32 v208, s38, v147
	ds_read_b128 v[196:199], v208
	ds_read_b128 v[200:203], v208 offset:1024
	ds_read_b128 v[204:207], v208 offset:2048
	ds_read_b128 v[208:211], v208 offset:3072
	s_waitcnt lgkmcnt(0)
	s_barrier
	s_setprio 1
	v_mfma_f32_16x16x32_bf16 v[124:127], v[140:143], v[164:167], v[124:127]
	v_mfma_f32_16x16x32_bf16 v[120:123], v[156:159], v[164:167], v[120:123]
	v_mfma_f32_16x16x32_bf16 v[112:115], v[140:143], v[172:175], v[112:115]
	v_mfma_f32_16x16x32_bf16 v[104:107], v[156:159], v[172:175], v[104:107]
	v_mfma_f32_16x16x32_bf16 v[92:95], v[140:143], v[180:183], v[92:95]
	v_mfma_f32_16x16x32_bf16 v[88:91], v[156:159], v[180:183], v[88:91]
	v_mfma_f32_16x16x32_bf16 v[80:83], v[140:143], v[188:191], v[80:83]
	v_mfma_f32_16x16x32_bf16 v[72:75], v[156:159], v[188:191], v[72:75]
	v_mfma_f32_16x16x32_bf16 v[124:127], v[152:155], v[168:171], v[124:127]
	v_mfma_f32_16x16x32_bf16 v[120:123], v[160:163], v[168:171], v[120:123]
	v_mfma_f32_16x16x32_bf16 v[112:115], v[152:155], v[176:179], v[112:115]
	v_mfma_f32_16x16x32_bf16 v[104:107], v[160:163], v[176:179], v[104:107]
	v_mfma_f32_16x16x32_bf16 v[92:95], v[152:155], v[184:187], v[92:95]
	v_mfma_f32_16x16x32_bf16 v[88:91], v[160:163], v[184:187], v[88:91]
	v_mfma_f32_16x16x32_bf16 v[80:83], v[152:155], v[192:195], v[80:83]
	v_mfma_f32_16x16x32_bf16 v[72:75], v[160:163], v[192:195], v[72:75]
	v_mfma_f32_16x16x32_bf16 v[116:119], v[196:199], v[164:167], v[116:119]
	v_mfma_f32_16x16x32_bf16 v[108:111], v[204:207], v[164:167], v[108:111]
	v_mfma_f32_16x16x32_bf16 v[100:103], v[196:199], v[172:175], v[100:103]
	v_mfma_f32_16x16x32_bf16 v[96:99], v[204:207], v[172:175], v[96:99]
	v_mfma_f32_16x16x32_bf16 v[84:87], v[196:199], v[180:183], v[84:87]
	v_mfma_f32_16x16x32_bf16 v[76:79], v[204:207], v[180:183], v[76:79]
	v_mfma_f32_16x16x32_bf16 v[68:71], v[196:199], v[188:191], v[68:71]
	v_mfma_f32_16x16x32_bf16 v[64:67], v[204:207], v[188:191], v[64:67]
	v_mfma_f32_16x16x32_bf16 v[116:119], v[200:203], v[168:171], v[116:119]
	v_mfma_f32_16x16x32_bf16 v[108:111], v[208:211], v[168:171], v[108:111]
	v_mfma_f32_16x16x32_bf16 v[100:103], v[200:203], v[176:179], v[100:103]
	v_mfma_f32_16x16x32_bf16 v[96:99], v[208:211], v[176:179], v[96:99]
	v_mfma_f32_16x16x32_bf16 v[84:87], v[200:203], v[184:187], v[84:87]
	v_mfma_f32_16x16x32_bf16 v[76:79], v[208:211], v[184:187], v[76:79]
	v_mfma_f32_16x16x32_bf16 v[68:71], v[200:203], v[192:195], v[68:71]
	v_mfma_f32_16x16x32_bf16 v[64:67], v[208:211], v[192:195], v[64:67]
	s_setprio 0
	s_barrier
; #define PG8_STAGE(bufoff, gbase, voff) do { _Pragma("unroll") for (int _i = 0; _i < 2; ++_i) \
;         __builtin_amdgcn_global_load_lds((const unsigned*)((const char*)(gbase) + (voff)[_i]), (LAS unsigned*)(lds + (bufoff) + ldsw + _i * 8192), 16, 0, 0); } while (0)
; #define PG8_LDA(dst, b, h) do { _Pragma("unroll") for (int m = 0; m < 4; ++m) _Pragma("unroll") for (int k = 0; k < 2; ++k) dst[m][k] = *(const LAS bf16x8*)(lds + PG8_SA(b, h) + aoff + m * 2048 + k * 1024); } while (0)
; #define PG8_MMA(ai, bj, At, Bt) do { __builtin_amdgcn_s_setprio(1); _Pragma("unroll") for (int m = 0; m < 4; ++m) _Pragma("unroll") for (int n = 0; n < 2; ++n) _Pragma("unroll") for (int k = 0; k < 2; ++k) \
;         acc[ai][bj][m][n] = __builtin_amdgcn_mfma_f32_16x16x32_bf16(Bt[n][k], At[m][k], acc[ai][bj][m][n], 0, 0, 0); __builtin_amdgcn_s_setprio(0); } while (0)
; #define PG8_WAIT_V(n) asm volatile("s_waitcnt vmcnt(" #n ")" ::: "memory")
; #define PG8_WAIT_L(n) asm volatile("s_waitcnt lgkmcnt(" #n ")" ::: "memory")
; #define PG8_BAR __builtin_amdgcn_s_barrier()
; #define PG8_SCHED __builtin_amdgcn_sched_barrier(0)
; template <class Epi>
; __device__ __forceinline__ void gemm_phase(LAS unsigned char* lds, const Gemm g, const StaticOrder& S, const Epi& E) {
;     ...
;             PG8_LDA(At, 1, 1); PG8_STAGE(PG8_SA(1, 0), a3, voffA);
;             PG8_BAR; PG8_WAIT_L(0); PG8_MMA(1, 0, At, B0); PG8_BAR; PG8_SCHED;
;             PG8_STAGE(PG8_SB(1, 1), b3 + hstepB, voffB);
;             PG8_WAIT_V(6); PG8_BAR; PG8_MMA(1, 1, At, B1); PG8_BAR;
	s_nop 1
	ds_read_b128 v[164:167], v150 offset:49152
	ds_read_b128 v[168:171], v150 offset:50176
	ds_read_b128 v[172:175], v150 offset:51200
	ds_read_b128 v[176:179], v150 offset:52224
	ds_read_b128 v[180:183], v150 offset:53248
	ds_read_b128 v[184:187], v150 offset:54272
	ds_read_b128 v[188:191], v150 offset:55296
	ds_read_b128 v[192:195], v150 offset:56320
	s_add_i32 s30, s75, s7
	v_lshl_add_u64 v[254:255], v[144:145], 0, s[22:23]
	s_mov_b32 m0, s30
	s_nop 0
	global_load_lds_dwordx4 v[254:255], off
	v_lshl_add_u64 v[254:255], v[212:213], 0, s[22:23]
	s_add_i32 m0, s30, 0x2000
	s_nop 0
	global_load_lds_dwordx4 v[254:255], off
	s_mov_b32 m0, s43
	v_lshl_add_u64 v[254:255], v[214:215], 0, s[22:23]
	global_load_lds_dwordx4 v[254:255], off
	v_lshl_add_u64 v[144:145], v[216:217], 0, s[22:23]
	s_mov_b32 m0, s44
	s_nop 0
	global_load_lds_dwordx4 v[144:145], off
	s_add_u32 s30, s36, 0xb0080
	s_addc_u32 s31, s37, 0
	s_add_i32 s36, s38, s7
	v_lshl_add_u64 v[254:255], s[30:31], 0, v[128:129]
	s_mov_b32 m0, s36
	s_nop 0
	global_load_lds_dwordx4 v[254:255], off
	v_lshl_add_u64 v[254:255], s[30:31], 0, v[130:131]
	s_add_i32 m0, s36, 0x2000
	s_nop 0
	global_load_lds_dwordx4 v[254:255], off
	s_waitcnt vmcnt(6)
	s_waitcnt lgkmcnt(0)
	s_barrier
	s_setprio 1
	v_mfma_f32_16x16x32_bf16 v[60:63], v[140:143], v[164:167], v[60:63]
	v_mfma_f32_16x16x32_bf16 v[56:59], v[156:159], v[164:167], v[56:59]
	v_mfma_f32_16x16x32_bf16 v[48:51], v[140:143], v[172:175], v[48:51]
	v_mfma_f32_16x16x32_bf16 v[40:43], v[156:159], v[172:175], v[40:43]
	v_mfma_f32_16x16x32_bf16 v[28:31], v[140:143], v[180:183], v[28:31]
	v_mfma_f32_16x16x32_bf16 v[24:27], v[156:159], v[180:183], v[24:27]
	v_mfma_f32_16x16x32_bf16 v[16:19], v[140:143], v[188:191], v[16:19]
	v_mfma_f32_16x16x32_bf16 v[8:11], v[156:159], v[188:191], v[8:11]
	v_mfma_f32_16x16x32_bf16 v[60:63], v[152:155], v[168:171], v[60:63]
	v_mfma_f32_16x16x32_bf16 v[56:59], v[160:163], v[168:171], v[56:59]
	v_mfma_f32_16x16x32_bf16 v[48:51], v[152:155], v[176:179], v[48:51]
	v_mfma_f32_16x16x32_bf16 v[40:43], v[160:163], v[176:179], v[40:43]
	v_mfma_f32_16x16x32_bf16 v[28:31], v[152:155], v[184:187], v[28:31]
	v_mfma_f32_16x16x32_bf16 v[24:27], v[160:163], v[184:187], v[24:27]
	v_mfma_f32_16x16x32_bf16 v[16:19], v[152:155], v[192:195], v[16:19]
	v_mfma_f32_16x16x32_bf16 v[8:11], v[160:163], v[192:195], v[8:11]
	v_mfma_f32_16x16x32_bf16 v[52:55], v[196:199], v[164:167], v[52:55]
	v_mfma_f32_16x16x32_bf16 v[44:47], v[204:207], v[164:167], v[44:47]
	v_mfma_f32_16x16x32_bf16 v[36:39], v[196:199], v[172:175], v[36:39]
	v_mfma_f32_16x16x32_bf16 v[32:35], v[204:207], v[172:175], v[32:35]
	v_mfma_f32_16x16x32_bf16 v[20:23], v[196:199], v[180:183], v[20:23]
	v_mfma_f32_16x16x32_bf16 v[12:15], v[204:207], v[180:183], v[12:15]
	v_mfma_f32_16x16x32_bf16 v[4:7], v[196:199], v[188:191], v[4:7]
	v_mfma_f32_16x16x32_bf16 v[0:3], v[204:207], v[188:191], v[0:3]
	v_mfma_f32_16x16x32_bf16 v[52:55], v[200:203], v[168:171], v[52:55]
	v_mfma_f32_16x16x32_bf16 v[44:47], v[208:211], v[168:171], v[44:47]
	v_mfma_f32_16x16x32_bf16 v[36:39], v[200:203], v[176:179], v[36:39]
	v_mfma_f32_16x16x32_bf16 v[32:35], v[208:211], v[176:179], v[32:35]
	v_mfma_f32_16x16x32_bf16 v[20:23], v[200:203], v[184:187], v[20:23]
	v_mfma_f32_16x16x32_bf16 v[12:15], v[208:211], v[184:187], v[12:15]
	v_mfma_f32_16x16x32_bf16 v[4:7], v[200:203], v[192:195], v[4:7]
	v_mfma_f32_16x16x32_bf16 v[0:3], v[208:211], v[192:195], v[0:3]
	s_setprio 0
	s_add_i32 s74, s74, 2
	s_add_u32 s72, s72, 0x100
	s_addc_u32 s73, s73, 0
	s_cmp_gt_u32 s74, 41
	s_mov_b64 s[30:31], s[34:35]
	s_barrier
	.p2alignl 6, 3212836864

; #define PG8_STAGE(bufoff, gbase, voff) do { _Pragma("unroll") for (int _i = 0; _i < 2; ++_i) \
;         __builtin_amdgcn_global_load_lds((const unsigned*)((const char*)(gbase) + (voff)[_i]), (LAS unsigned*)(lds + (bufoff) + ldsw + _i * 8192), 16, 0, 0); } while (0)
; #define PG8_LDA(dst, b, h) do { _Pragma("unroll") for (int m = 0; m < 4; ++m) _Pragma("unroll") for (int k = 0; k < 2; ++k) dst[m][k] = *(const LAS bf16x8*)(lds + PG8_SA(b, h) + aoff + m * 2048 + k * 1024); } while (0)
; #define PG8_LDB(dst, b, h) do { _Pragma("unroll") for (int n = 0; n < 2; ++n) _Pragma("unroll") for (int k = 0; k < 2; ++k) dst[n][k] = *(const LAS bf16x8*)(lds + PG8_SB(b, h) + boff + n * 2048 + k * 1024); } while (0)
; #define PG8_MMA(ai, bj, At, Bt) do { __builtin_amdgcn_s_setprio(1); _Pragma("unroll") for (int m = 0; m < 4; ++m) _Pragma("unroll") for (int n = 0; n < 2; ++n) _Pragma("unroll") for (int k = 0; k < 2; ++k) \
;         acc[ai][bj][m][n] = __builtin_amdgcn_mfma_f32_16x16x32_bf16(Bt[n][k], At[m][k], acc[ai][bj][m][n], 0, 0, 0); __builtin_amdgcn_s_setprio(0); } while (0)
; #define PG8_WAIT_L(n) asm volatile("s_waitcnt lgkmcnt(" #n ")" ::: "memory")
; #define PG8_BAR __builtin_amdgcn_s_barrier()
; template <class Epi>
; __device__ __forceinline__ void gemm_phase(LAS unsigned char* lds, const Gemm g, const StaticOrder& S, const Epi& E) {
;     ...
;         const bool has_next = S.next(ui + 1, nxt);
;         const char* nA = has_next ? (const char*)g.A + (size_t)nxt.pm * tstepA + (size_t)(nxt.pn >> g.a_shift) * g.a_step : cA; const char* nB = has_next ? (const char*)g.Bt + (size_t)nxt.pn * tstepB : cB;
;         for (int t = 0; t < nt; t += 2) {
;             const bool last = (t == nt - 2);
;             const char* a1 = cA + (size_t)(t + 1) * kstep;
;             const char* a2 = last ? nA : cA + (size_t)(t + 2) * kstep; const char* b2 = last ? nB : cB + (size_t)(t + 2) * kstep;
;             const char* a3 = a2 + kstep; const char* b3 = b2 + kstep;
;             PG8_LDB(B0, 0, 0); PG8_SCHED; PG8_LDA(At, 0, 0); PG8_STAGE(PG8_SA(1, 1), a1 + hstepA, voffA);
;             PG8_WAIT_L(8); PG8_BAR; PG8_WAIT_L(0); PG8_MMA(0, 0, At, B0); PG8_BAR; PG8_SCHED;
;             PG8_LDB(B1, 0, 1); PG8_STAGE(PG8_SB(0, 0), b2, voffB);
;             PG8_BAR; PG8_WAIT_L(0); PG8_MMA(0, 1, At, B1); PG8_BAR;
;             PG8_LDA(At, 0, 1); PG8_STAGE(PG8_SA(0, 0), a2, voffA);
.LBB0_1582:
	s_ashr_i32 s25, s24, 31
	v_cmp_lt_i64_e32 vcc, s[12:13], v[162:163]
	s_lshl_b64 s[12:13], s[24:25], 19
	s_add_u32 s26, s66, s12
	s_addc_u32 s27, s67, s13
	s_and_b64 s[12:13], vcc, exec
	s_cselect_b32 s25, s27, s39
	s_cselect_b32 s31, s26, s38
	s_ashr_i32 s23, s22, 31
	s_lshl_b64 s[12:13], s[22:23], 19
	s_add_u32 s28, s5, s12
	s_addc_u32 s29, s6, s13
	s_and_b64 s[12:13], vcc, exec
	s_cselect_b32 s23, s29, s37
	s_cselect_b32 s35, s28, s36
	s_add_u32 s12, s38, 0x40080
	s_addc_u32 s13, s39, 0
	s_add_u32 s38, s36, 0x100
	s_addc_u32 s39, s37, 0
	s_mov_b32 s74, -2
	ds_read_b128 v[80:83], v180
	ds_read_b128 v[84:87], v180 offset:1024
	ds_read_b128 v[88:91], v180 offset:2048
	ds_read_b128 v[92:95], v180 offset:3072
	s_add_u32 s14, s12, 0xfffc0080
	s_addc_u32 s15, s13, -1
	s_cmp_eq_u32 s74, 12
	s_cselect_b32 s37, s25, s15
	s_cselect_b32 s36, s31, s14
	s_cselect_b32 s15, s23, s39
	s_cselect_b32 s14, s35, s38
	v_lshl_add_u64 v[210:211], s[12:13], 0, v[158:159]
	s_add_i32 m0, s8, 0xc000
	ds_read_b128 v[166:169], v181
	ds_read_b128 v[170:173], v181 offset:1024
	ds_read_b128 v[186:189], v181 offset:2048
	ds_read_b128 v[190:193], v181 offset:3072
	ds_read_b128 v[194:197], v181 offset:4096
	ds_read_b128 v[198:201], v181 offset:5120
	ds_read_b128 v[202:205], v181 offset:6144
	ds_read_b128 v[206:209], v181 offset:7168
	global_load_lds_dwordx4 v[210:211], off
	v_lshl_add_u64 v[210:211], s[12:13], 0, v[160:161]
	s_add_i32 m0, s8, 0xe000
	s_nop 0
	global_load_lds_dwordx4 v[210:211], off
	ds_read_b128 v[210:213], v182
	ds_read_b128 v[214:217], v182 offset:1024
	ds_read_b128 v[220:223], v182 offset:2048
	ds_read_b128 v[224:227], v182 offset:3072
	s_waitcnt lgkmcnt(0)
	s_barrier
	s_setprio 1
	v_mfma_f32_16x16x32_bf16 v[140:143], v[80:83], v[166:169], 0
	v_mfma_f32_16x16x32_bf16 v[136:139], v[88:91], v[166:169], 0
	v_mfma_f32_16x16x32_bf16 v[124:127], v[80:83], v[186:189], 0
	v_mfma_f32_16x16x32_bf16 v[120:123], v[88:91], v[186:189], 0
	v_mfma_f32_16x16x32_bf16 v[108:111], v[80:83], v[194:197], 0
	v_mfma_f32_16x16x32_bf16 v[104:107], v[88:91], v[194:197], 0
	v_mfma_f32_16x16x32_bf16 v[76:79], v[80:83], v[202:205], 0
	v_mfma_f32_16x16x32_bf16 v[72:75], v[88:91], v[202:205], 0
	v_mfma_f32_16x16x32_bf16 v[140:143], v[84:87], v[170:173], v[140:143]
	v_mfma_f32_16x16x32_bf16 v[136:139], v[92:95], v[170:173], v[136:139]
	v_mfma_f32_16x16x32_bf16 v[124:127], v[84:87], v[190:193], v[124:127]
	v_mfma_f32_16x16x32_bf16 v[120:123], v[92:95], v[190:193], v[120:123]
	v_mfma_f32_16x16x32_bf16 v[108:111], v[84:87], v[198:201], v[108:111]
	v_mfma_f32_16x16x32_bf16 v[104:107], v[92:95], v[198:201], v[104:107]
	v_mfma_f32_16x16x32_bf16 v[76:79], v[84:87], v[206:209], v[76:79]
	v_mfma_f32_16x16x32_bf16 v[72:75], v[92:95], v[206:209], v[72:75]
	v_mfma_f32_16x16x32_bf16 v[132:135], v[210:213], v[166:169], 0
	v_mfma_f32_16x16x32_bf16 v[128:131], v[220:223], v[166:169], 0
	v_mfma_f32_16x16x32_bf16 v[116:119], v[210:213], v[186:189], 0
	v_mfma_f32_16x16x32_bf16 v[112:115], v[220:223], v[186:189], 0
	v_mfma_f32_16x16x32_bf16 v[100:103], v[210:213], v[194:197], 0
	v_mfma_f32_16x16x32_bf16 v[96:99], v[220:223], v[194:197], 0
	v_mfma_f32_16x16x32_bf16 v[68:71], v[210:213], v[202:205], 0
	v_mfma_f32_16x16x32_bf16 v[64:67], v[220:223], v[202:205], 0
	v_mfma_f32_16x16x32_bf16 v[132:135], v[214:217], v[170:173], v[132:135]
	v_mfma_f32_16x16x32_bf16 v[128:131], v[224:227], v[170:173], v[128:131]
	v_mfma_f32_16x16x32_bf16 v[116:119], v[214:217], v[190:193], v[116:119]
	v_mfma_f32_16x16x32_bf16 v[112:115], v[224:227], v[190:193], v[112:115]
	v_mfma_f32_16x16x32_bf16 v[100:103], v[214:217], v[198:201], v[100:103]
	v_mfma_f32_16x16x32_bf16 v[96:99], v[224:227], v[198:201], v[96:99]
	v_mfma_f32_16x16x32_bf16 v[68:71], v[214:217], v[206:209], v[68:71]
	v_mfma_f32_16x16x32_bf16 v[64:67], v[224:227], v[206:209], v[64:67]
	s_setprio 0
	s_barrier
	s_nop 1
	ds_read_b128 v[166:169], v181 offset:16384
	ds_read_b128 v[170:173], v181 offset:17408
	ds_read_b128 v[186:189], v181 offset:18432
	ds_read_b128 v[190:193], v181 offset:19456
	ds_read_b128 v[194:197], v181 offset:20480
	ds_read_b128 v[198:201], v181 offset:21504
	ds_read_b128 v[202:205], v181 offset:22528
	ds_read_b128 v[206:209], v181 offset:23552
	s_add_i32 s75, s48, s7
	v_lshl_add_u64 v[228:229], s[14:15], 0, v[146:147]
	s_mov_b32 m0, s75
	s_nop 0
	global_load_lds_dwordx4 v[228:229], off
	v_lshl_add_u64 v[230:231], s[14:15], 0, v[150:151]
	s_add_i32 m0, s75, 0x2000
	s_nop 0
	global_load_lds_dwordx4 v[230:231], off
	s_mov_b32 m0, s8
	v_lshl_add_u64 v[232:233], s[36:37], 0, v[144:145]
	global_load_lds_dwordx4 v[232:233], off
	v_lshl_add_u64 v[236:237], s[36:37], 0, v[148:149]
	s_mov_b32 m0, s9
	s_nop 0
	global_load_lds_dwordx4 v[236:237], off
	s_add_u32 s76, s14, 0x40000
	s_addc_u32 s77, s15, 0
	s_add_i32 s75, s49, s7
	v_lshl_add_u64 v[254:255], s[76:77], 0, v[146:147]
	s_mov_b32 m0, s75
	s_nop 0
	global_load_lds_dwordx4 v[254:255], off
	v_lshl_add_u64 v[254:255], s[76:77], 0, v[150:151]
	s_add_i32 m0, s75, 0x2000
	s_nop 0
	global_load_lds_dwordx4 v[254:255], off
	s_waitcnt vmcnt(6)
	s_waitcnt lgkmcnt(0)
	s_barrier
; #define PG8_STAGE(bufoff, gbase, voff) do { _Pragma("unroll") for (int _i = 0; _i < 2; ++_i) \
;         __builtin_amdgcn_global_load_lds((const unsigned*)((const char*)(gbase) + (voff)[_i]), (LAS unsigned*)(lds + (bufoff) + ldsw + _i * 8192), 16, 0, 0); } while (0)
; #define PG8_LDA(dst, b, h) do { _Pragma("unroll") for (int m = 0; m < 4; ++m) _Pragma("unroll") for (int k = 0; k < 2; ++k) dst[m][k] = *(const LAS bf16x8*)(lds + PG8_SA(b, h) + aoff + m * 2048 + k * 1024); } while (0)
; #define PG8_LDB(dst, b, h) do { _Pragma("unroll") for (int n = 0; n < 2; ++n) _Pragma("unroll") for (int k = 0; k < 2; ++k) dst[n][k] = *(const LAS bf16x8*)(lds + PG8_SB(b, h) + boff + n * 2048 + k * 1024); } while (0)
; #define PG8_MMA(ai, bj, At, Bt) do { __builtin_amdgcn_s_setprio(1); _Pragma("unroll") for (int m = 0; m < 4; ++m) _Pragma("unroll") for (int n = 0; n < 2; ++n) _Pragma("unroll") for (int k = 0; k < 2; ++k) \
;         acc[ai][bj][m][n] = __builtin_amdgcn_mfma_f32_16x16x32_bf16(Bt[n][k], At[m][k], acc[ai][bj][m][n], 0, 0, 0); __builtin_amdgcn_s_setprio(0); } while (0)
; #define PG8_WAIT_V(n) asm volatile("s_waitcnt vmcnt(" #n ")" ::: "memory")
; #define PG8_WAIT_L(n) asm volatile("s_waitcnt lgkmcnt(" #n ")" ::: "memory")
; #define PG8_BAR __builtin_amdgcn_s_barrier()
; #define PG8_SCHED __builtin_amdgcn_sched_barrier(0)
; template <class Epi>
; __device__ __forceinline__ void gemm_phase(LAS unsigned char* lds, const Gemm g, const StaticOrder& S, const Epi& E) {
;     ...
;             PG8_BAR; PG8_WAIT_L(0); PG8_MMA(1, 0, At, B0); PG8_BAR; PG8_SCHED;
;             PG8_STAGE(PG8_SB(0, 1), b2 + hstepB, voffB);
;             PG8_WAIT_V(6); PG8_BAR; PG8_MMA(1, 1, At, B1); PG8_BAR;
;             PG8_LDB(B0, 1, 0); PG8_SCHED; PG8_LDA(At, 1, 0); PG8_STAGE(PG8_SA(0, 1), a2 + hstepA, voffA);
;             PG8_WAIT_L(8); PG8_BAR; PG8_WAIT_L(0); PG8_MMA(0, 0, At, B0); PG8_BAR; PG8_SCHED;
;             PG8_LDB(B1, 1, 1); PG8_STAGE(PG8_SB(1, 0), b3, voffB);
;             PG8_BAR; PG8_WAIT_L(0); PG8_MMA(0, 1, At, B1); PG8_BAR;
	s_setprio 1
	v_mfma_f32_16x16x32_bf16 v[60:63], v[80:83], v[166:169], 0
	v_mfma_f32_16x16x32_bf16 v[56:59], v[88:91], v[166:169], 0
	v_mfma_f32_16x16x32_bf16 v[44:47], v[80:83], v[186:189], 0
	v_mfma_f32_16x16x32_bf16 v[40:43], v[88:91], v[186:189], 0
	v_mfma_f32_16x16x32_bf16 v[28:31], v[80:83], v[194:197], 0
	v_mfma_f32_16x16x32_bf16 v[24:27], v[88:91], v[194:197], 0
	v_mfma_f32_16x16x32_bf16 v[12:15], v[80:83], v[202:205], 0
	v_mfma_f32_16x16x32_bf16 v[8:11], v[88:91], v[202:205], 0
	v_mfma_f32_16x16x32_bf16 v[60:63], v[84:87], v[170:173], v[60:63]
	v_mfma_f32_16x16x32_bf16 v[56:59], v[92:95], v[170:173], v[56:59]
	v_mfma_f32_16x16x32_bf16 v[44:47], v[84:87], v[190:193], v[44:47]
	v_mfma_f32_16x16x32_bf16 v[40:43], v[92:95], v[190:193], v[40:43]
	v_mfma_f32_16x16x32_bf16 v[28:31], v[84:87], v[198:201], v[28:31]
	v_mfma_f32_16x16x32_bf16 v[24:27], v[92:95], v[198:201], v[24:27]
	v_mfma_f32_16x16x32_bf16 v[12:15], v[84:87], v[206:209], v[12:15]
	v_mfma_f32_16x16x32_bf16 v[8:11], v[92:95], v[206:209], v[8:11]
	v_mfma_f32_16x16x32_bf16 v[52:55], v[210:213], v[166:169], 0
	v_mfma_f32_16x16x32_bf16 v[48:51], v[220:223], v[166:169], 0
	v_mfma_f32_16x16x32_bf16 v[36:39], v[210:213], v[186:189], 0
	v_mfma_f32_16x16x32_bf16 v[32:35], v[220:223], v[186:189], 0
	v_mfma_f32_16x16x32_bf16 v[20:23], v[210:213], v[194:197], 0
	v_mfma_f32_16x16x32_bf16 v[16:19], v[220:223], v[194:197], 0
	v_mfma_f32_16x16x32_bf16 v[4:7], v[210:213], v[202:205], 0
	v_mfma_f32_16x16x32_bf16 v[0:3], v[220:223], v[202:205], 0
	v_mfma_f32_16x16x32_bf16 v[52:55], v[214:217], v[170:173], v[52:55]
	v_mfma_f32_16x16x32_bf16 v[48:51], v[224:227], v[170:173], v[48:51]
	v_mfma_f32_16x16x32_bf16 v[36:39], v[214:217], v[190:193], v[36:39]
	v_mfma_f32_16x16x32_bf16 v[32:35], v[224:227], v[190:193], v[32:35]
	v_mfma_f32_16x16x32_bf16 v[20:23], v[214:217], v[198:201], v[20:23]
	v_mfma_f32_16x16x32_bf16 v[16:19], v[224:227], v[198:201], v[16:19]
	v_mfma_f32_16x16x32_bf16 v[4:7], v[214:217], v[206:209], v[4:7]
	v_mfma_f32_16x16x32_bf16 v[0:3], v[224:227], v[206:209], v[0:3]
	s_setprio 0
	s_add_i32 s75, 0, 0x18000
	v_add_u32_e32 v92, s75, v175
	s_barrier
	ds_read_b128 v[80:83], v92
	ds_read_b128 v[84:87], v92 offset:1024
	ds_read_b128 v[88:91], v92 offset:2048
	ds_read_b128 v[92:95], v92 offset:3072
	s_add_u32 s36, s36, 0x40000
	s_addc_u32 s37, s37, 0
	s_mov_b32 m0, s40
	v_lshl_add_u64 v[210:211], s[36:37], 0, v[144:145]
	ds_read_b128 v[166:169], v181 offset:32768
	ds_read_b128 v[170:173], v181 offset:33792
	ds_read_b128 v[186:189], v181 offset:34816
	ds_read_b128 v[190:193], v181 offset:35840
	ds_read_b128 v[194:197], v181 offset:36864
	ds_read_b128 v[198:201], v181 offset:37888
	ds_read_b128 v[202:205], v181 offset:38912
	ds_read_b128 v[206:209], v181 offset:39936
	global_load_lds_dwordx4 v[210:211], off
	v_lshl_add_u64 v[210:211], s[36:37], 0, v[148:149]
	s_mov_b32 m0, s41
	s_nop 0
	global_load_lds_dwordx4 v[210:211], off
	s_add_i32 s36, 0, 0x1c000
	v_add_u32_e32 v152, s36, v175
	ds_read_b128 v[210:213], v152
	ds_read_b128 v[214:217], v152 offset:1024
	ds_read_b128 v[220:223], v152 offset:2048
	ds_read_b128 v[224:227], v152 offset:3072
	s_waitcnt lgkmcnt(0)
	s_barrier
	s_setprio 1
	v_mfma_f32_16x16x32_bf16 v[140:143], v[80:83], v[166:169], v[140:143]
	v_mfma_f32_16x16x32_bf16 v[136:139], v[88:91], v[166:169], v[136:139]
	v_mfma_f32_16x16x32_bf16 v[124:127], v[80:83], v[186:189], v[124:127]
	v_mfma_f32_16x16x32_bf16 v[120:123], v[88:91], v[186:189], v[120:123]
	v_mfma_f32_16x16x32_bf16 v[108:111], v[80:83], v[194:197], v[108:111]
	v_mfma_f32_16x16x32_bf16 v[104:107], v[88:91], v[194:197], v[104:107]
	v_mfma_f32_16x16x32_bf16 v[76:79], v[80:83], v[202:205], v[76:79]
	v_mfma_f32_16x16x32_bf16 v[72:75], v[88:91], v[202:205], v[72:75]
	v_mfma_f32_16x16x32_bf16 v[140:143], v[84:87], v[170:173], v[140:143]
	v_mfma_f32_16x16x32_bf16 v[136:139], v[92:95], v[170:173], v[136:139]
	v_mfma_f32_16x16x32_bf16 v[124:127], v[84:87], v[190:193], v[124:127]
	v_mfma_f32_16x16x32_bf16 v[120:123], v[92:95], v[190:193], v[120:123]
	v_mfma_f32_16x16x32_bf16 v[108:111], v[84:87], v[198:201], v[108:111]
	v_mfma_f32_16x16x32_bf16 v[104:107], v[92:95], v[198:201], v[104:107]
	v_mfma_f32_16x16x32_bf16 v[76:79], v[84:87], v[206:209], v[76:79]
	v_mfma_f32_16x16x32_bf16 v[72:75], v[92:95], v[206:209], v[72:75]
	v_mfma_f32_16x16x32_bf16 v[132:135], v[210:213], v[166:169], v[132:135]
	v_mfma_f32_16x16x32_bf16 v[128:131], v[220:223], v[166:169], v[128:131]
	v_mfma_f32_16x16x32_bf16 v[116:119], v[210:213], v[186:189], v[116:119]
	v_mfma_f32_16x16x32_bf16 v[112:115], v[220:223], v[186:189], v[112:115]
	v_mfma_f32_16x16x32_bf16 v[100:103], v[210:213], v[194:197], v[100:103]
	v_mfma_f32_16x16x32_bf16 v[96:99], v[220:223], v[194:197], v[96:99]
	v_mfma_f32_16x16x32_bf16 v[68:71], v[210:213], v[202:205], v[68:71]
	v_mfma_f32_16x16x32_bf16 v[64:67], v[220:223], v[202:205], v[64:67]
	v_mfma_f32_16x16x32_bf16 v[132:135], v[214:217], v[170:173], v[132:135]
	v_mfma_f32_16x16x32_bf16 v[128:131], v[224:227], v[170:173], v[128:131]
	v_mfma_f32_16x16x32_bf16 v[116:119], v[214:217], v[190:193], v[116:119]
	v_mfma_f32_16x16x32_bf16 v[112:115], v[224:227], v[190:193], v[112:115]
	v_mfma_f32_16x16x32_bf16 v[100:103], v[214:217], v[198:201], v[100:103]
	v_mfma_f32_16x16x32_bf16 v[96:99], v[224:227], v[198:201], v[96:99]
	v_mfma_f32_16x16x32_bf16 v[68:71], v[214:217], v[206:209], v[68:71]
	v_mfma_f32_16x16x32_bf16 v[64:67], v[224:227], v[206:209], v[64:67]
	s_setprio 0
	s_barrier
; #define PG8_STAGE(bufoff, gbase, voff) do { _Pragma("unroll") for (int _i = 0; _i < 2; ++_i) \
;         __builtin_amdgcn_global_load_lds((const unsigned*)((const char*)(gbase) + (voff)[_i]), (LAS unsigned*)(lds + (bufoff) + ldsw + _i * 8192), 16, 0, 0); } while (0)
; #define PG8_LDA(dst, b, h) do { _Pragma("unroll") for (int m = 0; m < 4; ++m) _Pragma("unroll") for (int k = 0; k < 2; ++k) dst[m][k] = *(const LAS bf16x8*)(lds + PG8_SA(b, h) + aoff + m * 2048 + k * 1024); } while (0)
; #define PG8_MMA(ai, bj, At, Bt) do { __builtin_amdgcn_s_setprio(1); _Pragma("unroll") for (int m = 0; m < 4; ++m) _Pragma("unroll") for (int n = 0; n < 2; ++n) _Pragma("unroll") for (int k = 0; k < 2; ++k) \
;         acc[ai][bj][m][n] = __builtin_amdgcn_mfma_f32_16x16x32_bf16(Bt[n][k], At[m][k], acc[ai][bj][m][n], 0, 0, 0); __builtin_amdgcn_s_setprio(0); } while (0)
; #define PG8_WAIT_V(n) asm volatile("s_waitcnt vmcnt(" #n ")" ::: "memory")
; #define PG8_WAIT_L(n) asm volatile("s_waitcnt lgkmcnt(" #n ")" ::: "memory")
; #define PG8_BAR __builtin_amdgcn_s_barrier()
; #define PG8_SCHED __builtin_amdgcn_sched_barrier(0)
; template <class Epi>
; __device__ __forceinline__ void gemm_phase(LAS unsigned char* lds, const Gemm g, const StaticOrder& S, const Epi& E) {
;     ...
;             PG8_LDA(At, 1, 1); PG8_STAGE(PG8_SA(1, 0), a3, voffA);
;             PG8_BAR; PG8_WAIT_L(0); PG8_MMA(1, 0, At, B0); PG8_BAR; PG8_SCHED;
;             PG8_STAGE(PG8_SB(1, 1), b3 + hstepB, voffB);
;             PG8_WAIT_V(6); PG8_BAR; PG8_MMA(1, 1, At, B1); PG8_BAR;
	s_nop 1
	ds_read_b128 v[166:169], v181 offset:49152
	ds_read_b128 v[170:173], v181 offset:50176
	ds_read_b128 v[186:189], v181 offset:51200
	ds_read_b128 v[190:193], v181 offset:52224
	ds_read_b128 v[194:197], v181 offset:53248
	ds_read_b128 v[198:201], v181 offset:54272
	ds_read_b128 v[202:205], v181 offset:55296
	ds_read_b128 v[206:209], v181 offset:56320
	s_add_i32 s37, s75, s7
	v_lshl_add_u64 v[254:255], v[228:229], 0, s[16:17]
	s_mov_b32 m0, s37
	s_nop 0
	global_load_lds_dwordx4 v[254:255], off
	v_lshl_add_u64 v[254:255], v[230:231], 0, s[16:17]
	s_add_i32 m0, s37, 0x2000
	s_nop 0
	global_load_lds_dwordx4 v[254:255], off
	s_mov_b32 m0, s45
	v_lshl_add_u64 v[254:255], v[232:233], 0, s[16:17]
	global_load_lds_dwordx4 v[254:255], off
	v_lshl_add_u64 v[228:229], v[236:237], 0, s[16:17]
	s_mov_b32 m0, s46
	s_nop 0
	global_load_lds_dwordx4 v[228:229], off
	s_add_u32 s14, s14, 0x40080
	s_addc_u32 s15, s15, 0
	s_add_i32 s36, s36, s7
	v_lshl_add_u64 v[254:255], s[14:15], 0, v[146:147]
	s_mov_b32 m0, s36
	s_nop 0
	global_load_lds_dwordx4 v[254:255], off
	v_lshl_add_u64 v[254:255], s[14:15], 0, v[150:151]
	s_add_i32 m0, s36, 0x2000
	s_nop 0
	global_load_lds_dwordx4 v[254:255], off
	s_waitcnt vmcnt(6)
	s_waitcnt lgkmcnt(0)
	s_barrier
	s_setprio 1
	v_mfma_f32_16x16x32_bf16 v[60:63], v[80:83], v[166:169], v[60:63]
	v_mfma_f32_16x16x32_bf16 v[56:59], v[88:91], v[166:169], v[56:59]
	v_mfma_f32_16x16x32_bf16 v[44:47], v[80:83], v[186:189], v[44:47]
	v_mfma_f32_16x16x32_bf16 v[40:43], v[88:91], v[186:189], v[40:43]
	v_mfma_f32_16x16x32_bf16 v[28:31], v[80:83], v[194:197], v[28:31]
	v_mfma_f32_16x16x32_bf16 v[24:27], v[88:91], v[194:197], v[24:27]
	v_mfma_f32_16x16x32_bf16 v[12:15], v[80:83], v[202:205], v[12:15]
	v_mfma_f32_16x16x32_bf16 v[8:11], v[88:91], v[202:205], v[8:11]
	v_mfma_f32_16x16x32_bf16 v[60:63], v[84:87], v[170:173], v[60:63]
	v_mfma_f32_16x16x32_bf16 v[56:59], v[92:95], v[170:173], v[56:59]
	v_mfma_f32_16x16x32_bf16 v[44:47], v[84:87], v[190:193], v[44:47]
	v_mfma_f32_16x16x32_bf16 v[40:43], v[92:95], v[190:193], v[40:43]
	v_mfma_f32_16x16x32_bf16 v[28:31], v[84:87], v[198:201], v[28:31]
	v_mfma_f32_16x16x32_bf16 v[24:27], v[92:95], v[198:201], v[24:27]
	v_mfma_f32_16x16x32_bf16 v[12:15], v[84:87], v[206:209], v[12:15]
	v_mfma_f32_16x16x32_bf16 v[8:11], v[92:95], v[206:209], v[8:11]
	v_mfma_f32_16x16x32_bf16 v[52:55], v[210:213], v[166:169], v[52:55]
	v_mfma_f32_16x16x32_bf16 v[48:51], v[220:223], v[166:169], v[48:51]
	v_mfma_f32_16x16x32_bf16 v[36:39], v[210:213], v[186:189], v[36:39]
	v_mfma_f32_16x16x32_bf16 v[32:35], v[220:223], v[186:189], v[32:35]
	v_mfma_f32_16x16x32_bf16 v[20:23], v[210:213], v[194:197], v[20:23]
	v_mfma_f32_16x16x32_bf16 v[16:19], v[220:223], v[194:197], v[16:19]
	v_mfma_f32_16x16x32_bf16 v[4:7], v[210:213], v[202:205], v[4:7]
	v_mfma_f32_16x16x32_bf16 v[0:3], v[220:223], v[202:205], v[0:3]
	v_mfma_f32_16x16x32_bf16 v[52:55], v[214:217], v[170:173], v[52:55]
	v_mfma_f32_16x16x32_bf16 v[48:51], v[224:227], v[170:173], v[48:51]
	v_mfma_f32_16x16x32_bf16 v[36:39], v[214:217], v[190:193], v[36:39]
	v_mfma_f32_16x16x32_bf16 v[32:35], v[224:227], v[190:193], v[32:35]
	v_mfma_f32_16x16x32_bf16 v[20:23], v[214:217], v[198:201], v[20:23]
	v_mfma_f32_16x16x32_bf16 v[16:19], v[224:227], v[198:201], v[16:19]
	v_mfma_f32_16x16x32_bf16 v[4:7], v[214:217], v[206:209], v[4:7]
	v_mfma_f32_16x16x32_bf16 v[0:3], v[224:227], v[206:209], v[0:3]
	s_setprio 0
	s_add_i32 s74, s74, 2
	s_add_u32 s12, s12, 0x100
	s_addc_u32 s13, s13, 0
	s_add_u32 s38, s38, 0x100
	s_addc_u32 s39, s39, 0
	s_cmp_gt_u32 s74, 13
	s_barrier
	.p2alignl 6, 3212836864

; #define PG8_STAGE(bufoff, gbase, voff) do { _Pragma("unroll") for (int _i = 0; _i < 2; ++_i) \
;         __builtin_amdgcn_global_load_lds((const unsigned*)((const char*)(gbase) + (voff)[_i]), (LAS unsigned*)(lds + (bufoff) + ldsw + _i * 8192), 16, 0, 0); } while (0)
; #define PG8_LDA(dst, b, h) do { _Pragma("unroll") for (int m = 0; m < 4; ++m) _Pragma("unroll") for (int k = 0; k < 2; ++k) dst[m][k] = *(const LAS bf16x8*)(lds + PG8_SA(b, h) + aoff + m * 2048 + k * 1024); } while (0)
; #define PG8_LDB(dst, b, h) do { _Pragma("unroll") for (int n = 0; n < 2; ++n) _Pragma("unroll") for (int k = 0; k < 2; ++k) dst[n][k] = *(const LAS bf16x8*)(lds + PG8_SB(b, h) + boff + n * 2048 + k * 1024); } while (0)
; #define PG8_MMA(ai, bj, At, Bt) do { __builtin_amdgcn_s_setprio(1); _Pragma("unroll") for (int m = 0; m < 4; ++m) _Pragma("unroll") for (int n = 0; n < 2; ++n) _Pragma("unroll") for (int k = 0; k < 2; ++k) \
;         acc[ai][bj][m][n] = __builtin_amdgcn_mfma_f32_16x16x32_bf16(Bt[n][k], At[m][k], acc[ai][bj][m][n], 0, 0, 0); __builtin_amdgcn_s_setprio(0); } while (0)
; #define PG8_WAIT_L(n) asm volatile("s_waitcnt lgkmcnt(" #n ")" ::: "memory")
; #define PG8_BAR __builtin_amdgcn_s_barrier()
; template <class Epi>
; __device__ __forceinline__ void gemm_phase(LAS unsigned char* lds, const Gemm g, const StaticOrder& S, const Epi& E) {
;     ...
;         const bool has_next = S.next(ui + 1, nxt);
;         const char* nA = has_next ? (const char*)g.A + (size_t)nxt.pm * tstepA + (size_t)(nxt.pn >> g.a_shift) * g.a_step : cA; const char* nB = has_next ? (const char*)g.Bt + (size_t)nxt.pn * tstepB : cB;
;         for (int t = 0; t < nt; t += 2) {
;             const bool last = (t == nt - 2);
;             const char* a1 = cA + (size_t)(t + 1) * kstep;
;             const char* a2 = last ? nA : cA + (size_t)(t + 2) * kstep; const char* b2 = last ? nB : cB + (size_t)(t + 2) * kstep;
;             const char* a3 = a2 + kstep; const char* b3 = b2 + kstep;
;             PG8_LDB(B0, 0, 0); PG8_SCHED; PG8_LDA(At, 0, 0); PG8_STAGE(PG8_SA(1, 1), a1 + hstepA, voffA);
;             PG8_WAIT_L(8); PG8_BAR; PG8_WAIT_L(0); PG8_MMA(0, 0, At, B0); PG8_BAR; PG8_SCHED;
;             PG8_LDB(B1, 0, 1); PG8_STAGE(PG8_SB(0, 0), b2, voffB);
;             PG8_BAR; PG8_WAIT_L(0); PG8_MMA(0, 1, At, B1); PG8_BAR;
;             PG8_LDA(At, 0, 1); PG8_STAGE(PG8_SA(0, 0), a2, voffA);
.LBB0_1819:
	s_ashr_i32 s25, s24, 31
	v_cmp_lt_i64_e32 vcc, s[26:27], v[136:137]
	s_lshl_b64 s[26:27], s[24:25], 19
	s_add_u32 s26, s68, s26
	s_addc_u32 s27, s69, s27
	s_and_b64 s[28:29], vcc, exec
	s_cselect_b32 s25, s27, s35
	s_cselect_b32 s47, s26, s34
	s_ashr_i32 s23, s22, 31
	s_lshl_b64 s[28:29], s[22:23], 19
	s_add_u32 s28, s5, s28
	s_addc_u32 s29, s6, s29
	s_and_b64 s[38:39], vcc, exec
	s_cselect_b32 s23, s29, s37
	s_cselect_b32 s48, s28, s36
	s_add_u32 s34, s34, 0x40080
	s_addc_u32 s35, s35, 0
	s_add_u32 s49, s36, 0x100
	s_addc_u32 s63, s37, 0
	s_mov_b32 s70, -2
	ds_read_b128 v[140:143], v149
	ds_read_b128 v[152:155], v149 offset:1024
	ds_read_b128 v[156:159], v149 offset:2048
	ds_read_b128 v[160:163], v149 offset:3072
	s_add_u32 s36, s34, 0xfffc0080
	s_addc_u32 s37, s35, -1
	s_cmp_eq_u32 s70, 12
	s_cselect_b32 s39, s25, s37
	s_cselect_b32 s38, s47, s36
	s_cselect_b32 s37, s23, s63
	s_cselect_b32 s36, s48, s49
	v_lshl_add_u64 v[144:145], s[34:35], 0, v[132:133]
	s_add_i32 m0, s8, 0xc000
	ds_read_b128 v[164:167], v150
	ds_read_b128 v[168:171], v150 offset:1024
	ds_read_b128 v[172:175], v150 offset:2048
	ds_read_b128 v[176:179], v150 offset:3072
	ds_read_b128 v[180:183], v150 offset:4096
	ds_read_b128 v[184:187], v150 offset:5120
	ds_read_b128 v[188:191], v150 offset:6144
	ds_read_b128 v[192:195], v150 offset:7168
	global_load_lds_dwordx4 v[144:145], off
	v_lshl_add_u64 v[144:145], s[34:35], 0, v[134:135]
	s_add_i32 m0, s8, 0xe000
	s_nop 0
	global_load_lds_dwordx4 v[144:145], off
	ds_read_b128 v[196:199], v151
	ds_read_b128 v[200:203], v151 offset:1024
	ds_read_b128 v[204:207], v151 offset:2048
	ds_read_b128 v[208:211], v151 offset:3072
	s_waitcnt lgkmcnt(0)
	s_barrier
	s_setprio 1
	v_mfma_f32_16x16x32_bf16 v[124:127], v[140:143], v[164:167], 0
	v_mfma_f32_16x16x32_bf16 v[120:123], v[156:159], v[164:167], 0
	v_mfma_f32_16x16x32_bf16 v[112:115], v[140:143], v[172:175], 0
	v_mfma_f32_16x16x32_bf16 v[104:107], v[156:159], v[172:175], 0
	v_mfma_f32_16x16x32_bf16 v[92:95], v[140:143], v[180:183], 0
	v_mfma_f32_16x16x32_bf16 v[88:91], v[156:159], v[180:183], 0
	v_mfma_f32_16x16x32_bf16 v[80:83], v[140:143], v[188:191], 0
	v_mfma_f32_16x16x32_bf16 v[72:75], v[156:159], v[188:191], 0
	v_mfma_f32_16x16x32_bf16 v[124:127], v[152:155], v[168:171], v[124:127]
	v_mfma_f32_16x16x32_bf16 v[120:123], v[160:163], v[168:171], v[120:123]
	v_mfma_f32_16x16x32_bf16 v[112:115], v[152:155], v[176:179], v[112:115]
	v_mfma_f32_16x16x32_bf16 v[104:107], v[160:163], v[176:179], v[104:107]
	v_mfma_f32_16x16x32_bf16 v[92:95], v[152:155], v[184:187], v[92:95]
	v_mfma_f32_16x16x32_bf16 v[88:91], v[160:163], v[184:187], v[88:91]
	v_mfma_f32_16x16x32_bf16 v[80:83], v[152:155], v[192:195], v[80:83]
	v_mfma_f32_16x16x32_bf16 v[72:75], v[160:163], v[192:195], v[72:75]
	v_mfma_f32_16x16x32_bf16 v[116:119], v[196:199], v[164:167], 0
	v_mfma_f32_16x16x32_bf16 v[108:111], v[204:207], v[164:167], 0
	v_mfma_f32_16x16x32_bf16 v[100:103], v[196:199], v[172:175], 0
	v_mfma_f32_16x16x32_bf16 v[96:99], v[204:207], v[172:175], 0
	v_mfma_f32_16x16x32_bf16 v[84:87], v[196:199], v[180:183], 0
	v_mfma_f32_16x16x32_bf16 v[76:79], v[204:207], v[180:183], 0
	v_mfma_f32_16x16x32_bf16 v[68:71], v[196:199], v[188:191], 0
	v_mfma_f32_16x16x32_bf16 v[64:67], v[204:207], v[188:191], 0
	v_mfma_f32_16x16x32_bf16 v[116:119], v[200:203], v[168:171], v[116:119]
	v_mfma_f32_16x16x32_bf16 v[108:111], v[208:211], v[168:171], v[108:111]
	v_mfma_f32_16x16x32_bf16 v[100:103], v[200:203], v[176:179], v[100:103]
	v_mfma_f32_16x16x32_bf16 v[96:99], v[208:211], v[176:179], v[96:99]
	v_mfma_f32_16x16x32_bf16 v[84:87], v[200:203], v[184:187], v[84:87]
	v_mfma_f32_16x16x32_bf16 v[76:79], v[208:211], v[184:187], v[76:79]
	v_mfma_f32_16x16x32_bf16 v[68:71], v[200:203], v[192:195], v[68:71]
	v_mfma_f32_16x16x32_bf16 v[64:67], v[208:211], v[192:195], v[64:67]
	s_setprio 0
	s_barrier
	s_nop 1
	ds_read_b128 v[164:167], v150 offset:16384
	ds_read_b128 v[168:171], v150 offset:17408
	ds_read_b128 v[172:175], v150 offset:18432
	ds_read_b128 v[176:179], v150 offset:19456
	ds_read_b128 v[180:183], v150 offset:20480
	ds_read_b128 v[184:187], v150 offset:21504
	ds_read_b128 v[188:191], v150 offset:22528
	ds_read_b128 v[192:195], v150 offset:23552
	s_add_i32 s71, s44, s7
	v_lshl_add_u64 v[144:145], s[36:37], 0, v[128:129]
	s_mov_b32 m0, s71
	s_nop 0
	global_load_lds_dwordx4 v[144:145], off
	v_lshl_add_u64 v[212:213], s[36:37], 0, v[130:131]
	s_add_i32 m0, s71, 0x2000
	s_nop 0
	global_load_lds_dwordx4 v[212:213], off
	s_mov_b32 m0, s8
	v_lshl_add_u64 v[214:215], s[38:39], 0, v[128:129]
	global_load_lds_dwordx4 v[214:215], off
	v_lshl_add_u64 v[216:217], s[38:39], 0, v[130:131]
	s_mov_b32 m0, s9
	s_nop 0
	global_load_lds_dwordx4 v[216:217], off
	s_add_u32 s72, s36, 0x40000
	s_addc_u32 s73, s37, 0
	s_add_i32 s71, s45, s7
	v_lshl_add_u64 v[254:255], s[72:73], 0, v[128:129]
	s_mov_b32 m0, s71
	s_nop 0
	global_load_lds_dwordx4 v[254:255], off
	v_lshl_add_u64 v[254:255], s[72:73], 0, v[130:131]
	s_add_i32 m0, s71, 0x2000
	s_nop 0
	global_load_lds_dwordx4 v[254:255], off
	s_waitcnt vmcnt(6)
	s_waitcnt lgkmcnt(0)
	s_barrier
; #define PG8_STAGE(bufoff, gbase, voff) do { _Pragma("unroll") for (int _i = 0; _i < 2; ++_i) \
;         __builtin_amdgcn_global_load_lds((const unsigned*)((const char*)(gbase) + (voff)[_i]), (LAS unsigned*)(lds + (bufoff) + ldsw + _i * 8192), 16, 0, 0); } while (0)
; #define PG8_LDA(dst, b, h) do { _Pragma("unroll") for (int m = 0; m < 4; ++m) _Pragma("unroll") for (int k = 0; k < 2; ++k) dst[m][k] = *(const LAS bf16x8*)(lds + PG8_SA(b, h) + aoff + m * 2048 + k * 1024); } while (0)
; #define PG8_LDB(dst, b, h) do { _Pragma("unroll") for (int n = 0; n < 2; ++n) _Pragma("unroll") for (int k = 0; k < 2; ++k) dst[n][k] = *(const LAS bf16x8*)(lds + PG8_SB(b, h) + boff + n * 2048 + k * 1024); } while (0)
; #define PG8_MMA(ai, bj, At, Bt) do { __builtin_amdgcn_s_setprio(1); _Pragma("unroll") for (int m = 0; m < 4; ++m) _Pragma("unroll") for (int n = 0; n < 2; ++n) _Pragma("unroll") for (int k = 0; k < 2; ++k) \
;         acc[ai][bj][m][n] = __builtin_amdgcn_mfma_f32_16x16x32_bf16(Bt[n][k], At[m][k], acc[ai][bj][m][n], 0, 0, 0); __builtin_amdgcn_s_setprio(0); } while (0)
; #define PG8_WAIT_V(n) asm volatile("s_waitcnt vmcnt(" #n ")" ::: "memory")
; #define PG8_WAIT_L(n) asm volatile("s_waitcnt lgkmcnt(" #n ")" ::: "memory")
; #define PG8_BAR __builtin_amdgcn_s_barrier()
; #define PG8_SCHED __builtin_amdgcn_sched_barrier(0)
; template <class Epi>
; __device__ __forceinline__ void gemm_phase(LAS unsigned char* lds, const Gemm g, const StaticOrder& S, const Epi& E) {
;     ...
;             PG8_BAR; PG8_WAIT_L(0); PG8_MMA(1, 0, At, B0); PG8_BAR; PG8_SCHED;
;             PG8_STAGE(PG8_SB(0, 1), b2 + hstepB, voffB);
;             PG8_WAIT_V(6); PG8_BAR; PG8_MMA(1, 1, At, B1); PG8_BAR;
;             PG8_LDB(B0, 1, 0); PG8_SCHED; PG8_LDA(At, 1, 0); PG8_STAGE(PG8_SA(0, 1), a2 + hstepA, voffA);
;             PG8_WAIT_L(8); PG8_BAR; PG8_WAIT_L(0); PG8_MMA(0, 0, At, B0); PG8_BAR; PG8_SCHED;
;             PG8_LDB(B1, 1, 1); PG8_STAGE(PG8_SB(1, 0), b3, voffB);
;             PG8_BAR; PG8_WAIT_L(0); PG8_MMA(0, 1, At, B1); PG8_BAR;
	s_setprio 1
	v_mfma_f32_16x16x32_bf16 v[60:63], v[140:143], v[164:167], 0
	v_mfma_f32_16x16x32_bf16 v[56:59], v[156:159], v[164:167], 0
	v_mfma_f32_16x16x32_bf16 v[48:51], v[140:143], v[172:175], 0
	v_mfma_f32_16x16x32_bf16 v[40:43], v[156:159], v[172:175], 0
	v_mfma_f32_16x16x32_bf16 v[28:31], v[140:143], v[180:183], 0
	v_mfma_f32_16x16x32_bf16 v[24:27], v[156:159], v[180:183], 0
	v_mfma_f32_16x16x32_bf16 v[16:19], v[140:143], v[188:191], 0
	v_mfma_f32_16x16x32_bf16 v[8:11], v[156:159], v[188:191], 0
	v_mfma_f32_16x16x32_bf16 v[60:63], v[152:155], v[168:171], v[60:63]
	v_mfma_f32_16x16x32_bf16 v[56:59], v[160:163], v[168:171], v[56:59]
	v_mfma_f32_16x16x32_bf16 v[48:51], v[152:155], v[176:179], v[48:51]
	v_mfma_f32_16x16x32_bf16 v[40:43], v[160:163], v[176:179], v[40:43]
	v_mfma_f32_16x16x32_bf16 v[28:31], v[152:155], v[184:187], v[28:31]
	v_mfma_f32_16x16x32_bf16 v[24:27], v[160:163], v[184:187], v[24:27]
	v_mfma_f32_16x16x32_bf16 v[16:19], v[152:155], v[192:195], v[16:19]
	v_mfma_f32_16x16x32_bf16 v[8:11], v[160:163], v[192:195], v[8:11]
	v_mfma_f32_16x16x32_bf16 v[52:55], v[196:199], v[164:167], 0
	v_mfma_f32_16x16x32_bf16 v[44:47], v[204:207], v[164:167], 0
	v_mfma_f32_16x16x32_bf16 v[36:39], v[196:199], v[172:175], 0
	v_mfma_f32_16x16x32_bf16 v[32:35], v[204:207], v[172:175], 0
	v_mfma_f32_16x16x32_bf16 v[20:23], v[196:199], v[180:183], 0
	v_mfma_f32_16x16x32_bf16 v[12:15], v[204:207], v[180:183], 0
	v_mfma_f32_16x16x32_bf16 v[4:7], v[196:199], v[188:191], 0
	v_mfma_f32_16x16x32_bf16 v[0:3], v[204:207], v[188:191], 0
	v_mfma_f32_16x16x32_bf16 v[52:55], v[200:203], v[168:171], v[52:55]
	v_mfma_f32_16x16x32_bf16 v[44:47], v[208:211], v[168:171], v[44:47]
	v_mfma_f32_16x16x32_bf16 v[36:39], v[200:203], v[176:179], v[36:39]
	v_mfma_f32_16x16x32_bf16 v[32:35], v[208:211], v[176:179], v[32:35]
	v_mfma_f32_16x16x32_bf16 v[20:23], v[200:203], v[184:187], v[20:23]
	v_mfma_f32_16x16x32_bf16 v[12:15], v[208:211], v[184:187], v[12:15]
	v_mfma_f32_16x16x32_bf16 v[4:7], v[200:203], v[192:195], v[4:7]
	v_mfma_f32_16x16x32_bf16 v[0:3], v[208:211], v[192:195], v[0:3]
	s_setprio 0
	s_add_i32 s71, 0, 0x18000
	v_add_u32_e32 v160, s71, v147
	s_barrier
	ds_read_b128 v[140:143], v160
	ds_read_b128 v[152:155], v160 offset:1024
	ds_read_b128 v[156:159], v160 offset:2048
	ds_read_b128 v[160:163], v160 offset:3072
	s_add_u32 s38, s38, 0x40000
	s_addc_u32 s39, s39, 0
	s_mov_b32 m0, s31
	v_lshl_add_u64 v[196:197], s[38:39], 0, v[128:129]
	ds_read_b128 v[164:167], v150 offset:32768
	ds_read_b128 v[168:171], v150 offset:33792
	ds_read_b128 v[172:175], v150 offset:34816
	ds_read_b128 v[176:179], v150 offset:35840
	ds_read_b128 v[180:183], v150 offset:36864
	ds_read_b128 v[184:187], v150 offset:37888
	ds_read_b128 v[188:191], v150 offset:38912
	ds_read_b128 v[192:195], v150 offset:39936
	global_load_lds_dwordx4 v[196:197], off
	v_lshl_add_u64 v[196:197], s[38:39], 0, v[130:131]
	s_mov_b32 m0, s40
	s_nop 0
	global_load_lds_dwordx4 v[196:197], off
	s_add_i32 s38, 0, 0x1c000
	v_add_u32_e32 v208, s38, v147
	ds_read_b128 v[196:199], v208
	ds_read_b128 v[200:203], v208 offset:1024
	ds_read_b128 v[204:207], v208 offset:2048
	ds_read_b128 v[208:211], v208 offset:3072
	s_waitcnt lgkmcnt(0)
	s_barrier
	s_setprio 1
	v_mfma_f32_16x16x32_bf16 v[124:127], v[140:143], v[164:167], v[124:127]
	v_mfma_f32_16x16x32_bf16 v[120:123], v[156:159], v[164:167], v[120:123]
	v_mfma_f32_16x16x32_bf16 v[112:115], v[140:143], v[172:175], v[112:115]
	v_mfma_f32_16x16x32_bf16 v[104:107], v[156:159], v[172:175], v[104:107]
	v_mfma_f32_16x16x32_bf16 v[92:95], v[140:143], v[180:183], v[92:95]
	v_mfma_f32_16x16x32_bf16 v[88:91], v[156:159], v[180:183], v[88:91]
	v_mfma_f32_16x16x32_bf16 v[80:83], v[140:143], v[188:191], v[80:83]
	v_mfma_f32_16x16x32_bf16 v[72:75], v[156:159], v[188:191], v[72:75]
	v_mfma_f32_16x16x32_bf16 v[124:127], v[152:155], v[168:171], v[124:127]
	v_mfma_f32_16x16x32_bf16 v[120:123], v[160:163], v[168:171], v[120:123]
	v_mfma_f32_16x16x32_bf16 v[112:115], v[152:155], v[176:179], v[112:115]
	v_mfma_f32_16x16x32_bf16 v[104:107], v[160:163], v[176:179], v[104:107]
	v_mfma_f32_16x16x32_bf16 v[92:95], v[152:155], v[184:187], v[92:95]
	v_mfma_f32_16x16x32_bf16 v[88:91], v[160:163], v[184:187], v[88:91]
	v_mfma_f32_16x16x32_bf16 v[80:83], v[152:155], v[192:195], v[80:83]
	v_mfma_f32_16x16x32_bf16 v[72:75], v[160:163], v[192:195], v[72:75]
	v_mfma_f32_16x16x32_bf16 v[116:119], v[196:199], v[164:167], v[116:119]
	v_mfma_f32_16x16x32_bf16 v[108:111], v[204:207], v[164:167], v[108:111]
	v_mfma_f32_16x16x32_bf16 v[100:103], v[196:199], v[172:175], v[100:103]
	v_mfma_f32_16x16x32_bf16 v[96:99], v[204:207], v[172:175], v[96:99]
	v_mfma_f32_16x16x32_bf16 v[84:87], v[196:199], v[180:183], v[84:87]
	v_mfma_f32_16x16x32_bf16 v[76:79], v[204:207], v[180:183], v[76:79]
	v_mfma_f32_16x16x32_bf16 v[68:71], v[196:199], v[188:191], v[68:71]
	v_mfma_f32_16x16x32_bf16 v[64:67], v[204:207], v[188:191], v[64:67]
	v_mfma_f32_16x16x32_bf16 v[116:119], v[200:203], v[168:171], v[116:119]
	v_mfma_f32_16x16x32_bf16 v[108:111], v[208:211], v[168:171], v[108:111]
	v_mfma_f32_16x16x32_bf16 v[100:103], v[200:203], v[176:179], v[100:103]
	v_mfma_f32_16x16x32_bf16 v[96:99], v[208:211], v[176:179], v[96:99]
	v_mfma_f32_16x16x32_bf16 v[84:87], v[200:203], v[184:187], v[84:87]
	v_mfma_f32_16x16x32_bf16 v[76:79], v[208:211], v[184:187], v[76:79]
	v_mfma_f32_16x16x32_bf16 v[68:71], v[200:203], v[192:195], v[68:71]
	v_mfma_f32_16x16x32_bf16 v[64:67], v[208:211], v[192:195], v[64:67]
	s_setprio 0
	s_barrier
; #define PG8_STAGE(bufoff, gbase, voff) do { _Pragma("unroll") for (int _i = 0; _i < 2; ++_i) \
;         __builtin_amdgcn_global_load_lds((const unsigned*)((const char*)(gbase) + (voff)[_i]), (LAS unsigned*)(lds + (bufoff) + ldsw + _i * 8192), 16, 0, 0); } while (0)
; #define PG8_LDA(dst, b, h) do { _Pragma("unroll") for (int m = 0; m < 4; ++m) _Pragma("unroll") for (int k = 0; k < 2; ++k) dst[m][k] = *(const LAS bf16x8*)(lds + PG8_SA(b, h) + aoff + m * 2048 + k * 1024); } while (0)
; #define PG8_MMA(ai, bj, At, Bt) do { __builtin_amdgcn_s_setprio(1); _Pragma("unroll") for (int m = 0; m < 4; ++m) _Pragma("unroll") for (int n = 0; n < 2; ++n) _Pragma("unroll") for (int k = 0; k < 2; ++k) \
;         acc[ai][bj][m][n] = __builtin_amdgcn_mfma_f32_16x16x32_bf16(Bt[n][k], At[m][k], acc[ai][bj][m][n], 0, 0, 0); __builtin_amdgcn_s_setprio(0); } while (0)
; #define PG8_WAIT_V(n) asm volatile("s_waitcnt vmcnt(" #n ")" ::: "memory")
; #define PG8_WAIT_L(n) asm volatile("s_waitcnt lgkmcnt(" #n ")" ::: "memory")
; #define PG8_BAR __builtin_amdgcn_s_barrier()
; #define PG8_SCHED __builtin_amdgcn_sched_barrier(0)
; template <class Epi>
; __device__ __forceinline__ void gemm_phase(LAS unsigned char* lds, const Gemm g, const StaticOrder& S, const Epi& E) {
;     ...
;             PG8_LDA(At, 1, 1); PG8_STAGE(PG8_SA(1, 0), a3, voffA);
;             PG8_BAR; PG8_WAIT_L(0); PG8_MMA(1, 0, At, B0); PG8_BAR; PG8_SCHED;
;             PG8_STAGE(PG8_SB(1, 1), b3 + hstepB, voffB);
;             PG8_WAIT_V(6); PG8_BAR; PG8_MMA(1, 1, At, B1); PG8_BAR;
	s_nop 1
	ds_read_b128 v[164:167], v150 offset:49152
	ds_read_b128 v[168:171], v150 offset:50176
	ds_read_b128 v[172:175], v150 offset:51200
	ds_read_b128 v[176:179], v150 offset:52224
	ds_read_b128 v[180:183], v150 offset:53248
	ds_read_b128 v[184:187], v150 offset:54272
	ds_read_b128 v[188:191], v150 offset:55296
	ds_read_b128 v[192:195], v150 offset:56320
	s_add_i32 s39, s71, s7
	v_lshl_add_u64 v[254:255], v[144:145], 0, s[12:13]
	s_mov_b32 m0, s39
	s_nop 0
	global_load_lds_dwordx4 v[254:255], off
	v_lshl_add_u64 v[254:255], v[212:213], 0, s[12:13]
	s_add_i32 m0, s39, 0x2000
	s_nop 0
	global_load_lds_dwordx4 v[254:255], off
	s_mov_b32 m0, s42
	v_lshl_add_u64 v[254:255], v[214:215], 0, s[12:13]
	global_load_lds_dwordx4 v[254:255], off
	v_lshl_add_u64 v[144:145], v[216:217], 0, s[12:13]
	s_mov_b32 m0, s43
	s_nop 0
	global_load_lds_dwordx4 v[144:145], off
	s_add_u32 s36, s36, 0x40080
	s_addc_u32 s37, s37, 0
	s_add_i32 s38, s38, s7
	v_lshl_add_u64 v[254:255], s[36:37], 0, v[128:129]
	s_mov_b32 m0, s38
	s_nop 0
	global_load_lds_dwordx4 v[254:255], off
	v_lshl_add_u64 v[254:255], s[36:37], 0, v[130:131]
	s_add_i32 m0, s38, 0x2000
	s_nop 0
	global_load_lds_dwordx4 v[254:255], off
	s_waitcnt vmcnt(6)
	s_waitcnt lgkmcnt(0)
	s_barrier
	s_setprio 1
	v_mfma_f32_16x16x32_bf16 v[60:63], v[140:143], v[164:167], v[60:63]
	v_mfma_f32_16x16x32_bf16 v[56:59], v[156:159], v[164:167], v[56:59]
	v_mfma_f32_16x16x32_bf16 v[48:51], v[140:143], v[172:175], v[48:51]
	v_mfma_f32_16x16x32_bf16 v[40:43], v[156:159], v[172:175], v[40:43]
	v_mfma_f32_16x16x32_bf16 v[28:31], v[140:143], v[180:183], v[28:31]
	v_mfma_f32_16x16x32_bf16 v[24:27], v[156:159], v[180:183], v[24:27]
	v_mfma_f32_16x16x32_bf16 v[16:19], v[140:143], v[188:191], v[16:19]
	v_mfma_f32_16x16x32_bf16 v[8:11], v[156:159], v[188:191], v[8:11]
	v_mfma_f32_16x16x32_bf16 v[60:63], v[152:155], v[168:171], v[60:63]
	v_mfma_f32_16x16x32_bf16 v[56:59], v[160:163], v[168:171], v[56:59]
	v_mfma_f32_16x16x32_bf16 v[48:51], v[152:155], v[176:179], v[48:51]
	v_mfma_f32_16x16x32_bf16 v[40:43], v[160:163], v[176:179], v[40:43]
	v_mfma_f32_16x16x32_bf16 v[28:31], v[152:155], v[184:187], v[28:31]
	v_mfma_f32_16x16x32_bf16 v[24:27], v[160:163], v[184:187], v[24:27]
	v_mfma_f32_16x16x32_bf16 v[16:19], v[152:155], v[192:195], v[16:19]
	v_mfma_f32_16x16x32_bf16 v[8:11], v[160:163], v[192:195], v[8:11]
	v_mfma_f32_16x16x32_bf16 v[52:55], v[196:199], v[164:167], v[52:55]
	v_mfma_f32_16x16x32_bf16 v[44:47], v[204:207], v[164:167], v[44:47]
	v_mfma_f32_16x16x32_bf16 v[36:39], v[196:199], v[172:175], v[36:39]
	v_mfma_f32_16x16x32_bf16 v[32:35], v[204:207], v[172:175], v[32:35]
	v_mfma_f32_16x16x32_bf16 v[20:23], v[196:199], v[180:183], v[20:23]
	v_mfma_f32_16x16x32_bf16 v[12:15], v[204:207], v[180:183], v[12:15]
	v_mfma_f32_16x16x32_bf16 v[4:7], v[196:199], v[188:191], v[4:7]
	v_mfma_f32_16x16x32_bf16 v[0:3], v[204:207], v[188:191], v[0:3]
	v_mfma_f32_16x16x32_bf16 v[52:55], v[200:203], v[168:171], v[52:55]
	v_mfma_f32_16x16x32_bf16 v[44:47], v[208:211], v[168:171], v[44:47]
	v_mfma_f32_16x16x32_bf16 v[36:39], v[200:203], v[176:179], v[36:39]
	v_mfma_f32_16x16x32_bf16 v[32:35], v[208:211], v[176:179], v[32:35]
	v_mfma_f32_16x16x32_bf16 v[20:23], v[200:203], v[184:187], v[20:23]
	v_mfma_f32_16x16x32_bf16 v[12:15], v[208:211], v[184:187], v[12:15]
	v_mfma_f32_16x16x32_bf16 v[4:7], v[200:203], v[192:195], v[4:7]
	v_mfma_f32_16x16x32_bf16 v[0:3], v[208:211], v[192:195], v[0:3]
	s_setprio 0
	s_add_i32 s70, s70, 2
	s_add_u32 s34, s34, 0x100
	s_addc_u32 s35, s35, 0
	s_add_u32 s49, s49, 0x100
	s_addc_u32 s63, s63, 0
	s_cmp_gt_u32 s70, 13
	s_barrier
	.p2alignl 6, 3212836864

; #define PG8_STAGE(bufoff, gbase, voff) do { _Pragma("unroll") for (int _i = 0; _i < 2; ++_i) \
;         __builtin_amdgcn_global_load_lds((const unsigned*)((const char*)(gbase) + (voff)[_i]), (LAS unsigned*)(lds + (bufoff) + ldsw + _i * 8192), 16, 0, 0); } while (0)
; #define PG8_LDA(dst, b, h) do { _Pragma("unroll") for (int m = 0; m < 4; ++m) _Pragma("unroll") for (int k = 0; k < 2; ++k) dst[m][k] = *(const LAS bf16x8*)(lds + PG8_SA(b, h) + aoff + m * 2048 + k * 1024); } while (0)
; #define PG8_LDB(dst, b, h) do { _Pragma("unroll") for (int n = 0; n < 2; ++n) _Pragma("unroll") for (int k = 0; k < 2; ++k) dst[n][k] = *(const LAS bf16x8*)(lds + PG8_SB(b, h) + boff + n * 2048 + k * 1024); } while (0)
; #define PG8_MMA(ai, bj, At, Bt) do { __builtin_amdgcn_s_setprio(1); _Pragma("unroll") for (int m = 0; m < 4; ++m) _Pragma("unroll") for (int n = 0; n < 2; ++n) _Pragma("unroll") for (int k = 0; k < 2; ++k) \
;         acc[ai][bj][m][n] = __builtin_amdgcn_mfma_f32_16x16x32_bf16(Bt[n][k], At[m][k], acc[ai][bj][m][n], 0, 0, 0); __builtin_amdgcn_s_setprio(0); } while (0)
; #define PG8_WAIT_L(n) asm volatile("s_waitcnt lgkmcnt(" #n ")" ::: "memory")
; #define PG8_BAR __builtin_amdgcn_s_barrier()
; template <class Epi>
; __device__ __forceinline__ void gemm_phase(LAS unsigned char* lds, const Gemm g, const StaticOrder& S, const Epi& E) {
;     ...
;         const bool has_next = S.next(ui + 1, nxt);
;         const char* nA = has_next ? (const char*)g.A + (size_t)nxt.pm * tstepA + (size_t)(nxt.pn >> g.a_shift) * g.a_step : cA; const char* nB = has_next ? (const char*)g.Bt + (size_t)nxt.pn * tstepB : cB;
;         for (int t = 0; t < nt; t += 2) {
;             const bool last = (t == nt - 2);
;             const char* a1 = cA + (size_t)(t + 1) * kstep;
;             const char* a2 = last ? nA : cA + (size_t)(t + 2) * kstep; const char* b2 = last ? nB : cB + (size_t)(t + 2) * kstep;
;             const char* a3 = a2 + kstep; const char* b3 = b2 + kstep;
;             PG8_LDB(B0, 0, 0); PG8_SCHED; PG8_LDA(At, 0, 0); PG8_STAGE(PG8_SA(1, 1), a1 + hstepA, voffA);
;             PG8_WAIT_L(8); PG8_BAR; PG8_WAIT_L(0); PG8_MMA(0, 0, At, B0); PG8_BAR; PG8_SCHED;
;             PG8_LDB(B1, 0, 1); PG8_STAGE(PG8_SB(0, 0), b2, voffB);
;             PG8_BAR; PG8_WAIT_L(0); PG8_MMA(0, 1, At, B1); PG8_BAR;
;             PG8_LDA(At, 0, 1); PG8_STAGE(PG8_SA(0, 0), a2, voffA);
.LBB0_1939:
	s_ashr_i32 s27, s26, 31
	v_cmp_lt_i64_e32 vcc, s[28:29], v[228:229]
	s_lshl_b64 s[28:29], s[26:27], 19
	s_add_u32 s28, s66, s28
	s_addc_u32 s29, s67, s29
	s_and_b64 s[30:31], vcc, exec
	s_cselect_b32 s27, s29, s37
	s_cselect_b32 s68, s28, s36
	s_ashr_i32 s25, s24, 31
	s_lshl_b64 s[30:31], s[24:25], 19
	s_add_u32 s30, s5, s30
	s_addc_u32 s31, s6, s31
	s_and_b64 s[40:41], vcc, exec
	s_cselect_b32 s25, s31, s39
	s_cselect_b32 s69, s30, s38
	s_add_u32 s70, s38, 0x100
	s_addc_u32 s71, s39, 0
	s_mov_b32 s72, -2
	ds_read_b128 v[96:99], v242
	ds_read_b128 v[100:103], v242 offset:1024
	ds_read_b128 v[104:107], v242 offset:2048
	ds_read_b128 v[108:111], v242 offset:3072
	s_add_u32 s38, s36, 0x100
	s_addc_u32 s39, s37, 0
	s_cmp_eq_u32 s72, 12
	s_cselect_b32 s43, s27, s39
	s_cselect_b32 s42, s68, s38
	s_cselect_b32 s41, s25, s71
	s_cselect_b32 s40, s69, s70
	v_lshl_add_u64 v[176:177], s[36:37], 0, v[224:225]
	s_add_i32 m0, s45, 0xc000
	ds_read_b128 v[112:115], v243
	ds_read_b128 v[116:119], v243 offset:1024
	ds_read_b128 v[120:123], v243 offset:2048
	ds_read_b128 v[124:127], v243 offset:3072
	ds_read_b128 v[160:163], v243 offset:4096
	ds_read_b128 v[164:167], v243 offset:5120
	ds_read_b128 v[168:171], v243 offset:6144
	ds_read_b128 v[172:175], v243 offset:7168
	global_load_lds_dwordx4 v[176:177], off
	v_lshl_add_u64 v[176:177], s[36:37], 0, v[226:227]
	s_add_i32 m0, s45, 0xe000
	s_nop 0
	global_load_lds_dwordx4 v[176:177], off
	ds_read_b128 v[176:179], v244
	ds_read_b128 v[180:183], v244 offset:1024
	ds_read_b128 v[184:187], v244 offset:2048
	ds_read_b128 v[188:191], v244 offset:3072
	s_waitcnt lgkmcnt(0)
	s_barrier
	s_setprio 1
	v_mfma_f32_16x16x32_bf16 v[156:159], v[96:99], v[112:115], 0
	v_mfma_f32_16x16x32_bf16 v[60:63], v[104:107], v[112:115], 0
	v_mfma_f32_16x16x32_bf16 v[144:147], v[96:99], v[120:123], 0
	v_mfma_f32_16x16x32_bf16 v[48:51], v[104:107], v[120:123], 0
	v_mfma_f32_16x16x32_bf16 v[136:139], v[96:99], v[160:163], 0
	v_mfma_f32_16x16x32_bf16 v[40:43], v[104:107], v[160:163], 0
	v_mfma_f32_16x16x32_bf16 v[148:151], v[96:99], v[168:171], 0
	v_mfma_f32_16x16x32_bf16 v[52:55], v[104:107], v[168:171], 0
	v_mfma_f32_16x16x32_bf16 v[156:159], v[100:103], v[116:119], v[156:159]
	v_mfma_f32_16x16x32_bf16 v[60:63], v[108:111], v[116:119], v[60:63]
	v_mfma_f32_16x16x32_bf16 v[144:147], v[100:103], v[124:127], v[144:147]
	v_mfma_f32_16x16x32_bf16 v[48:51], v[108:111], v[124:127], v[48:51]
	v_mfma_f32_16x16x32_bf16 v[136:139], v[100:103], v[164:167], v[136:139]
	v_mfma_f32_16x16x32_bf16 v[40:43], v[108:111], v[164:167], v[40:43]
	v_mfma_f32_16x16x32_bf16 v[148:151], v[100:103], v[172:175], v[148:151]
	v_mfma_f32_16x16x32_bf16 v[52:55], v[108:111], v[172:175], v[52:55]
	v_mfma_f32_16x16x32_bf16 v[152:155], v[176:179], v[112:115], 0
	v_mfma_f32_16x16x32_bf16 v[56:59], v[184:187], v[112:115], 0
	v_mfma_f32_16x16x32_bf16 v[36:39], v[184:187], v[120:123], 0
	v_mfma_f32_16x16x32_bf16 v[32:35], v[184:187], v[160:163], 0
	v_mfma_f32_16x16x32_bf16 v[44:47], v[184:187], v[168:171], 0
	v_mfma_f32_16x16x32_bf16 v[152:155], v[180:183], v[116:119], v[152:155]
	v_mfma_f32_16x16x32_bf16 v[56:59], v[188:191], v[116:119], v[56:59]
	v_mfma_f32_16x16x32_bf16 v[112:115], v[176:179], v[120:123], 0
	v_mfma_f32_16x16x32_bf16 v[36:39], v[188:191], v[124:127], v[36:39]
	v_mfma_f32_16x16x32_bf16 v[116:119], v[176:179], v[160:163], 0
	v_mfma_f32_16x16x32_bf16 v[32:35], v[188:191], v[164:167], v[32:35]
	v_mfma_f32_16x16x32_bf16 v[120:123], v[176:179], v[168:171], 0
	v_mfma_f32_16x16x32_bf16 v[44:47], v[188:191], v[172:175], v[44:47]
	v_mfma_f32_16x16x32_bf16 v[112:115], v[180:183], v[124:127], v[112:115]
	v_mfma_f32_16x16x32_bf16 v[116:119], v[180:183], v[164:167], v[116:119]
	v_mfma_f32_16x16x32_bf16 v[120:123], v[180:183], v[172:175], v[120:123]
	s_setprio 0
	s_barrier
	s_nop 1
	ds_read_b128 v[124:127], v243 offset:16384
	ds_read_b128 v[128:131], v243 offset:17408
	ds_read_b128 v[132:135], v243 offset:18432
	ds_read_b128 v[140:143], v243 offset:19456
	ds_read_b128 v[160:163], v243 offset:20480
	ds_read_b128 v[164:167], v243 offset:21504
	ds_read_b128 v[168:171], v243 offset:22528
	ds_read_b128 v[172:175], v243 offset:23552
	s_add_i32 s36, s59, s7
	v_lshl_add_u64 v[196:197], s[40:41], 0, v[214:215]
	s_mov_b32 m0, s36
	s_nop 0
	global_load_lds_dwordx4 v[196:197], off
	v_lshl_add_u64 v[198:199], s[40:41], 0, v[210:211]
	s_add_i32 m0, s36, 0x2000
	s_nop 0
	global_load_lds_dwordx4 v[198:199], off
	s_mov_b32 m0, s45
	v_lshl_add_u64 v[200:201], s[42:43], 0, v[216:217]
	global_load_lds_dwordx4 v[200:201], off
	v_lshl_add_u64 v[202:203], s[42:43], 0, v[212:213]
	s_mov_b32 m0, s46
	s_nop 0
	global_load_lds_dwordx4 v[202:203], off
	s_add_u32 s36, s40, 0x40000
	s_addc_u32 s37, s41, 0
	s_add_i32 s73, s62, s7
	v_lshl_add_u64 v[254:255], s[36:37], 0, v[214:215]
	s_mov_b32 m0, s73
	s_nop 0
	global_load_lds_dwordx4 v[254:255], off
	v_lshl_add_u64 v[254:255], s[36:37], 0, v[210:211]
	s_add_i32 m0, s73, 0x2000
	s_nop 0
	global_load_lds_dwordx4 v[254:255], off
	s_waitcnt vmcnt(6)
	s_waitcnt lgkmcnt(0)
	s_barrier
; #define PG8_STAGE(bufoff, gbase, voff) do { _Pragma("unroll") for (int _i = 0; _i < 2; ++_i) \
;         __builtin_amdgcn_global_load_lds((const unsigned*)((const char*)(gbase) + (voff)[_i]), (LAS unsigned*)(lds + (bufoff) + ldsw + _i * 8192), 16, 0, 0); } while (0)
; #define PG8_LDA(dst, b, h) do { _Pragma("unroll") for (int m = 0; m < 4; ++m) _Pragma("unroll") for (int k = 0; k < 2; ++k) dst[m][k] = *(const LAS bf16x8*)(lds + PG8_SA(b, h) + aoff + m * 2048 + k * 1024); } while (0)
; #define PG8_LDB(dst, b, h) do { _Pragma("unroll") for (int n = 0; n < 2; ++n) _Pragma("unroll") for (int k = 0; k < 2; ++k) dst[n][k] = *(const LAS bf16x8*)(lds + PG8_SB(b, h) + boff + n * 2048 + k * 1024); } while (0)
; #define PG8_MMA(ai, bj, At, Bt) do { __builtin_amdgcn_s_setprio(1); _Pragma("unroll") for (int m = 0; m < 4; ++m) _Pragma("unroll") for (int n = 0; n < 2; ++n) _Pragma("unroll") for (int k = 0; k < 2; ++k) \
;         acc[ai][bj][m][n] = __builtin_amdgcn_mfma_f32_16x16x32_bf16(Bt[n][k], At[m][k], acc[ai][bj][m][n], 0, 0, 0); __builtin_amdgcn_s_setprio(0); } while (0)
; #define PG8_WAIT_V(n) asm volatile("s_waitcnt vmcnt(" #n ")" ::: "memory")
; #define PG8_WAIT_L(n) asm volatile("s_waitcnt lgkmcnt(" #n ")" ::: "memory")
; #define PG8_BAR __builtin_amdgcn_s_barrier()
; #define PG8_SCHED __builtin_amdgcn_sched_barrier(0)
; template <class Epi>
; __device__ __forceinline__ void gemm_phase(LAS unsigned char* lds, const Gemm g, const StaticOrder& S, const Epi& E) {
;     ...
;             PG8_BAR; PG8_WAIT_L(0); PG8_MMA(1, 0, At, B0); PG8_BAR; PG8_SCHED;
;             PG8_STAGE(PG8_SB(0, 1), b2 + hstepB, voffB);
;             PG8_WAIT_V(6); PG8_BAR; PG8_MMA(1, 1, At, B1); PG8_BAR;
;             PG8_LDB(B0, 1, 0); PG8_SCHED; PG8_LDA(At, 1, 0); PG8_STAGE(PG8_SA(0, 1), a2 + hstepA, voffA);
;             PG8_WAIT_L(8); PG8_BAR; PG8_WAIT_L(0); PG8_MMA(0, 0, At, B0); PG8_BAR; PG8_SCHED;
;             PG8_LDB(B1, 1, 1); PG8_STAGE(PG8_SB(1, 0), b3, voffB);
;             PG8_BAR; PG8_WAIT_L(0); PG8_MMA(0, 1, At, B1); PG8_BAR;
	s_setprio 1
	v_mfma_f32_16x16x32_bf16 v[92:95], v[96:99], v[124:127], 0
	v_mfma_f32_16x16x32_bf16 v[28:31], v[104:107], v[124:127], 0
	v_mfma_f32_16x16x32_bf16 v[80:83], v[96:99], v[132:135], 0
	v_mfma_f32_16x16x32_bf16 v[16:19], v[104:107], v[132:135], 0
	v_mfma_f32_16x16x32_bf16 v[76:79], v[96:99], v[160:163], 0
	v_mfma_f32_16x16x32_bf16 v[12:15], v[104:107], v[160:163], 0
	v_mfma_f32_16x16x32_bf16 v[84:87], v[96:99], v[168:171], 0
	v_mfma_f32_16x16x32_bf16 v[20:23], v[104:107], v[168:171], 0
	v_mfma_f32_16x16x32_bf16 v[92:95], v[100:103], v[128:131], v[92:95]
	v_mfma_f32_16x16x32_bf16 v[28:31], v[108:111], v[128:131], v[28:31]
	v_mfma_f32_16x16x32_bf16 v[80:83], v[100:103], v[140:143], v[80:83]
	v_mfma_f32_16x16x32_bf16 v[16:19], v[108:111], v[140:143], v[16:19]
	v_mfma_f32_16x16x32_bf16 v[76:79], v[100:103], v[164:167], v[76:79]
	v_mfma_f32_16x16x32_bf16 v[12:15], v[108:111], v[164:167], v[12:15]
	v_mfma_f32_16x16x32_bf16 v[84:87], v[100:103], v[172:175], v[84:87]
	v_mfma_f32_16x16x32_bf16 v[20:23], v[108:111], v[172:175], v[20:23]
	v_mfma_f32_16x16x32_bf16 v[88:91], v[176:179], v[124:127], 0
	v_mfma_f32_16x16x32_bf16 v[24:27], v[184:187], v[124:127], 0
	v_mfma_f32_16x16x32_bf16 v[68:71], v[176:179], v[132:135], 0
	v_mfma_f32_16x16x32_bf16 v[4:7], v[184:187], v[132:135], 0
	v_mfma_f32_16x16x32_bf16 v[64:67], v[176:179], v[160:163], 0
	v_mfma_f32_16x16x32_bf16 v[0:3], v[184:187], v[160:163], 0
	v_mfma_f32_16x16x32_bf16 v[72:75], v[176:179], v[168:171], 0
	v_mfma_f32_16x16x32_bf16 v[8:11], v[184:187], v[168:171], 0
	v_mfma_f32_16x16x32_bf16 v[88:91], v[180:183], v[128:131], v[88:91]
	v_mfma_f32_16x16x32_bf16 v[24:27], v[188:191], v[128:131], v[24:27]
	v_mfma_f32_16x16x32_bf16 v[68:71], v[180:183], v[140:143], v[68:71]
	v_mfma_f32_16x16x32_bf16 v[4:7], v[188:191], v[140:143], v[4:7]
	v_mfma_f32_16x16x32_bf16 v[64:67], v[180:183], v[164:167], v[64:67]
	v_mfma_f32_16x16x32_bf16 v[0:3], v[188:191], v[164:167], v[0:3]
	v_mfma_f32_16x16x32_bf16 v[72:75], v[180:183], v[172:175], v[72:75]
	v_mfma_f32_16x16x32_bf16 v[8:11], v[188:191], v[172:175], v[8:11]
	s_setprio 0
	s_add_i32 s73, 0, 0x18000
	v_add_u32_e32 v108, s73, v234
	s_barrier
	ds_read_b128 v[96:99], v108
	ds_read_b128 v[100:103], v108 offset:1024
	ds_read_b128 v[104:107], v108 offset:2048
	ds_read_b128 v[108:111], v108 offset:3072
	s_add_u32 s36, s42, 0x40000
	s_addc_u32 s37, s43, 0
	s_mov_b32 m0, s47
	v_lshl_add_u64 v[132:133], s[36:37], 0, v[216:217]
	ds_read_b128 v[124:127], v243 offset:32768
	ds_read_b128 v[128:131], v243 offset:33792
	ds_read_b128 v[140:143], v243 offset:34816
	ds_read_b128 v[160:163], v243 offset:35840
	ds_read_b128 v[164:167], v243 offset:36864
	ds_read_b128 v[168:171], v243 offset:37888
	ds_read_b128 v[172:175], v243 offset:38912
	ds_read_b128 v[176:179], v243 offset:39936
	global_load_lds_dwordx4 v[132:133], off
	v_lshl_add_u64 v[132:133], s[36:37], 0, v[212:213]
	s_mov_b32 m0, s48
	s_nop 0
	global_load_lds_dwordx4 v[132:133], off
	s_add_i32 s42, 0, 0x1c000
	v_add_u32_e32 v132, s42, v234
	ds_read_b128 v[180:183], v132
	ds_read_b128 v[184:187], v132 offset:1024
	ds_read_b128 v[188:191], v132 offset:2048
	ds_read_b128 v[192:195], v132 offset:3072
	s_waitcnt lgkmcnt(0)
	s_barrier
	s_setprio 1
	v_mfma_f32_16x16x32_bf16 v[132:135], v[96:99], v[124:127], v[156:159]
	v_mfma_f32_16x16x32_bf16 v[156:159], v[100:103], v[128:131], v[132:135]
	v_mfma_f32_16x16x32_bf16 v[132:135], v[96:99], v[140:143], v[144:147]
	v_mfma_f32_16x16x32_bf16 v[144:147], v[100:103], v[160:163], v[132:135]
	v_mfma_f32_16x16x32_bf16 v[132:135], v[96:99], v[164:167], v[136:139]
	v_mfma_f32_16x16x32_bf16 v[60:63], v[104:107], v[124:127], v[60:63]
	v_mfma_f32_16x16x32_bf16 v[48:51], v[104:107], v[140:143], v[48:51]
	v_mfma_f32_16x16x32_bf16 v[136:139], v[100:103], v[168:171], v[132:135]
	v_mfma_f32_16x16x32_bf16 v[40:43], v[104:107], v[164:167], v[40:43]
	v_mfma_f32_16x16x32_bf16 v[132:135], v[96:99], v[172:175], v[148:151]
	v_mfma_f32_16x16x32_bf16 v[52:55], v[104:107], v[172:175], v[52:55]
	v_mfma_f32_16x16x32_bf16 v[60:63], v[108:111], v[128:131], v[60:63]
	v_mfma_f32_16x16x32_bf16 v[48:51], v[108:111], v[160:163], v[48:51]
	v_mfma_f32_16x16x32_bf16 v[40:43], v[108:111], v[168:171], v[40:43]
	v_mfma_f32_16x16x32_bf16 v[148:151], v[100:103], v[176:179], v[132:135]
	v_mfma_f32_16x16x32_bf16 v[52:55], v[108:111], v[176:179], v[52:55]
	v_mfma_f32_16x16x32_bf16 v[132:135], v[180:183], v[124:127], v[152:155]
	v_mfma_f32_16x16x32_bf16 v[112:115], v[180:183], v[140:143], v[112:115]
	v_mfma_f32_16x16x32_bf16 v[152:155], v[184:187], v[128:131], v[132:135]
	v_mfma_f32_16x16x32_bf16 v[56:59], v[188:191], v[124:127], v[56:59]
	v_mfma_f32_16x16x32_bf16 v[132:135], v[184:187], v[160:163], v[112:115]
	v_mfma_f32_16x16x32_bf16 v[112:115], v[180:183], v[164:167], v[116:119]
	v_mfma_f32_16x16x32_bf16 v[56:59], v[192:195], v[128:131], v[56:59]
	v_mfma_f32_16x16x32_bf16 v[36:39], v[188:191], v[140:143], v[36:39]
	v_mfma_f32_16x16x32_bf16 v[128:131], v[184:187], v[168:171], v[112:115]
	v_mfma_f32_16x16x32_bf16 v[32:35], v[188:191], v[164:167], v[32:35]
	v_mfma_f32_16x16x32_bf16 v[112:115], v[180:183], v[172:175], v[120:123]
	v_mfma_f32_16x16x32_bf16 v[44:47], v[188:191], v[172:175], v[44:47]
	v_mfma_f32_16x16x32_bf16 v[36:39], v[192:195], v[160:163], v[36:39]
	v_mfma_f32_16x16x32_bf16 v[32:35], v[192:195], v[168:171], v[32:35]
	v_mfma_f32_16x16x32_bf16 v[140:143], v[184:187], v[176:179], v[112:115]
	v_mfma_f32_16x16x32_bf16 v[44:47], v[192:195], v[176:179], v[44:47]
	s_setprio 0
	s_barrier
; #define PG8_STAGE(bufoff, gbase, voff) do { _Pragma("unroll") for (int _i = 0; _i < 2; ++_i) \
;         __builtin_amdgcn_global_load_lds((const unsigned*)((const char*)(gbase) + (voff)[_i]), (LAS unsigned*)(lds + (bufoff) + ldsw + _i * 8192), 16, 0, 0); } while (0)
; #define PG8_LDA(dst, b, h) do { _Pragma("unroll") for (int m = 0; m < 4; ++m) _Pragma("unroll") for (int k = 0; k < 2; ++k) dst[m][k] = *(const LAS bf16x8*)(lds + PG8_SA(b, h) + aoff + m * 2048 + k * 1024); } while (0)
; #define PG8_MMA(ai, bj, At, Bt) do { __builtin_amdgcn_s_setprio(1); _Pragma("unroll") for (int m = 0; m < 4; ++m) _Pragma("unroll") for (int n = 0; n < 2; ++n) _Pragma("unroll") for (int k = 0; k < 2; ++k) \
;         acc[ai][bj][m][n] = __builtin_amdgcn_mfma_f32_16x16x32_bf16(Bt[n][k], At[m][k], acc[ai][bj][m][n], 0, 0, 0); __builtin_amdgcn_s_setprio(0); } while (0)
; #define PG8_WAIT_V(n) asm volatile("s_waitcnt vmcnt(" #n ")" ::: "memory")
; #define PG8_WAIT_L(n) asm volatile("s_waitcnt lgkmcnt(" #n ")" ::: "memory")
; #define PG8_BAR __builtin_amdgcn_s_barrier()
; #define PG8_SCHED __builtin_amdgcn_sched_barrier(0)
; template <class Epi>
; __device__ __forceinline__ void gemm_phase(LAS unsigned char* lds, const Gemm g, const StaticOrder& S, const Epi& E) {
;     ...
;             PG8_LDA(At, 1, 1); PG8_STAGE(PG8_SA(1, 0), a3, voffA);
;             PG8_BAR; PG8_WAIT_L(0); PG8_MMA(1, 0, At, B0); PG8_BAR; PG8_SCHED;
;             PG8_STAGE(PG8_SB(1, 1), b3 + hstepB, voffB);
;             PG8_WAIT_V(6); PG8_BAR; PG8_MMA(1, 1, At, B1); PG8_BAR;
	s_nop 1
	ds_read_b128 v[112:115], v243 offset:49152
	ds_read_b128 v[116:119], v243 offset:50176
	ds_read_b128 v[120:123], v243 offset:51200
	ds_read_b128 v[124:127], v243 offset:52224
	ds_read_b128 v[160:163], v243 offset:53248
	ds_read_b128 v[164:167], v243 offset:54272
	ds_read_b128 v[168:171], v243 offset:55296
	ds_read_b128 v[172:175], v243 offset:56320
	s_add_i32 s36, s73, s7
	v_lshl_add_u64 v[254:255], v[196:197], 0, s[16:17]
	s_mov_b32 m0, s36
	s_nop 0
	global_load_lds_dwordx4 v[254:255], off
	v_lshl_add_u64 v[254:255], v[198:199], 0, s[16:17]
	s_add_i32 m0, s36, 0x2000
	s_nop 0
	global_load_lds_dwordx4 v[254:255], off
	s_mov_b32 m0, s57
	v_lshl_add_u64 v[254:255], v[200:201], 0, s[16:17]
	global_load_lds_dwordx4 v[254:255], off
	v_lshl_add_u64 v[254:255], v[202:203], 0, s[16:17]
	s_mov_b32 m0, s58
	s_nop 0
	global_load_lds_dwordx4 v[254:255], off
	s_add_u32 s36, s40, 0x40080
	s_addc_u32 s37, s41, 0
	s_add_i32 s40, s42, s7
	v_lshl_add_u64 v[254:255], s[36:37], 0, v[214:215]
	s_mov_b32 m0, s40
	s_nop 0
	global_load_lds_dwordx4 v[254:255], off
	v_lshl_add_u64 v[254:255], s[36:37], 0, v[210:211]
	s_add_i32 m0, s40, 0x2000
	s_nop 0
	global_load_lds_dwordx4 v[254:255], off
	s_waitcnt vmcnt(6)
	s_waitcnt lgkmcnt(0)
	s_barrier
	s_setprio 1
	v_mfma_f32_16x16x32_bf16 v[92:95], v[96:99], v[112:115], v[92:95]
	v_mfma_f32_16x16x32_bf16 v[28:31], v[104:107], v[112:115], v[28:31]
	v_mfma_f32_16x16x32_bf16 v[80:83], v[96:99], v[120:123], v[80:83]
	v_mfma_f32_16x16x32_bf16 v[16:19], v[104:107], v[120:123], v[16:19]
	v_mfma_f32_16x16x32_bf16 v[76:79], v[96:99], v[160:163], v[76:79]
	v_mfma_f32_16x16x32_bf16 v[12:15], v[104:107], v[160:163], v[12:15]
	v_mfma_f32_16x16x32_bf16 v[84:87], v[96:99], v[168:171], v[84:87]
	v_mfma_f32_16x16x32_bf16 v[20:23], v[104:107], v[168:171], v[20:23]
	v_mfma_f32_16x16x32_bf16 v[92:95], v[100:103], v[116:119], v[92:95]
	v_mfma_f32_16x16x32_bf16 v[28:31], v[108:111], v[116:119], v[28:31]
	v_mfma_f32_16x16x32_bf16 v[80:83], v[100:103], v[124:127], v[80:83]
	v_mfma_f32_16x16x32_bf16 v[16:19], v[108:111], v[124:127], v[16:19]
	v_mfma_f32_16x16x32_bf16 v[76:79], v[100:103], v[164:167], v[76:79]
	v_mfma_f32_16x16x32_bf16 v[12:15], v[108:111], v[164:167], v[12:15]
	v_mfma_f32_16x16x32_bf16 v[84:87], v[100:103], v[172:175], v[84:87]
	v_mfma_f32_16x16x32_bf16 v[20:23], v[108:111], v[172:175], v[20:23]
	v_mfma_f32_16x16x32_bf16 v[88:91], v[180:183], v[112:115], v[88:91]
	v_mfma_f32_16x16x32_bf16 v[24:27], v[188:191], v[112:115], v[24:27]
	v_mfma_f32_16x16x32_bf16 v[68:71], v[180:183], v[120:123], v[68:71]
	v_mfma_f32_16x16x32_bf16 v[4:7], v[188:191], v[120:123], v[4:7]
	v_mfma_f32_16x16x32_bf16 v[64:67], v[180:183], v[160:163], v[64:67]
	v_mfma_f32_16x16x32_bf16 v[0:3], v[188:191], v[160:163], v[0:3]
	v_mfma_f32_16x16x32_bf16 v[72:75], v[180:183], v[168:171], v[72:75]
	v_mfma_f32_16x16x32_bf16 v[8:11], v[188:191], v[168:171], v[8:11]
	v_mfma_f32_16x16x32_bf16 v[88:91], v[184:187], v[116:119], v[88:91]
	v_mfma_f32_16x16x32_bf16 v[24:27], v[192:195], v[116:119], v[24:27]
	v_mfma_f32_16x16x32_bf16 v[68:71], v[184:187], v[124:127], v[68:71]
	v_mfma_f32_16x16x32_bf16 v[4:7], v[192:195], v[124:127], v[4:7]
	v_mfma_f32_16x16x32_bf16 v[64:67], v[184:187], v[164:167], v[64:67]
	v_mfma_f32_16x16x32_bf16 v[0:3], v[192:195], v[164:167], v[0:3]
	v_mfma_f32_16x16x32_bf16 v[72:75], v[184:187], v[172:175], v[72:75]
	v_mfma_f32_16x16x32_bf16 v[8:11], v[192:195], v[172:175], v[8:11]
	s_setprio 0
	s_add_i32 s72, s72, 2
	s_add_u32 s70, s70, 0x100
	s_addc_u32 s71, s71, 0
	s_cmp_gt_u32 s72, 13
	s_mov_b64 s[36:37], s[38:39]
	s_barrier
	.p2alignl 6, 3212836864

; #define PG8_STAGE(bufoff, gbase, voff) do { _Pragma("unroll") for (int _i = 0; _i < 2; ++_i) \
;         __builtin_amdgcn_global_load_lds((const unsigned*)((const char*)(gbase) + (voff)[_i]), (LAS unsigned*)(lds + (bufoff) + ldsw + _i * 8192), 16, 0, 0); } while (0)
; #define PG8_LDA(dst, b, h) do { _Pragma("unroll") for (int m = 0; m < 4; ++m) _Pragma("unroll") for (int k = 0; k < 2; ++k) dst[m][k] = *(const LAS bf16x8*)(lds + PG8_SA(b, h) + aoff + m * 2048 + k * 1024); } while (0)
; #define PG8_LDB(dst, b, h) do { _Pragma("unroll") for (int n = 0; n < 2; ++n) _Pragma("unroll") for (int k = 0; k < 2; ++k) dst[n][k] = *(const LAS bf16x8*)(lds + PG8_SB(b, h) + boff + n * 2048 + k * 1024); } while (0)
; #define PG8_MMA(ai, bj, At, Bt) do { __builtin_amdgcn_s_setprio(1); _Pragma("unroll") for (int m = 0; m < 4; ++m) _Pragma("unroll") for (int n = 0; n < 2; ++n) _Pragma("unroll") for (int k = 0; k < 2; ++k) \
;         acc[ai][bj][m][n] = __builtin_amdgcn_mfma_f32_16x16x32_bf16(Bt[n][k], At[m][k], acc[ai][bj][m][n], 0, 0, 0); __builtin_amdgcn_s_setprio(0); } while (0)
; #define PG8_WAIT_L(n) asm volatile("s_waitcnt lgkmcnt(" #n ")" ::: "memory")
; #define PG8_BAR __builtin_amdgcn_s_barrier()
; #define PG8_SCHED __builtin_amdgcn_sched_barrier(0)
; template <class Epi>
; __device__ __forceinline__ void gemm_phase(LAS unsigned char* lds, const Gemm g, const StaticOrder& S, const Epi& E) {
;     ...
;             const bool last = (t == nt - 2);
;             const char* a1 = cA + (size_t)(t + 1) * kstep;
;             const char* a2 = last ? nA : cA + (size_t)(t + 2) * kstep; const char* b2 = last ? nB : cB + (size_t)(t + 2) * kstep;
;             const char* a3 = a2 + kstep; const char* b3 = b2 + kstep;
;             PG8_LDB(B0, 0, 0); PG8_SCHED; PG8_LDA(At, 0, 0); PG8_STAGE(PG8_SA(1, 1), a1 + hstepA, voffA);
;             PG8_WAIT_L(8); PG8_BAR; PG8_WAIT_L(0); PG8_MMA(0, 0, At, B0); PG8_BAR; PG8_SCHED;
;             PG8_LDB(B1, 0, 1); PG8_STAGE(PG8_SB(0, 0), b2, voffB);
;             PG8_BAR; PG8_WAIT_L(0); PG8_MMA(0, 1, At, B1); PG8_BAR;
;             PG8_LDA(At, 0, 1); PG8_STAGE(PG8_SA(0, 0), a2, voffA);
.LBB0_2041:
	s_add_u32 s44, s20, 0x100
	s_addc_u32 s45, s21, 0
	s_mov_b32 s46, -2
	ds_read_b128 v[140:143], v149
	ds_read_b128 v[152:155], v149 offset:1024
	ds_read_b128 v[156:159], v149 offset:2048
	ds_read_b128 v[160:163], v149 offset:3072
	s_add_u32 s20, s18, 0x100
	s_addc_u32 s21, s19, 0
	s_cmp_eq_u32 s46, 40
	s_cselect_b32 s25, s5, s21
	s_cselect_b32 s24, s4, s20
	s_cselect_b32 s23, s7, s45
	s_cselect_b32 s22, s6, s44
	v_lshl_add_u64 v[144:145], s[18:19], 0, v[132:133]
	s_add_i32 m0, s30, 0xc000
	ds_read_b128 v[164:167], v150
	ds_read_b128 v[168:171], v150 offset:1024
	ds_read_b128 v[172:175], v150 offset:2048
	ds_read_b128 v[176:179], v150 offset:3072
	ds_read_b128 v[180:183], v150 offset:4096
	ds_read_b128 v[184:187], v150 offset:5120
	ds_read_b128 v[188:191], v150 offset:6144
	ds_read_b128 v[192:195], v150 offset:7168
	global_load_lds_dwordx4 v[144:145], off
	v_lshl_add_u64 v[144:145], s[18:19], 0, v[134:135]
	s_add_i32 m0, s30, 0xe000
	s_nop 0
	global_load_lds_dwordx4 v[144:145], off
	ds_read_b128 v[196:199], v151
	ds_read_b128 v[200:203], v151 offset:1024
	ds_read_b128 v[204:207], v151 offset:2048
	ds_read_b128 v[208:211], v151 offset:3072
	s_waitcnt lgkmcnt(0)
	s_barrier
	s_setprio 1
	v_mfma_f32_16x16x32_bf16 v[124:127], v[140:143], v[164:167], 0
	v_mfma_f32_16x16x32_bf16 v[120:123], v[156:159], v[164:167], 0
	v_mfma_f32_16x16x32_bf16 v[112:115], v[140:143], v[172:175], 0
	v_mfma_f32_16x16x32_bf16 v[104:107], v[156:159], v[172:175], 0
	v_mfma_f32_16x16x32_bf16 v[92:95], v[140:143], v[180:183], 0
	v_mfma_f32_16x16x32_bf16 v[88:91], v[156:159], v[180:183], 0
	v_mfma_f32_16x16x32_bf16 v[80:83], v[140:143], v[188:191], 0
	v_mfma_f32_16x16x32_bf16 v[72:75], v[156:159], v[188:191], 0
	v_mfma_f32_16x16x32_bf16 v[124:127], v[152:155], v[168:171], v[124:127]
	v_mfma_f32_16x16x32_bf16 v[120:123], v[160:163], v[168:171], v[120:123]
	v_mfma_f32_16x16x32_bf16 v[112:115], v[152:155], v[176:179], v[112:115]
	v_mfma_f32_16x16x32_bf16 v[104:107], v[160:163], v[176:179], v[104:107]
	v_mfma_f32_16x16x32_bf16 v[92:95], v[152:155], v[184:187], v[92:95]
	v_mfma_f32_16x16x32_bf16 v[88:91], v[160:163], v[184:187], v[88:91]
	v_mfma_f32_16x16x32_bf16 v[80:83], v[152:155], v[192:195], v[80:83]
	v_mfma_f32_16x16x32_bf16 v[72:75], v[160:163], v[192:195], v[72:75]
	v_mfma_f32_16x16x32_bf16 v[116:119], v[196:199], v[164:167], 0
	v_mfma_f32_16x16x32_bf16 v[108:111], v[204:207], v[164:167], 0
	v_mfma_f32_16x16x32_bf16 v[100:103], v[196:199], v[172:175], 0
	v_mfma_f32_16x16x32_bf16 v[96:99], v[204:207], v[172:175], 0
	v_mfma_f32_16x16x32_bf16 v[84:87], v[196:199], v[180:183], 0
	v_mfma_f32_16x16x32_bf16 v[76:79], v[204:207], v[180:183], 0
	v_mfma_f32_16x16x32_bf16 v[68:71], v[196:199], v[188:191], 0
	v_mfma_f32_16x16x32_bf16 v[64:67], v[204:207], v[188:191], 0
	v_mfma_f32_16x16x32_bf16 v[116:119], v[200:203], v[168:171], v[116:119]
	v_mfma_f32_16x16x32_bf16 v[108:111], v[208:211], v[168:171], v[108:111]
	v_mfma_f32_16x16x32_bf16 v[100:103], v[200:203], v[176:179], v[100:103]
	v_mfma_f32_16x16x32_bf16 v[96:99], v[208:211], v[176:179], v[96:99]
	v_mfma_f32_16x16x32_bf16 v[84:87], v[200:203], v[184:187], v[84:87]
	v_mfma_f32_16x16x32_bf16 v[76:79], v[208:211], v[184:187], v[76:79]
	v_mfma_f32_16x16x32_bf16 v[68:71], v[200:203], v[192:195], v[68:71]
	v_mfma_f32_16x16x32_bf16 v[64:67], v[208:211], v[192:195], v[64:67]
	s_setprio 0
	s_barrier
	s_nop 1
	ds_read_b128 v[164:167], v150 offset:16384
	ds_read_b128 v[168:171], v150 offset:17408
	ds_read_b128 v[172:175], v150 offset:18432
	ds_read_b128 v[176:179], v150 offset:19456
	ds_read_b128 v[180:183], v150 offset:20480
	ds_read_b128 v[184:187], v150 offset:21504
	ds_read_b128 v[188:191], v150 offset:22528
	ds_read_b128 v[192:195], v150 offset:23552
	s_add_i32 s18, s38, s29
	v_lshl_add_u64 v[144:145], s[22:23], 0, v[128:129]
	s_mov_b32 m0, s18
	s_nop 0
	global_load_lds_dwordx4 v[144:145], off
	v_lshl_add_u64 v[212:213], s[22:23], 0, v[130:131]
	s_add_i32 m0, s18, 0x2000
	s_nop 0
	global_load_lds_dwordx4 v[212:213], off
	s_mov_b32 m0, s30
	v_lshl_add_u64 v[214:215], s[24:25], 0, v[128:129]
	global_load_lds_dwordx4 v[214:215], off
	v_lshl_add_u64 v[216:217], s[24:25], 0, v[130:131]
	s_mov_b32 m0, s31
	s_nop 0
	global_load_lds_dwordx4 v[216:217], off
	s_add_u32 s18, s22, 0xb0000
	s_addc_u32 s19, s23, 0
	s_add_i32 s47, s39, s29
	v_lshl_add_u64 v[254:255], s[18:19], 0, v[128:129]
	s_mov_b32 m0, s47
	s_nop 0
	global_load_lds_dwordx4 v[254:255], off
	v_lshl_add_u64 v[254:255], s[18:19], 0, v[130:131]
	s_add_i32 m0, s47, 0x2000
	s_nop 0
	global_load_lds_dwordx4 v[254:255], off
	s_waitcnt vmcnt(6)
	s_waitcnt lgkmcnt(0)
	s_barrier
; #define PG8_STAGE(bufoff, gbase, voff) do { _Pragma("unroll") for (int _i = 0; _i < 2; ++_i) \
;         __builtin_amdgcn_global_load_lds((const unsigned*)((const char*)(gbase) + (voff)[_i]), (LAS unsigned*)(lds + (bufoff) + ldsw + _i * 8192), 16, 0, 0); } while (0)
; #define PG8_LDA(dst, b, h) do { _Pragma("unroll") for (int m = 0; m < 4; ++m) _Pragma("unroll") for (int k = 0; k < 2; ++k) dst[m][k] = *(const LAS bf16x8*)(lds + PG8_SA(b, h) + aoff + m * 2048 + k * 1024); } while (0)
; #define PG8_LDB(dst, b, h) do { _Pragma("unroll") for (int n = 0; n < 2; ++n) _Pragma("unroll") for (int k = 0; k < 2; ++k) dst[n][k] = *(const LAS bf16x8*)(lds + PG8_SB(b, h) + boff + n * 2048 + k * 1024); } while (0)
; #define PG8_MMA(ai, bj, At, Bt) do { __builtin_amdgcn_s_setprio(1); _Pragma("unroll") for (int m = 0; m < 4; ++m) _Pragma("unroll") for (int n = 0; n < 2; ++n) _Pragma("unroll") for (int k = 0; k < 2; ++k) \
;         acc[ai][bj][m][n] = __builtin_amdgcn_mfma_f32_16x16x32_bf16(Bt[n][k], At[m][k], acc[ai][bj][m][n], 0, 0, 0); __builtin_amdgcn_s_setprio(0); } while (0)
; #define PG8_WAIT_V(n) asm volatile("s_waitcnt vmcnt(" #n ")" ::: "memory")
; #define PG8_WAIT_L(n) asm volatile("s_waitcnt lgkmcnt(" #n ")" ::: "memory")
; #define PG8_BAR __builtin_amdgcn_s_barrier()
; #define PG8_SCHED __builtin_amdgcn_sched_barrier(0)
; template <class Epi>
; __device__ __forceinline__ void gemm_phase(LAS unsigned char* lds, const Gemm g, const StaticOrder& S, const Epi& E) {
;     ...
;             PG8_BAR; PG8_WAIT_L(0); PG8_MMA(1, 0, At, B0); PG8_BAR; PG8_SCHED;
;             PG8_STAGE(PG8_SB(0, 1), b2 + hstepB, voffB);
;             PG8_WAIT_V(6); PG8_BAR; PG8_MMA(1, 1, At, B1); PG8_BAR;
;             PG8_LDB(B0, 1, 0); PG8_SCHED; PG8_LDA(At, 1, 0); PG8_STAGE(PG8_SA(0, 1), a2 + hstepA, voffA);
;             PG8_WAIT_L(8); PG8_BAR; PG8_WAIT_L(0); PG8_MMA(0, 0, At, B0); PG8_BAR; PG8_SCHED;
;             PG8_LDB(B1, 1, 1); PG8_STAGE(PG8_SB(1, 0), b3, voffB);
;             PG8_BAR; PG8_WAIT_L(0); PG8_MMA(0, 1, At, B1); PG8_BAR;
	s_setprio 1
	v_mfma_f32_16x16x32_bf16 v[60:63], v[140:143], v[164:167], 0
	v_mfma_f32_16x16x32_bf16 v[56:59], v[156:159], v[164:167], 0
	v_mfma_f32_16x16x32_bf16 v[48:51], v[140:143], v[172:175], 0
	v_mfma_f32_16x16x32_bf16 v[40:43], v[156:159], v[172:175], 0
	v_mfma_f32_16x16x32_bf16 v[28:31], v[140:143], v[180:183], 0
	v_mfma_f32_16x16x32_bf16 v[24:27], v[156:159], v[180:183], 0
	v_mfma_f32_16x16x32_bf16 v[16:19], v[140:143], v[188:191], 0
	v_mfma_f32_16x16x32_bf16 v[8:11], v[156:159], v[188:191], 0
	v_mfma_f32_16x16x32_bf16 v[60:63], v[152:155], v[168:171], v[60:63]
	v_mfma_f32_16x16x32_bf16 v[56:59], v[160:163], v[168:171], v[56:59]
	v_mfma_f32_16x16x32_bf16 v[48:51], v[152:155], v[176:179], v[48:51]
	v_mfma_f32_16x16x32_bf16 v[40:43], v[160:163], v[176:179], v[40:43]
	v_mfma_f32_16x16x32_bf16 v[28:31], v[152:155], v[184:187], v[28:31]
	v_mfma_f32_16x16x32_bf16 v[24:27], v[160:163], v[184:187], v[24:27]
	v_mfma_f32_16x16x32_bf16 v[16:19], v[152:155], v[192:195], v[16:19]
	v_mfma_f32_16x16x32_bf16 v[8:11], v[160:163], v[192:195], v[8:11]
	v_mfma_f32_16x16x32_bf16 v[52:55], v[196:199], v[164:167], 0
	v_mfma_f32_16x16x32_bf16 v[44:47], v[204:207], v[164:167], 0
	v_mfma_f32_16x16x32_bf16 v[36:39], v[196:199], v[172:175], 0
	v_mfma_f32_16x16x32_bf16 v[32:35], v[204:207], v[172:175], 0
	v_mfma_f32_16x16x32_bf16 v[20:23], v[196:199], v[180:183], 0
	v_mfma_f32_16x16x32_bf16 v[12:15], v[204:207], v[180:183], 0
	v_mfma_f32_16x16x32_bf16 v[4:7], v[196:199], v[188:191], 0
	v_mfma_f32_16x16x32_bf16 v[0:3], v[204:207], v[188:191], 0
	v_mfma_f32_16x16x32_bf16 v[52:55], v[200:203], v[168:171], v[52:55]
	v_mfma_f32_16x16x32_bf16 v[44:47], v[208:211], v[168:171], v[44:47]
	v_mfma_f32_16x16x32_bf16 v[36:39], v[200:203], v[176:179], v[36:39]
	v_mfma_f32_16x16x32_bf16 v[32:35], v[208:211], v[176:179], v[32:35]
	v_mfma_f32_16x16x32_bf16 v[20:23], v[200:203], v[184:187], v[20:23]
	v_mfma_f32_16x16x32_bf16 v[12:15], v[208:211], v[184:187], v[12:15]
	v_mfma_f32_16x16x32_bf16 v[4:7], v[200:203], v[192:195], v[4:7]
	v_mfma_f32_16x16x32_bf16 v[0:3], v[208:211], v[192:195], v[0:3]
	s_setprio 0
	s_add_i32 s47, 0, 0x18000
	v_add_u32_e32 v160, s47, v147
	s_barrier
	ds_read_b128 v[140:143], v160
	ds_read_b128 v[152:155], v160 offset:1024
	ds_read_b128 v[156:159], v160 offset:2048
	ds_read_b128 v[160:163], v160 offset:3072
	s_add_u32 s18, s24, 0xb0000
	s_addc_u32 s19, s25, 0
	s_mov_b32 m0, s33
	v_lshl_add_u64 v[196:197], s[18:19], 0, v[128:129]
	ds_read_b128 v[164:167], v150 offset:32768
	ds_read_b128 v[168:171], v150 offset:33792
	ds_read_b128 v[172:175], v150 offset:34816
	ds_read_b128 v[176:179], v150 offset:35840
	ds_read_b128 v[180:183], v150 offset:36864
	ds_read_b128 v[184:187], v150 offset:37888
	ds_read_b128 v[188:191], v150 offset:38912
	ds_read_b128 v[192:195], v150 offset:39936
	global_load_lds_dwordx4 v[196:197], off
	v_lshl_add_u64 v[196:197], s[18:19], 0, v[130:131]
	s_mov_b32 m0, s34
	s_nop 0
	global_load_lds_dwordx4 v[196:197], off
	s_add_i32 s24, 0, 0x1c000
	v_add_u32_e32 v208, s24, v147
	ds_read_b128 v[196:199], v208
	ds_read_b128 v[200:203], v208 offset:1024
	ds_read_b128 v[204:207], v208 offset:2048
	ds_read_b128 v[208:211], v208 offset:3072
	s_waitcnt lgkmcnt(0)
	s_barrier
	s_setprio 1
	v_mfma_f32_16x16x32_bf16 v[124:127], v[140:143], v[164:167], v[124:127]
	v_mfma_f32_16x16x32_bf16 v[120:123], v[156:159], v[164:167], v[120:123]
	v_mfma_f32_16x16x32_bf16 v[112:115], v[140:143], v[172:175], v[112:115]
	v_mfma_f32_16x16x32_bf16 v[104:107], v[156:159], v[172:175], v[104:107]
	v_mfma_f32_16x16x32_bf16 v[92:95], v[140:143], v[180:183], v[92:95]
	v_mfma_f32_16x16x32_bf16 v[88:91], v[156:159], v[180:183], v[88:91]
	v_mfma_f32_16x16x32_bf16 v[80:83], v[140:143], v[188:191], v[80:83]
	v_mfma_f32_16x16x32_bf16 v[72:75], v[156:159], v[188:191], v[72:75]
	v_mfma_f32_16x16x32_bf16 v[124:127], v[152:155], v[168:171], v[124:127]
	v_mfma_f32_16x16x32_bf16 v[120:123], v[160:163], v[168:171], v[120:123]
	v_mfma_f32_16x16x32_bf16 v[112:115], v[152:155], v[176:179], v[112:115]
	v_mfma_f32_16x16x32_bf16 v[104:107], v[160:163], v[176:179], v[104:107]
	v_mfma_f32_16x16x32_bf16 v[92:95], v[152:155], v[184:187], v[92:95]
	v_mfma_f32_16x16x32_bf16 v[88:91], v[160:163], v[184:187], v[88:91]
	v_mfma_f32_16x16x32_bf16 v[80:83], v[152:155], v[192:195], v[80:83]
	v_mfma_f32_16x16x32_bf16 v[72:75], v[160:163], v[192:195], v[72:75]
	v_mfma_f32_16x16x32_bf16 v[116:119], v[196:199], v[164:167], v[116:119]
	v_mfma_f32_16x16x32_bf16 v[108:111], v[204:207], v[164:167], v[108:111]
	v_mfma_f32_16x16x32_bf16 v[100:103], v[196:199], v[172:175], v[100:103]
	v_mfma_f32_16x16x32_bf16 v[96:99], v[204:207], v[172:175], v[96:99]
	v_mfma_f32_16x16x32_bf16 v[84:87], v[196:199], v[180:183], v[84:87]
	v_mfma_f32_16x16x32_bf16 v[76:79], v[204:207], v[180:183], v[76:79]
	v_mfma_f32_16x16x32_bf16 v[68:71], v[196:199], v[188:191], v[68:71]
	v_mfma_f32_16x16x32_bf16 v[64:67], v[204:207], v[188:191], v[64:67]
	v_mfma_f32_16x16x32_bf16 v[116:119], v[200:203], v[168:171], v[116:119]
	v_mfma_f32_16x16x32_bf16 v[108:111], v[208:211], v[168:171], v[108:111]
	v_mfma_f32_16x16x32_bf16 v[100:103], v[200:203], v[176:179], v[100:103]
	v_mfma_f32_16x16x32_bf16 v[96:99], v[208:211], v[176:179], v[96:99]
	v_mfma_f32_16x16x32_bf16 v[84:87], v[200:203], v[184:187], v[84:87]
	v_mfma_f32_16x16x32_bf16 v[76:79], v[208:211], v[184:187], v[76:79]
	v_mfma_f32_16x16x32_bf16 v[68:71], v[200:203], v[192:195], v[68:71]
	v_mfma_f32_16x16x32_bf16 v[64:67], v[208:211], v[192:195], v[64:67]
	s_setprio 0
	s_barrier
; #define PG8_STAGE(bufoff, gbase, voff) do { _Pragma("unroll") for (int _i = 0; _i < 2; ++_i) \
;         __builtin_amdgcn_global_load_lds((const unsigned*)((const char*)(gbase) + (voff)[_i]), (LAS unsigned*)(lds + (bufoff) + ldsw + _i * 8192), 16, 0, 0); } while (0)
; #define PG8_LDA(dst, b, h) do { _Pragma("unroll") for (int m = 0; m < 4; ++m) _Pragma("unroll") for (int k = 0; k < 2; ++k) dst[m][k] = *(const LAS bf16x8*)(lds + PG8_SA(b, h) + aoff + m * 2048 + k * 1024); } while (0)
; #define PG8_MMA(ai, bj, At, Bt) do { __builtin_amdgcn_s_setprio(1); _Pragma("unroll") for (int m = 0; m < 4; ++m) _Pragma("unroll") for (int n = 0; n < 2; ++n) _Pragma("unroll") for (int k = 0; k < 2; ++k) \
;         acc[ai][bj][m][n] = __builtin_amdgcn_mfma_f32_16x16x32_bf16(Bt[n][k], At[m][k], acc[ai][bj][m][n], 0, 0, 0); __builtin_amdgcn_s_setprio(0); } while (0)
; #define PG8_WAIT_V(n) asm volatile("s_waitcnt vmcnt(" #n ")" ::: "memory")
; #define PG8_WAIT_L(n) asm volatile("s_waitcnt lgkmcnt(" #n ")" ::: "memory")
; #define PG8_BAR __builtin_amdgcn_s_barrier()
; #define PG8_SCHED __builtin_amdgcn_sched_barrier(0)
; template <class Epi>
; __device__ __forceinline__ void gemm_phase(LAS unsigned char* lds, const Gemm g, const StaticOrder& S, const Epi& E) {
;     ...
;             PG8_LDA(At, 1, 1); PG8_STAGE(PG8_SA(1, 0), a3, voffA);
;             PG8_BAR; PG8_WAIT_L(0); PG8_MMA(1, 0, At, B0); PG8_BAR; PG8_SCHED;
;             PG8_STAGE(PG8_SB(1, 1), b3 + hstepB, voffB);
;             PG8_WAIT_V(6); PG8_BAR; PG8_MMA(1, 1, At, B1); PG8_BAR;
	s_nop 1
	ds_read_b128 v[164:167], v150 offset:49152
	ds_read_b128 v[168:171], v150 offset:50176
	ds_read_b128 v[172:175], v150 offset:51200
	ds_read_b128 v[176:179], v150 offset:52224
	ds_read_b128 v[180:183], v150 offset:53248
	ds_read_b128 v[184:187], v150 offset:54272
	ds_read_b128 v[188:191], v150 offset:55296
	ds_read_b128 v[192:195], v150 offset:56320
	s_add_i32 s18, s47, s29
	v_lshl_add_u64 v[254:255], v[144:145], 0, s[10:11]
	s_mov_b32 m0, s18
	s_nop 0
	global_load_lds_dwordx4 v[254:255], off
	v_lshl_add_u64 v[254:255], v[212:213], 0, s[10:11]
	s_add_i32 m0, s18, 0x2000
	s_nop 0
	global_load_lds_dwordx4 v[254:255], off
	s_mov_b32 m0, s36
	v_lshl_add_u64 v[254:255], v[214:215], 0, s[10:11]
	global_load_lds_dwordx4 v[254:255], off
	v_lshl_add_u64 v[144:145], v[216:217], 0, s[10:11]
	s_mov_b32 m0, s37
	s_nop 0
	global_load_lds_dwordx4 v[144:145], off
	s_add_u32 s18, s22, 0xb0080
	s_addc_u32 s19, s23, 0
	s_add_i32 s22, s24, s29
	v_lshl_add_u64 v[254:255], s[18:19], 0, v[128:129]
	s_mov_b32 m0, s22
	s_nop 0
	global_load_lds_dwordx4 v[254:255], off
	v_lshl_add_u64 v[254:255], s[18:19], 0, v[130:131]
	s_add_i32 m0, s22, 0x2000
	s_nop 0
	global_load_lds_dwordx4 v[254:255], off
	s_waitcnt vmcnt(6)
	s_waitcnt lgkmcnt(0)
	s_barrier
	s_setprio 1
	v_mfma_f32_16x16x32_bf16 v[60:63], v[140:143], v[164:167], v[60:63]
	v_mfma_f32_16x16x32_bf16 v[56:59], v[156:159], v[164:167], v[56:59]
	v_mfma_f32_16x16x32_bf16 v[48:51], v[140:143], v[172:175], v[48:51]
	v_mfma_f32_16x16x32_bf16 v[40:43], v[156:159], v[172:175], v[40:43]
	v_mfma_f32_16x16x32_bf16 v[28:31], v[140:143], v[180:183], v[28:31]
	v_mfma_f32_16x16x32_bf16 v[24:27], v[156:159], v[180:183], v[24:27]
	v_mfma_f32_16x16x32_bf16 v[16:19], v[140:143], v[188:191], v[16:19]
	v_mfma_f32_16x16x32_bf16 v[8:11], v[156:159], v[188:191], v[8:11]
	v_mfma_f32_16x16x32_bf16 v[60:63], v[152:155], v[168:171], v[60:63]
	v_mfma_f32_16x16x32_bf16 v[56:59], v[160:163], v[168:171], v[56:59]
	v_mfma_f32_16x16x32_bf16 v[48:51], v[152:155], v[176:179], v[48:51]
	v_mfma_f32_16x16x32_bf16 v[40:43], v[160:163], v[176:179], v[40:43]
	v_mfma_f32_16x16x32_bf16 v[28:31], v[152:155], v[184:187], v[28:31]
	v_mfma_f32_16x16x32_bf16 v[24:27], v[160:163], v[184:187], v[24:27]
	v_mfma_f32_16x16x32_bf16 v[16:19], v[152:155], v[192:195], v[16:19]
	v_mfma_f32_16x16x32_bf16 v[8:11], v[160:163], v[192:195], v[8:11]
	v_mfma_f32_16x16x32_bf16 v[52:55], v[196:199], v[164:167], v[52:55]
	v_mfma_f32_16x16x32_bf16 v[44:47], v[204:207], v[164:167], v[44:47]
	v_mfma_f32_16x16x32_bf16 v[36:39], v[196:199], v[172:175], v[36:39]
	v_mfma_f32_16x16x32_bf16 v[32:35], v[204:207], v[172:175], v[32:35]
	v_mfma_f32_16x16x32_bf16 v[20:23], v[196:199], v[180:183], v[20:23]
	v_mfma_f32_16x16x32_bf16 v[12:15], v[204:207], v[180:183], v[12:15]
	v_mfma_f32_16x16x32_bf16 v[4:7], v[196:199], v[188:191], v[4:7]
	v_mfma_f32_16x16x32_bf16 v[0:3], v[204:207], v[188:191], v[0:3]
	v_mfma_f32_16x16x32_bf16 v[52:55], v[200:203], v[168:171], v[52:55]
	v_mfma_f32_16x16x32_bf16 v[44:47], v[208:211], v[168:171], v[44:47]
	v_mfma_f32_16x16x32_bf16 v[36:39], v[200:203], v[176:179], v[36:39]
	v_mfma_f32_16x16x32_bf16 v[32:35], v[208:211], v[176:179], v[32:35]
	v_mfma_f32_16x16x32_bf16 v[20:23], v[200:203], v[184:187], v[20:23]
	v_mfma_f32_16x16x32_bf16 v[12:15], v[208:211], v[184:187], v[12:15]
	v_mfma_f32_16x16x32_bf16 v[4:7], v[200:203], v[192:195], v[4:7]
	v_mfma_f32_16x16x32_bf16 v[0:3], v[208:211], v[192:195], v[0:3]
	s_setprio 0
	s_add_i32 s46, s46, 2
	s_add_u32 s44, s44, 0x100
	s_addc_u32 s45, s45, 0
	s_cmp_gt_u32 s46, 41
	s_mov_b64 s[18:19], s[20:21]
	s_barrier
	.p2alignl 6, 3212836864
